# epilogue vmcnt(0) waits that only needed older loads relaxed to leave the trailing stores in flight
# speedup vs baseline: 1.0049x; 1.0049x over previous
.LBB0_110:
	s_add_u32 s8, s60, 0xfff00080
	s_addc_u32 s9, s61, -1
	s_add_i32 s16, 0, 0x10000
	v_add_u32_e32 v140, s16, v169
	ds_read_b128 v[128:131], v140
	ds_read_b128 v[132:135], v140 offset:1024
	ds_read_b128 v[136:139], v140 offset:2048
	ds_read_b128 v[140:143], v140 offset:3072
	s_cmp_eq_u32 s15, 60
	s_cselect_b32 s9, s5, s9
	s_cselect_b32 s8, s50, s8
	s_cselect_b32 s63, s1, s14
	s_cselect_b32 s62, s12, s13
	v_lshl_add_u64 v[164:165], s[60:61], 0, v[178:179]
	s_add_i32 m0, s38, 0xc000
	ds_read_b128 v[144:147], v171
	ds_read_b128 v[148:151], v171 offset:1024
	ds_read_b128 v[152:155], v171 offset:2048
	ds_read_b128 v[156:159], v171 offset:3072
	ds_read_b128 v[182:185], v171 offset:4096
	ds_read_b128 v[186:189], v171 offset:5120
	ds_read_b128 v[190:193], v171 offset:6144
	ds_read_b128 v[194:197], v171 offset:7168
	global_load_lds_dwordx4 v[164:165], off
	v_lshl_add_u64 v[164:165], s[60:61], 0, v[180:181]
	s_add_i32 m0, s38, 0xe000
	s_nop 0
	global_load_lds_dwordx4 v[164:165], off
	s_waitcnt lgkmcnt(8)
	s_barrier
	s_waitcnt lgkmcnt(0)
	s_setprio 1
	s_waitcnt lgkmcnt(0)
	v_mfma_f32_16x16x32_bf16 v[124:127], v[128:131], v[144:147], v[124:127]
	v_mfma_f32_16x16x32_bf16 v[120:123], v[136:139], v[144:147], v[120:123]
	v_mfma_f32_16x16x32_bf16 v[116:119], v[128:131], v[152:155], v[116:119]
	v_mfma_f32_16x16x32_bf16 v[112:115], v[136:139], v[152:155], v[112:115]
	v_mfma_f32_16x16x32_bf16 v[108:111], v[128:131], v[182:185], v[108:111]
	v_mfma_f32_16x16x32_bf16 v[104:107], v[136:139], v[182:185], v[104:107]
	v_mfma_f32_16x16x32_bf16 v[100:103], v[128:131], v[190:193], v[100:103]
	v_mfma_f32_16x16x32_bf16 v[96:99], v[136:139], v[190:193], v[96:99]
	v_mfma_f32_16x16x32_bf16 v[124:127], v[132:135], v[148:151], v[124:127]
	v_mfma_f32_16x16x32_bf16 v[120:123], v[140:143], v[148:151], v[120:123]
	v_mfma_f32_16x16x32_bf16 v[116:119], v[132:135], v[156:159], v[116:119]
	v_mfma_f32_16x16x32_bf16 v[112:115], v[140:143], v[156:159], v[112:115]
	v_mfma_f32_16x16x32_bf16 v[108:111], v[132:135], v[186:189], v[108:111]
	v_mfma_f32_16x16x32_bf16 v[104:107], v[140:143], v[186:189], v[104:107]
	v_mfma_f32_16x16x32_bf16 v[100:103], v[132:135], v[194:197], v[100:103]
	v_mfma_f32_16x16x32_bf16 v[96:99], v[140:143], v[194:197], v[96:99]
	s_setprio 0
	s_barrier
	s_add_i32 s18, 0, 0x14000
	s_add_i32 s16, s16, s37
	v_add_u32_e32 v162, s18, v169
	v_lshl_add_u64 v[164:165], s[62:63], 0, v[160:161]
	s_mov_b32 m0, s16
	ds_read_b128 v[198:201], v162
	ds_read_b128 v[202:205], v162 offset:1024
	ds_read_b128 v[206:209], v162 offset:2048
	ds_read_b128 v[210:213], v162 offset:3072
	global_load_lds_dwordx4 v[164:165], off
	v_lshl_add_u64 v[166:167], s[62:63], 0, v[172:173]
	s_add_i32 m0, s16, 0x2000
	s_nop 0
	global_load_lds_dwordx4 v[166:167], off
	s_barrier
	s_waitcnt lgkmcnt(0)
	s_setprio 1
	s_waitcnt lgkmcnt(0)
	v_mfma_f32_16x16x32_bf16 v[60:63], v[198:201], v[144:147], v[60:63]
	v_mfma_f32_16x16x32_bf16 v[56:59], v[206:209], v[144:147], v[56:59]
	v_mfma_f32_16x16x32_bf16 v[52:55], v[198:201], v[152:155], v[52:55]
	v_mfma_f32_16x16x32_bf16 v[48:51], v[206:209], v[152:155], v[48:51]
	v_mfma_f32_16x16x32_bf16 v[44:47], v[198:201], v[182:185], v[44:47]
	v_mfma_f32_16x16x32_bf16 v[40:43], v[206:209], v[182:185], v[40:43]
	v_mfma_f32_16x16x32_bf16 v[36:39], v[198:201], v[190:193], v[36:39]
	v_mfma_f32_16x16x32_bf16 v[32:35], v[206:209], v[190:193], v[32:35]
	v_mfma_f32_16x16x32_bf16 v[60:63], v[202:205], v[148:151], v[60:63]
	v_mfma_f32_16x16x32_bf16 v[56:59], v[210:213], v[148:151], v[56:59]
	v_mfma_f32_16x16x32_bf16 v[52:55], v[202:205], v[156:159], v[52:55]
	v_mfma_f32_16x16x32_bf16 v[48:51], v[210:213], v[156:159], v[48:51]
	v_mfma_f32_16x16x32_bf16 v[44:47], v[202:205], v[186:189], v[44:47]
	v_mfma_f32_16x16x32_bf16 v[40:43], v[210:213], v[186:189], v[40:43]
	v_mfma_f32_16x16x32_bf16 v[36:39], v[202:205], v[194:197], v[36:39]
	v_mfma_f32_16x16x32_bf16 v[32:35], v[210:213], v[194:197], v[32:35]
	s_setprio 0
	s_mov_b32 m0, s38
	v_lshl_add_u64 v[214:215], s[8:9], 0, v[176:177]
	s_barrier
	ds_read_b128 v[144:147], v171 offset:16384
	ds_read_b128 v[148:151], v171 offset:17408
	ds_read_b128 v[152:155], v171 offset:18432
	ds_read_b128 v[156:159], v171 offset:19456
	ds_read_b128 v[182:185], v171 offset:20480
	ds_read_b128 v[186:189], v171 offset:21504
	ds_read_b128 v[190:193], v171 offset:22528
	ds_read_b128 v[194:197], v171 offset:23552
	global_load_lds_dwordx4 v[214:215], off
	v_lshl_add_u64 v[216:217], s[8:9], 0, v[174:175]
	s_mov_b32 m0, s39
	s_nop 0
	global_load_lds_dwordx4 v[216:217], off
	s_barrier
	s_waitcnt lgkmcnt(0)
	s_setprio 1
	s_waitcnt lgkmcnt(0)
	v_mfma_f32_16x16x32_bf16 v[92:95], v[128:131], v[144:147], v[92:95]
	v_mfma_f32_16x16x32_bf16 v[88:91], v[136:139], v[144:147], v[88:91]
	v_mfma_f32_16x16x32_bf16 v[84:87], v[128:131], v[152:155], v[84:87]
	v_mfma_f32_16x16x32_bf16 v[80:83], v[136:139], v[152:155], v[80:83]
	v_mfma_f32_16x16x32_bf16 v[76:79], v[128:131], v[182:185], v[76:79]
	v_mfma_f32_16x16x32_bf16 v[72:75], v[136:139], v[182:185], v[72:75]
	v_mfma_f32_16x16x32_bf16 v[68:71], v[128:131], v[190:193], v[68:71]
	v_mfma_f32_16x16x32_bf16 v[64:67], v[136:139], v[190:193], v[64:67]
	v_mfma_f32_16x16x32_bf16 v[92:95], v[132:135], v[148:151], v[92:95]
	v_mfma_f32_16x16x32_bf16 v[88:91], v[140:143], v[148:151], v[88:91]
	v_mfma_f32_16x16x32_bf16 v[84:87], v[132:135], v[156:159], v[84:87]
	v_mfma_f32_16x16x32_bf16 v[80:83], v[140:143], v[156:159], v[80:83]
	v_mfma_f32_16x16x32_bf16 v[76:79], v[132:135], v[186:189], v[76:79]
	v_mfma_f32_16x16x32_bf16 v[72:75], v[140:143], v[186:189], v[72:75]
	v_mfma_f32_16x16x32_bf16 v[68:71], v[132:135], v[194:197], v[68:71]
	v_mfma_f32_16x16x32_bf16 v[64:67], v[140:143], v[194:197], v[64:67]
	s_setprio 0
	s_barrier
	s_add_u32 s16, s62, 0x100000
	s_addc_u32 s17, s63, 0
	s_add_i32 s18, s18, s37
	v_lshl_add_u64 v[128:129], s[16:17], 0, v[160:161]
	s_mov_b32 m0, s18
	s_nop 0
	global_load_lds_dwordx4 v[128:129], off
	v_lshl_add_u64 v[128:129], s[16:17], 0, v[172:173]
	s_add_i32 m0, s18, 0x2000
	s_nop 0
	global_load_lds_dwordx4 v[128:129], off
	s_waitcnt vmcnt(6)
	s_barrier
	s_setprio 1
	v_mfma_f32_16x16x32_bf16 v[28:31], v[198:201], v[144:147], v[28:31]
	v_mfma_f32_16x16x32_bf16 v[24:27], v[206:209], v[144:147], v[24:27]
	v_mfma_f32_16x16x32_bf16 v[20:23], v[198:201], v[152:155], v[20:23]
	v_mfma_f32_16x16x32_bf16 v[16:19], v[206:209], v[152:155], v[16:19]
	v_mfma_f32_16x16x32_bf16 v[12:15], v[198:201], v[182:185], v[12:15]
	v_mfma_f32_16x16x32_bf16 v[8:11], v[206:209], v[182:185], v[8:11]
	v_mfma_f32_16x16x32_bf16 v[4:7], v[198:201], v[190:193], v[4:7]
	v_mfma_f32_16x16x32_bf16 v[0:3], v[206:209], v[190:193], v[0:3]
	v_mfma_f32_16x16x32_bf16 v[28:31], v[202:205], v[148:151], v[28:31]
	v_mfma_f32_16x16x32_bf16 v[24:27], v[210:213], v[148:151], v[24:27]
	v_mfma_f32_16x16x32_bf16 v[20:23], v[202:205], v[156:159], v[20:23]
	v_mfma_f32_16x16x32_bf16 v[16:19], v[210:213], v[156:159], v[16:19]
	v_mfma_f32_16x16x32_bf16 v[12:15], v[202:205], v[186:189], v[12:15]
	v_mfma_f32_16x16x32_bf16 v[8:11], v[210:213], v[186:189], v[8:11]
	v_mfma_f32_16x16x32_bf16 v[4:7], v[202:205], v[194:197], v[4:7]
	v_mfma_f32_16x16x32_bf16 v[0:3], v[210:213], v[194:197], v[0:3]
	s_setprio 0
	s_add_i32 s16, 0, 0x18000
	v_add_u32_e32 v140, s16, v169
	s_barrier
	ds_read_b128 v[128:131], v140
	ds_read_b128 v[132:135], v140 offset:1024
	ds_read_b128 v[136:139], v140 offset:2048
	ds_read_b128 v[140:143], v140 offset:3072
	s_add_u32 s8, s8, 0x100000
	s_addc_u32 s9, s9, 0
	s_mov_b32 m0, s40
	v_lshl_add_u64 v[198:199], s[8:9], 0, v[176:177]
	ds_read_b128 v[144:147], v171 offset:32768
	ds_read_b128 v[148:151], v171 offset:33792
	ds_read_b128 v[152:155], v171 offset:34816
	ds_read_b128 v[156:159], v171 offset:35840
	ds_read_b128 v[182:185], v171 offset:36864
	ds_read_b128 v[186:189], v171 offset:37888
	ds_read_b128 v[190:193], v171 offset:38912
	ds_read_b128 v[194:197], v171 offset:39936
	global_load_lds_dwordx4 v[198:199], off
	v_lshl_add_u64 v[198:199], s[8:9], 0, v[174:175]
	s_mov_b32 m0, s41
	s_nop 0
	global_load_lds_dwordx4 v[198:199], off
	s_waitcnt lgkmcnt(8)
	s_barrier
	s_waitcnt lgkmcnt(0)
	s_setprio 1
	s_waitcnt lgkmcnt(0)
	v_mfma_f32_16x16x32_bf16 v[124:127], v[128:131], v[144:147], v[124:127]
	v_mfma_f32_16x16x32_bf16 v[120:123], v[136:139], v[144:147], v[120:123]
	v_mfma_f32_16x16x32_bf16 v[116:119], v[128:131], v[152:155], v[116:119]
	v_mfma_f32_16x16x32_bf16 v[112:115], v[136:139], v[152:155], v[112:115]
	v_mfma_f32_16x16x32_bf16 v[108:111], v[128:131], v[182:185], v[108:111]
	v_mfma_f32_16x16x32_bf16 v[104:107], v[136:139], v[182:185], v[104:107]
	v_mfma_f32_16x16x32_bf16 v[100:103], v[128:131], v[190:193], v[100:103]
	v_mfma_f32_16x16x32_bf16 v[96:99], v[136:139], v[190:193], v[96:99]
	v_mfma_f32_16x16x32_bf16 v[124:127], v[132:135], v[148:151], v[124:127]
	v_mfma_f32_16x16x32_bf16 v[120:123], v[140:143], v[148:151], v[120:123]
	v_mfma_f32_16x16x32_bf16 v[116:119], v[132:135], v[156:159], v[116:119]
	v_mfma_f32_16x16x32_bf16 v[112:115], v[140:143], v[156:159], v[112:115]
	v_mfma_f32_16x16x32_bf16 v[108:111], v[132:135], v[186:189], v[108:111]
	v_mfma_f32_16x16x32_bf16 v[104:107], v[140:143], v[186:189], v[104:107]
	v_mfma_f32_16x16x32_bf16 v[100:103], v[132:135], v[194:197], v[100:103]
	v_mfma_f32_16x16x32_bf16 v[96:99], v[140:143], v[194:197], v[96:99]
	s_setprio 0
	s_barrier
	s_add_i32 s17, 0, 0x1c000
	s_add_i32 s8, s16, s37
	v_add_u32_e32 v162, s17, v169
	v_lshl_add_u64 v[164:165], v[164:165], 0, s[74:75]
	s_mov_b32 m0, s8
	ds_read_b128 v[198:201], v162
	ds_read_b128 v[202:205], v162 offset:1024
	ds_read_b128 v[206:209], v162 offset:2048
	ds_read_b128 v[210:213], v162 offset:3072
	global_load_lds_dwordx4 v[164:165], off
	v_lshl_add_u64 v[164:165], v[166:167], 0, s[74:75]
	s_add_i32 m0, s8, 0x2000
	s_nop 0
	global_load_lds_dwordx4 v[164:165], off
	s_barrier
	s_waitcnt lgkmcnt(0)
	s_setprio 1
	s_waitcnt lgkmcnt(0)
	v_mfma_f32_16x16x32_bf16 v[60:63], v[198:201], v[144:147], v[60:63]
	v_mfma_f32_16x16x32_bf16 v[56:59], v[206:209], v[144:147], v[56:59]
	v_mfma_f32_16x16x32_bf16 v[52:55], v[198:201], v[152:155], v[52:55]
	v_mfma_f32_16x16x32_bf16 v[48:51], v[206:209], v[152:155], v[48:51]
	v_mfma_f32_16x16x32_bf16 v[44:47], v[198:201], v[182:185], v[44:47]
	v_mfma_f32_16x16x32_bf16 v[40:43], v[206:209], v[182:185], v[40:43]
	v_mfma_f32_16x16x32_bf16 v[36:39], v[198:201], v[190:193], v[36:39]
	v_mfma_f32_16x16x32_bf16 v[32:35], v[206:209], v[190:193], v[32:35]
	v_mfma_f32_16x16x32_bf16 v[60:63], v[202:205], v[148:151], v[60:63]
	v_mfma_f32_16x16x32_bf16 v[56:59], v[210:213], v[148:151], v[56:59]
	v_mfma_f32_16x16x32_bf16 v[52:55], v[202:205], v[156:159], v[52:55]
	v_mfma_f32_16x16x32_bf16 v[48:51], v[210:213], v[156:159], v[48:51]
	v_mfma_f32_16x16x32_bf16 v[44:47], v[202:205], v[186:189], v[44:47]
	v_mfma_f32_16x16x32_bf16 v[40:43], v[210:213], v[186:189], v[40:43]
	v_mfma_f32_16x16x32_bf16 v[36:39], v[202:205], v[194:197], v[36:39]
	v_mfma_f32_16x16x32_bf16 v[32:35], v[210:213], v[194:197], v[32:35]
	s_setprio 0
	s_mov_b32 m0, s42
	v_lshl_add_u64 v[164:165], v[214:215], 0, s[74:75]
	s_barrier
	ds_read_b128 v[144:147], v171 offset:49152
	ds_read_b128 v[148:151], v171 offset:50176
	ds_read_b128 v[152:155], v171 offset:51200
	ds_read_b128 v[156:159], v171 offset:52224
	ds_read_b128 v[182:185], v171 offset:53248
	ds_read_b128 v[186:189], v171 offset:54272
	ds_read_b128 v[190:193], v171 offset:55296
	ds_read_b128 v[194:197], v171 offset:56320
	global_load_lds_dwordx4 v[164:165], off
	v_lshl_add_u64 v[164:165], v[216:217], 0, s[74:75]
	s_mov_b32 m0, s43
	s_nop 0
	global_load_lds_dwordx4 v[164:165], off
	s_barrier
	s_waitcnt lgkmcnt(0)
	s_setprio 1
	s_waitcnt lgkmcnt(0)
	v_mfma_f32_16x16x32_bf16 v[92:95], v[128:131], v[144:147], v[92:95]
	v_mfma_f32_16x16x32_bf16 v[88:91], v[136:139], v[144:147], v[88:91]
	v_mfma_f32_16x16x32_bf16 v[84:87], v[128:131], v[152:155], v[84:87]
	v_mfma_f32_16x16x32_bf16 v[80:83], v[136:139], v[152:155], v[80:83]
	v_mfma_f32_16x16x32_bf16 v[76:79], v[128:131], v[182:185], v[76:79]
	v_mfma_f32_16x16x32_bf16 v[72:75], v[136:139], v[182:185], v[72:75]
	v_mfma_f32_16x16x32_bf16 v[68:71], v[128:131], v[190:193], v[68:71]
	v_mfma_f32_16x16x32_bf16 v[64:67], v[136:139], v[190:193], v[64:67]
	v_mfma_f32_16x16x32_bf16 v[92:95], v[132:135], v[148:151], v[92:95]
	v_mfma_f32_16x16x32_bf16 v[88:91], v[140:143], v[148:151], v[88:91]
	v_mfma_f32_16x16x32_bf16 v[84:87], v[132:135], v[156:159], v[84:87]
	v_mfma_f32_16x16x32_bf16 v[80:83], v[140:143], v[156:159], v[80:83]
	v_mfma_f32_16x16x32_bf16 v[76:79], v[132:135], v[186:189], v[76:79]
	v_mfma_f32_16x16x32_bf16 v[72:75], v[140:143], v[186:189], v[72:75]
	v_mfma_f32_16x16x32_bf16 v[68:71], v[132:135], v[194:197], v[68:71]
	v_mfma_f32_16x16x32_bf16 v[64:67], v[140:143], v[194:197], v[64:67]
	s_setprio 0
	s_barrier
	s_add_u32 s8, s62, 0x100080
	s_addc_u32 s9, s63, 0
	s_add_i32 s16, s17, s37
	v_lshl_add_u64 v[128:129], s[8:9], 0, v[160:161]
	s_mov_b32 m0, s16
	s_nop 0
	global_load_lds_dwordx4 v[128:129], off
	v_lshl_add_u64 v[128:129], s[8:9], 0, v[172:173]
	s_add_i32 m0, s16, 0x2000
	s_nop 0
	global_load_lds_dwordx4 v[128:129], off
	s_waitcnt vmcnt(6)
	s_barrier
	s_setprio 1
	v_mfma_f32_16x16x32_bf16 v[28:31], v[198:201], v[144:147], v[28:31]
	v_mfma_f32_16x16x32_bf16 v[24:27], v[206:209], v[144:147], v[24:27]
	v_mfma_f32_16x16x32_bf16 v[20:23], v[198:201], v[152:155], v[20:23]
	v_mfma_f32_16x16x32_bf16 v[16:19], v[206:209], v[152:155], v[16:19]
	v_mfma_f32_16x16x32_bf16 v[12:15], v[198:201], v[182:185], v[12:15]
	v_mfma_f32_16x16x32_bf16 v[8:11], v[206:209], v[182:185], v[8:11]
	v_mfma_f32_16x16x32_bf16 v[4:7], v[198:201], v[190:193], v[4:7]
	v_mfma_f32_16x16x32_bf16 v[0:3], v[206:209], v[190:193], v[0:3]
	v_mfma_f32_16x16x32_bf16 v[28:31], v[202:205], v[148:151], v[28:31]
	v_mfma_f32_16x16x32_bf16 v[24:27], v[210:213], v[148:151], v[24:27]
	v_mfma_f32_16x16x32_bf16 v[20:23], v[202:205], v[156:159], v[20:23]
	v_mfma_f32_16x16x32_bf16 v[16:19], v[210:213], v[156:159], v[16:19]
	v_mfma_f32_16x16x32_bf16 v[12:15], v[202:205], v[186:189], v[12:15]
	v_mfma_f32_16x16x32_bf16 v[8:11], v[210:213], v[186:189], v[8:11]
	v_mfma_f32_16x16x32_bf16 v[4:7], v[202:205], v[194:197], v[4:7]
	v_mfma_f32_16x16x32_bf16 v[0:3], v[210:213], v[194:197], v[0:3]
	s_setprio 0
	s_add_i32 s15, s15, 2
	s_add_u32 s60, s60, 0x100
	s_addc_u32 s61, s61, 0
	s_add_u32 s13, s13, 0x100
	s_addc_u32 s14, s14, 0
	s_cmp_gt_u32 s15, 61
	s_barrier
	s_cbranch_scc0 .LBB0_110
	v_lshl_add_u32 v210, s65, 8, v168
	v_or_b32_e32 v132, 16, v210
	v_ashrrev_i32_e32 v133, 31, v132
	v_lshlrev_b64 v[212:213], 11, v[132:133]
	v_or_b32_e32 v132, 32, v210
	s_lshr_b32 s1, s65, 5
	v_ashrrev_i32_e32 v133, 31, v132
	v_lshl_or_b32 v128, s10, 8, v170
	s_mul_i32 s8, s1, 0x1800
	v_lshlrev_b64 v[208:209], 11, v[132:133]
	v_or_b32_e32 v132, 48, v210
	s_ashr_i32 s9, s8, 31
	v_ashrrev_i32_e32 v129, 31, v128
	v_readlane_b32 s12, v249, 12
	v_ashrrev_i32_e32 v133, 31, v132
	v_lshlrev_b64 v[182:183], 1, v[128:129]
	v_readlane_b32 s13, v249, 13
	v_readlane_b32 s14, v249, 14
	v_readlane_b32 s15, v249, 15
	v_ashrrev_i32_e32 v211, 31, v210
	v_lshlrev_b64 v[206:207], 11, v[132:133]
	v_add_u32_e32 v132, 0x90, v210
	s_lshl_b64 s[8:9], s[8:9], 2
	v_readlane_b32 s1, v250, 8
	v_lshl_add_u64 v[130:131], s[12:13], 0, v[182:183]
	v_lshlrev_b64 v[164:165], 11, v[210:211]
	s_mov_b64 s[14:15], 0x40000
	v_ashrrev_i32_e32 v133, 31, v132
	s_add_u32 s8, s1, s8
	v_readlane_b32 s1, v250, 9
	v_lshl_add_u64 v[184:185], v[130:131], 0, v[164:165]
	v_lshl_add_u64 v[204:205], v[164:165], 0, s[14:15]
	v_lshlrev_b64 v[200:201], 11, v[132:133]
	s_addc_u32 s9, s1, s9
	global_load_dwordx4 v[214:217], v[184:185], off
	v_lshl_add_u64 v[186:187], v[130:131], 0, v[212:213]
	v_lshl_add_u64 v[188:189], v[130:131], 0, v[208:209]
	v_lshl_add_u64 v[190:191], v[130:131], 0, v[206:207]
	v_lshl_add_u64 v[192:193], v[130:131], 0, v[204:205]
	v_lshl_add_u64 v[194:195], v[130:131], 0, v[200:201]
	v_lshl_add_u64 v[198:199], v[128:129], 2, s[8:9]
	global_load_dwordx4 v[156:159], v[186:187], off
	global_load_dwordx4 v[152:155], v[188:189], off
	global_load_dwordx4 v[148:151], v[190:191], off
	global_load_dwordx4 v[144:147], v[192:193], off
	global_load_dwordx4 v[136:139], v[194:195], off
	global_load_dwordx4 v[128:131], v[198:199], off offset:16
	global_load_dwordx4 v[132:135], v[198:199], off
	v_add_u32_e32 v140, 0xa0, v210
	v_ashrrev_i32_e32 v141, 31, v140
	v_lshlrev_b64 v[202:203], 11, v[140:141]
	v_lshl_add_u64 v[140:141], s[12:13], 0, v[202:203]
	v_readlane_b32 s8, v250, 5
	v_lshl_add_u64 v[196:197], v[140:141], 0, v[182:183]
	v_readlane_b32 s9, v250, 6
	global_load_dwordx4 v[140:143], v[196:197], off
	v_readlane_b32 s18, v249, 18
	s_and_b64 vcc, exec, s[2:3]
	s_mov_b32 s10, s0
	s_mov_b32 s65, s4
	s_mov_b64 s[20:21], s[6:7]
	v_readlane_b32 s62, v255, 4
	v_readlane_b32 s16, v249, 16
	v_readlane_b32 s17, v249, 17
	v_readlane_b32 s19, v249, 19
	v_readlane_b32 s63, v255, 5
	s_waitcnt vmcnt(0)
	v_lshlrev_b32_e32 v166, 16, v214
	v_and_b32_e32 v167, 0xffff0000, v214
	v_lshlrev_b32_e32 v218, 16, v216
	v_and_b32_e32 v219, 0xffff0000, v216
	v_lshlrev_b32_e32 v216, 16, v217
	v_and_b32_e32 v217, 0xffff0000, v217
	v_lshlrev_b32_e32 v214, 16, v215
	v_and_b32_e32 v215, 0xffff0000, v215
	v_pk_fma_f32 v[124:125], v[124:125], v[132:133], v[166:167]
	v_pk_fma_f32 v[166:167], v[122:123], v[130:131], v[216:217]
	v_pk_fma_f32 v[122:123], v[120:121], v[128:129], v[218:219]
	v_cvt_pk_bf16_f32 v120, v124, v125
	v_lshl_add_u64 v[124:125], s[8:9], 0, v[164:165]
	v_lshl_add_u64 v[124:125], v[124:125], 0, v[182:183]
	v_pk_fma_f32 v[126:127], v[126:127], v[134:135], v[214:215]
	v_lshlrev_b32_e32 v164, 16, v156
	v_cvt_pk_bf16_f32 v121, v126, v127
	v_cvt_pk_bf16_f32 v122, v122, v123
	v_cvt_pk_bf16_f32 v123, v166, v167
	global_store_dwordx4 v[124:125], v[120:123], off
	v_and_b32_e32 v165, 0xffff0000, v156
	v_lshlrev_b32_e32 v166, 16, v158
	v_add_u32_e32 v120, 0xb0, v210
	v_ashrrev_i32_e32 v121, 31, v120
	v_lshlrev_b64 v[210:211], 11, v[120:121]
	v_lshl_add_u64 v[120:121], s[12:13], 0, v[210:211]
	v_lshl_add_u64 v[126:127], v[120:121], 0, v[182:183]
	global_load_dwordx4 v[120:123], v[126:127], off
	v_and_b32_e32 v167, 0xffff0000, v158
	v_lshlrev_b32_e32 v156, 16, v157
	v_and_b32_e32 v157, 0xffff0000, v157
	v_lshlrev_b32_e32 v158, 16, v159
	v_and_b32_e32 v159, 0xffff0000, v159
	v_pk_fma_f32 v[116:117], v[116:117], v[132:133], v[164:165]
	v_pk_fma_f32 v[112:113], v[112:113], v[128:129], v[166:167]
	v_pk_fma_f32 v[118:119], v[118:119], v[134:135], v[156:157]
	v_pk_fma_f32 v[156:157], v[114:115], v[130:131], v[158:159]
	v_cvt_pk_bf16_f32 v114, v116, v117
	v_cvt_pk_bf16_f32 v115, v118, v119
	v_cvt_pk_bf16_f32 v116, v112, v113
	v_lshl_add_u64 v[112:113], s[8:9], 0, v[212:213]
	v_lshl_add_u64 v[112:113], v[112:113], 0, v[182:183]
	v_cvt_pk_bf16_f32 v117, v156, v157
	global_store_dwordx4 v[112:113], v[114:117], off
	v_lshlrev_b32_e32 v118, 16, v154
	v_and_b32_e32 v119, 0xffff0000, v154
	v_lshlrev_b32_e32 v114, 16, v152
	v_and_b32_e32 v115, 0xffff0000, v152
	v_lshlrev_b32_e32 v116, 16, v153
	v_and_b32_e32 v117, 0xffff0000, v153
	v_lshlrev_b32_e32 v152, 16, v155
	v_and_b32_e32 v153, 0xffff0000, v155
	v_pk_fma_f32 v[108:109], v[108:109], v[132:133], v[114:115]
	v_pk_fma_f32 v[104:105], v[104:105], v[128:129], v[118:119]
	v_pk_fma_f32 v[110:111], v[110:111], v[134:135], v[116:117]
	v_pk_fma_f32 v[114:115], v[106:107], v[130:131], v[152:153]
	v_cvt_pk_bf16_f32 v106, v108, v109
	v_cvt_pk_bf16_f32 v107, v110, v111
	v_cvt_pk_bf16_f32 v108, v104, v105
	v_lshl_add_u64 v[104:105], s[8:9], 0, v[208:209]
	v_lshl_add_u64 v[104:105], v[104:105], 0, v[182:183]
	v_cvt_pk_bf16_f32 v109, v114, v115
	global_store_dwordx4 v[104:105], v[106:109], off
	v_lshlrev_b32_e32 v110, 16, v150
	v_and_b32_e32 v111, 0xffff0000, v150
	v_lshlrev_b32_e32 v106, 16, v148
	v_and_b32_e32 v107, 0xffff0000, v148
	v_lshlrev_b32_e32 v108, 16, v149
	v_and_b32_e32 v109, 0xffff0000, v149
	v_lshlrev_b32_e32 v114, 16, v151
	v_and_b32_e32 v115, 0xffff0000, v151
	v_pk_fma_f32 v[100:101], v[100:101], v[132:133], v[106:107]
	v_pk_fma_f32 v[96:97], v[96:97], v[128:129], v[110:111]
	v_pk_fma_f32 v[102:103], v[102:103], v[134:135], v[108:109]
	v_pk_fma_f32 v[106:107], v[98:99], v[130:131], v[114:115]
	v_cvt_pk_bf16_f32 v98, v100, v101
	v_cvt_pk_bf16_f32 v99, v102, v103
	v_cvt_pk_bf16_f32 v100, v96, v97
	v_lshl_add_u64 v[96:97], s[8:9], 0, v[206:207]
	v_lshl_add_u64 v[96:97], v[96:97], 0, v[182:183]
	v_cvt_pk_bf16_f32 v101, v106, v107
	global_store_dwordx4 v[96:97], v[98:101], off
	v_lshlrev_b32_e32 v102, 16, v146
	v_and_b32_e32 v103, 0xffff0000, v146
	v_lshlrev_b32_e32 v98, 16, v144
	v_and_b32_e32 v99, 0xffff0000, v144
	v_lshlrev_b32_e32 v100, 16, v145
	v_and_b32_e32 v101, 0xffff0000, v145
	v_lshlrev_b32_e32 v106, 16, v147
	v_and_b32_e32 v107, 0xffff0000, v147
	v_pk_fma_f32 v[92:93], v[92:93], v[132:133], v[98:99]
	v_pk_fma_f32 v[94:95], v[94:95], v[134:135], v[100:101]
	v_pk_fma_f32 v[98:99], v[90:91], v[130:131], v[106:107]
	v_pk_fma_f32 v[90:91], v[88:89], v[128:129], v[102:103]
	v_cvt_pk_bf16_f32 v88, v92, v93
	v_lshl_add_u64 v[92:93], s[8:9], 0, v[204:205]
	v_cvt_pk_bf16_f32 v89, v94, v95
	v_lshl_add_u64 v[94:95], v[92:93], 0, v[182:183]
	v_cvt_pk_bf16_f32 v90, v90, v91
	v_cvt_pk_bf16_f32 v91, v98, v99
	global_store_dwordx4 v[94:95], v[88:91], off
	v_lshlrev_b32_e32 v92, 16, v138
	v_and_b32_e32 v93, 0xffff0000, v138
	v_lshlrev_b32_e32 v88, 16, v136
	v_and_b32_e32 v89, 0xffff0000, v136
	v_lshlrev_b32_e32 v98, 16, v139
	v_and_b32_e32 v99, 0xffff0000, v139
	v_pk_fma_f32 v[84:85], v[84:85], v[132:133], v[88:89]
	v_lshlrev_b32_e32 v90, 16, v137
	v_and_b32_e32 v91, 0xffff0000, v137
	v_pk_fma_f32 v[88:89], v[82:83], v[130:131], v[98:99]
	v_pk_fma_f32 v[82:83], v[80:81], v[128:129], v[92:93]
	v_cvt_pk_bf16_f32 v80, v84, v85
	v_lshl_add_u64 v[84:85], s[8:9], 0, v[200:201]
	v_pk_fma_f32 v[86:87], v[86:87], v[134:135], v[90:91]
	v_lshl_add_u64 v[92:93], v[84:85], 0, v[182:183]
	v_cvt_pk_bf16_f32 v81, v86, v87
	v_cvt_pk_bf16_f32 v82, v82, v83
	v_cvt_pk_bf16_f32 v83, v88, v89
	global_store_dwordx4 v[92:93], v[80:83], off
	v_lshlrev_b32_e32 v84, 16, v142
	v_and_b32_e32 v85, 0xffff0000, v142
	v_lshlrev_b32_e32 v80, 16, v140
	v_and_b32_e32 v81, 0xffff0000, v140
	v_lshlrev_b32_e32 v86, 16, v143
	v_and_b32_e32 v87, 0xffff0000, v143
	v_pk_fma_f32 v[76:77], v[76:77], v[132:133], v[80:81]
	v_lshlrev_b32_e32 v82, 16, v141
	v_and_b32_e32 v83, 0xffff0000, v141
	v_pk_fma_f32 v[80:81], v[74:75], v[130:131], v[86:87]
	v_pk_fma_f32 v[74:75], v[72:73], v[128:129], v[84:85]
	v_cvt_pk_bf16_f32 v72, v76, v77
	v_lshl_add_u64 v[76:77], s[8:9], 0, v[202:203]
	v_pk_fma_f32 v[78:79], v[78:79], v[134:135], v[82:83]
	v_lshl_add_u64 v[88:89], v[76:77], 0, v[182:183]
	v_cvt_pk_bf16_f32 v73, v78, v79
	v_cvt_pk_bf16_f32 v74, v74, v75
	v_cvt_pk_bf16_f32 v75, v80, v81
	global_store_dwordx4 v[88:89], v[72:75], off
	s_waitcnt vmcnt(6)
	v_lshlrev_b32_e32 v76, 16, v122
	v_and_b32_e32 v77, 0xffff0000, v122
	v_lshlrev_b32_e32 v72, 16, v120
	v_and_b32_e32 v73, 0xffff0000, v120
	v_lshlrev_b32_e32 v78, 16, v123
	v_and_b32_e32 v79, 0xffff0000, v123
	v_pk_fma_f32 v[68:69], v[68:69], v[132:133], v[72:73]
	v_pk_fma_f32 v[72:73], v[66:67], v[130:131], v[78:79]
	v_pk_fma_f32 v[66:67], v[64:65], v[128:129], v[76:77]
	v_cvt_pk_bf16_f32 v64, v68, v69
	v_lshl_add_u64 v[68:69], s[8:9], 0, v[210:211]
	v_lshlrev_b32_e32 v74, 16, v121
	v_and_b32_e32 v75, 0xffff0000, v121
	v_lshl_add_u64 v[90:91], v[68:69], 0, v[182:183]
	v_pk_fma_f32 v[70:71], v[70:71], v[134:135], v[74:75]
	s_mov_b64 s[8:9], s[58:59]
	v_cvt_pk_bf16_f32 v65, v70, v71
	v_cvt_pk_bf16_f32 v66, v66, v67
	v_cvt_pk_bf16_f32 v67, v72, v73
	global_store_dwordx4 v[90:91], v[64:67], off
	global_load_dwordx4 v[98:101], v[184:185], off offset:256
	global_load_dwordx4 v[106:109], v[186:187], off offset:256
	global_load_dwordx4 v[114:117], v[188:189], off offset:256
	global_load_dwordx4 v[84:87], v[190:191], off offset:256
	global_load_dwordx4 v[80:83], v[192:193], off offset:256
	global_load_dwordx4 v[76:79], v[194:195], off offset:256
	global_load_dwordx4 v[64:67], v[198:199], off offset:528
	global_load_dwordx4 v[68:71], v[198:199], off offset:512
	global_load_dwordx4 v[72:75], v[196:197], off offset:256
	s_waitcnt vmcnt(0)
	v_lshlrev_b32_e32 v102, 16, v98
	v_and_b32_e32 v103, 0xffff0000, v98
	v_lshlrev_b32_e32 v98, 16, v99
	v_and_b32_e32 v99, 0xffff0000, v99
	v_lshlrev_b32_e32 v110, 16, v100
	v_and_b32_e32 v111, 0xffff0000, v100
	v_lshlrev_b32_e32 v100, 16, v101
	v_and_b32_e32 v101, 0xffff0000, v101
	v_pk_fma_f32 v[62:63], v[62:63], v[70:71], v[98:99]
	v_pk_fma_f32 v[98:99], v[58:59], v[66:67], v[100:101]
	v_pk_fma_f32 v[58:59], v[56:57], v[64:65], v[110:111]
	v_pk_fma_f32 v[60:61], v[60:61], v[68:69], v[102:103]
	v_lshlrev_b32_e32 v100, 16, v109
	v_cvt_pk_bf16_f32 v56, v60, v61
	v_cvt_pk_bf16_f32 v57, v62, v63
	v_cvt_pk_bf16_f32 v58, v58, v59
	v_cvt_pk_bf16_f32 v59, v98, v99
	global_store_dwordx4 v[124:125], v[56:59], off offset:256
	global_load_dwordx4 v[56:59], v[126:127], off offset:256
	v_lshlrev_b32_e32 v60, 16, v106
	v_and_b32_e32 v61, 0xffff0000, v106
	v_lshlrev_b32_e32 v98, 16, v108
	v_and_b32_e32 v99, 0xffff0000, v108
	v_and_b32_e32 v101, 0xffff0000, v109
	v_lshlrev_b32_e32 v62, 16, v107
	v_and_b32_e32 v63, 0xffff0000, v107
	v_pk_fma_f32 v[52:53], v[52:53], v[68:69], v[60:61]
	v_pk_fma_f32 v[60:61], v[50:51], v[66:67], v[100:101]
	v_pk_fma_f32 v[50:51], v[48:49], v[64:65], v[98:99]
	v_pk_fma_f32 v[54:55], v[54:55], v[70:71], v[62:63]
	v_cvt_pk_bf16_f32 v48, v52, v53
	v_lshlrev_b32_e32 v52, 16, v116
	v_cvt_pk_bf16_f32 v49, v54, v55
	v_cvt_pk_bf16_f32 v50, v50, v51
	v_cvt_pk_bf16_f32 v51, v60, v61
	global_store_dwordx4 v[112:113], v[48:51], off offset:256
	v_and_b32_e32 v53, 0xffff0000, v116
	v_lshlrev_b32_e32 v54, 16, v117
	v_lshlrev_b32_e32 v48, 16, v114
	v_and_b32_e32 v49, 0xffff0000, v114
	v_lshlrev_b32_e32 v50, 16, v115
	v_and_b32_e32 v51, 0xffff0000, v115
	v_and_b32_e32 v55, 0xffff0000, v117
	v_pk_fma_f32 v[46:47], v[46:47], v[70:71], v[50:51]
	v_pk_fma_f32 v[44:45], v[44:45], v[68:69], v[48:49]
	v_pk_fma_f32 v[48:49], v[42:43], v[66:67], v[54:55]
	v_pk_fma_f32 v[42:43], v[40:41], v[64:65], v[52:53]
	v_cvt_pk_bf16_f32 v40, v44, v45
	v_cvt_pk_bf16_f32 v41, v46, v47
	v_lshlrev_b32_e32 v44, 16, v86
	v_cvt_pk_bf16_f32 v42, v42, v43
	v_cvt_pk_bf16_f32 v43, v48, v49
	global_store_dwordx4 v[104:105], v[40:43], off offset:256
	v_and_b32_e32 v45, 0xffff0000, v86
	v_lshlrev_b32_e32 v46, 16, v87
	v_lshlrev_b32_e32 v40, 16, v84
	v_and_b32_e32 v41, 0xffff0000, v84
	v_and_b32_e32 v47, 0xffff0000, v87
	v_lshlrev_b32_e32 v42, 16, v85
	v_and_b32_e32 v43, 0xffff0000, v85
	v_pk_fma_f32 v[36:37], v[36:37], v[68:69], v[40:41]
	v_pk_fma_f32 v[40:41], v[34:35], v[66:67], v[46:47]
	v_pk_fma_f32 v[34:35], v[32:33], v[64:65], v[44:45]
	v_pk_fma_f32 v[38:39], v[38:39], v[70:71], v[42:43]
	v_cvt_pk_bf16_f32 v32, v36, v37
	v_lshlrev_b32_e32 v36, 16, v82
	v_cvt_pk_bf16_f32 v33, v38, v39
	v_cvt_pk_bf16_f32 v34, v34, v35
	v_cvt_pk_bf16_f32 v35, v40, v41
	global_store_dwordx4 v[96:97], v[32:35], off offset:256
	v_and_b32_e32 v37, 0xffff0000, v82
	v_lshlrev_b32_e32 v38, 16, v83
	v_lshlrev_b32_e32 v32, 16, v80
	v_and_b32_e32 v33, 0xffff0000, v80
	v_lshlrev_b32_e32 v34, 16, v81
	v_and_b32_e32 v35, 0xffff0000, v81
	v_and_b32_e32 v39, 0xffff0000, v83
	v_pk_fma_f32 v[30:31], v[30:31], v[70:71], v[34:35]
	v_pk_fma_f32 v[28:29], v[28:29], v[68:69], v[32:33]
	v_pk_fma_f32 v[32:33], v[26:27], v[66:67], v[38:39]
	v_pk_fma_f32 v[26:27], v[24:25], v[64:65], v[36:37]
	v_cvt_pk_bf16_f32 v24, v28, v29
	v_cvt_pk_bf16_f32 v25, v30, v31
	v_lshlrev_b32_e32 v28, 16, v78
	v_cvt_pk_bf16_f32 v26, v26, v27
	v_cvt_pk_bf16_f32 v27, v32, v33
	global_store_dwordx4 v[94:95], v[24:27], off offset:256
	v_and_b32_e32 v29, 0xffff0000, v78
	v_lshlrev_b32_e32 v30, 16, v79
	v_lshlrev_b32_e32 v24, 16, v76
	v_and_b32_e32 v25, 0xffff0000, v76
	v_and_b32_e32 v31, 0xffff0000, v79
	v_lshlrev_b32_e32 v26, 16, v77
	v_and_b32_e32 v27, 0xffff0000, v77
	v_pk_fma_f32 v[20:21], v[20:21], v[68:69], v[24:25]
	v_pk_fma_f32 v[24:25], v[18:19], v[66:67], v[30:31]
	v_pk_fma_f32 v[18:19], v[16:17], v[64:65], v[28:29]
	v_pk_fma_f32 v[22:23], v[22:23], v[70:71], v[26:27]
	v_cvt_pk_bf16_f32 v16, v20, v21
	v_lshlrev_b32_e32 v20, 16, v74
	v_cvt_pk_bf16_f32 v17, v22, v23
	v_cvt_pk_bf16_f32 v18, v18, v19
	v_cvt_pk_bf16_f32 v19, v24, v25
	global_store_dwordx4 v[92:93], v[16:19], off offset:256
	v_and_b32_e32 v21, 0xffff0000, v74
	v_lshlrev_b32_e32 v22, 16, v75
	v_lshlrev_b32_e32 v16, 16, v72
	v_and_b32_e32 v17, 0xffff0000, v72
	v_lshlrev_b32_e32 v18, 16, v73
	v_and_b32_e32 v19, 0xffff0000, v73
	v_and_b32_e32 v23, 0xffff0000, v75
	v_pk_fma_f32 v[14:15], v[14:15], v[70:71], v[18:19]
	v_pk_fma_f32 v[12:13], v[12:13], v[68:69], v[16:17]
	v_pk_fma_f32 v[16:17], v[10:11], v[66:67], v[22:23]
	v_pk_fma_f32 v[10:11], v[8:9], v[64:65], v[20:21]
	v_cvt_pk_bf16_f32 v8, v12, v13
	v_cvt_pk_bf16_f32 v9, v14, v15
	s_waitcnt vmcnt(5)
	v_lshlrev_b32_e32 v12, 16, v58
	v_cvt_pk_bf16_f32 v10, v10, v11
	v_cvt_pk_bf16_f32 v11, v16, v17
	global_store_dwordx4 v[88:89], v[8:11], off offset:256
	v_and_b32_e32 v13, 0xffff0000, v58
	v_lshlrev_b32_e32 v14, 16, v59
	v_lshlrev_b32_e32 v8, 16, v56
	v_and_b32_e32 v9, 0xffff0000, v56
	v_and_b32_e32 v15, 0xffff0000, v59
	v_lshlrev_b32_e32 v10, 16, v57
	v_and_b32_e32 v11, 0xffff0000, v57
	v_pk_fma_f32 v[4:5], v[4:5], v[68:69], v[8:9]
	v_pk_fma_f32 v[8:9], v[2:3], v[66:67], v[14:15]
	v_pk_fma_f32 v[2:3], v[0:1], v[64:65], v[12:13]
	v_pk_fma_f32 v[6:7], v[6:7], v[70:71], v[10:11]
	v_cvt_pk_bf16_f32 v0, v4, v5
	s_nop 0
	v_cvt_pk_bf16_f32 v1, v6, v7
	v_cvt_pk_bf16_f32 v2, v2, v3
	v_cvt_pk_bf16_f32 v3, v8, v9
	global_store_dwordx4 v[90:91], v[0:3], off offset:256
	s_cbranch_vccz .LBB0_103
	s_waitcnt vmcnt(0)
	s_mov_b32 s90, s62
	s_cmpk_gt_u32 s36, 0xff
	s_cbranch_scc1 .LBB0_114
	s_barrier

.LBB0_130:
	s_add_u32 s8, s60, 0xfffc0080
	s_addc_u32 s9, s61, -1
	s_add_i32 s16, 0, 0x10000
	v_add_u32_e32 v150, s16, v168
	ds_read_b128 v[128:131], v150
	ds_read_b128 v[132:135], v150 offset:1024
	ds_read_b128 v[146:149], v150 offset:2048
	ds_read_b128 v[150:153], v150 offset:3072
	s_cmp_eq_u32 s15, 12
	s_cselect_b32 s9, s5, s9
	s_cselect_b32 s8, s10, s8
	s_cselect_b32 s63, s1, s14
	s_cselect_b32 s62, s12, s13
	v_lshl_add_u64 v[164:165], s[60:61], 0, v[142:143]
	s_add_i32 m0, s38, 0xc000
	ds_read_b128 v[154:157], v170
	ds_read_b128 v[172:175], v170 offset:1024
	ds_read_b128 v[176:179], v170 offset:2048
	ds_read_b128 v[180:183], v170 offset:3072
	ds_read_b128 v[184:187], v170 offset:4096
	ds_read_b128 v[188:191], v170 offset:5120
	ds_read_b128 v[192:195], v170 offset:6144
	ds_read_b128 v[196:199], v170 offset:7168
	global_load_lds_dwordx4 v[164:165], off
	v_lshl_add_u64 v[164:165], s[60:61], 0, v[144:145]
	s_add_i32 m0, s38, 0xe000
	s_nop 0
	global_load_lds_dwordx4 v[164:165], off
	s_waitcnt lgkmcnt(8)
	s_barrier
	s_waitcnt lgkmcnt(0)
	s_setprio 1
	s_waitcnt lgkmcnt(0)
	v_mfma_f32_16x16x32_bf16 v[124:127], v[128:131], v[154:157], v[124:127]
	v_mfma_f32_16x16x32_bf16 v[120:123], v[146:149], v[154:157], v[120:123]
	v_mfma_f32_16x16x32_bf16 v[116:119], v[128:131], v[176:179], v[116:119]
	v_mfma_f32_16x16x32_bf16 v[112:115], v[146:149], v[176:179], v[112:115]
	v_mfma_f32_16x16x32_bf16 v[108:111], v[128:131], v[184:187], v[108:111]
	v_mfma_f32_16x16x32_bf16 v[104:107], v[146:149], v[184:187], v[104:107]
	v_mfma_f32_16x16x32_bf16 v[100:103], v[128:131], v[192:195], v[100:103]
	v_mfma_f32_16x16x32_bf16 v[96:99], v[146:149], v[192:195], v[96:99]
	v_mfma_f32_16x16x32_bf16 v[124:127], v[132:135], v[172:175], v[124:127]
	v_mfma_f32_16x16x32_bf16 v[120:123], v[150:153], v[172:175], v[120:123]
	v_mfma_f32_16x16x32_bf16 v[116:119], v[132:135], v[180:183], v[116:119]
	v_mfma_f32_16x16x32_bf16 v[112:115], v[150:153], v[180:183], v[112:115]
	v_mfma_f32_16x16x32_bf16 v[108:111], v[132:135], v[188:191], v[108:111]
	v_mfma_f32_16x16x32_bf16 v[104:107], v[150:153], v[188:191], v[104:107]
	v_mfma_f32_16x16x32_bf16 v[100:103], v[132:135], v[196:199], v[100:103]
	v_mfma_f32_16x16x32_bf16 v[96:99], v[150:153], v[196:199], v[96:99]
	s_setprio 0
	s_barrier
	s_add_i32 s18, 0, 0x14000
	s_add_i32 s16, s16, s37
	v_add_u32_e32 v158, s18, v168
	v_lshl_add_u64 v[164:165], s[62:63], 0, v[160:161]
	s_mov_b32 m0, s16
	ds_read_b128 v[200:203], v158
	ds_read_b128 v[204:207], v158 offset:1024
	ds_read_b128 v[208:211], v158 offset:2048
	ds_read_b128 v[212:215], v158 offset:3072
	global_load_lds_dwordx4 v[164:165], off
	v_lshl_add_u64 v[166:167], s[62:63], 0, v[136:137]
	s_add_i32 m0, s16, 0x2000
	s_nop 0
	global_load_lds_dwordx4 v[166:167], off
	s_barrier
	s_waitcnt lgkmcnt(0)
	s_setprio 1
	s_waitcnt lgkmcnt(0)
	v_mfma_f32_16x16x32_bf16 v[68:71], v[200:203], v[154:157], v[68:71]
	v_mfma_f32_16x16x32_bf16 v[64:67], v[208:211], v[154:157], v[64:67]
	v_mfma_f32_16x16x32_bf16 v[52:55], v[200:203], v[176:179], v[52:55]
	v_mfma_f32_16x16x32_bf16 v[48:51], v[208:211], v[176:179], v[48:51]
	v_mfma_f32_16x16x32_bf16 v[44:47], v[200:203], v[184:187], v[44:47]
	v_mfma_f32_16x16x32_bf16 v[40:43], v[208:211], v[184:187], v[40:43]
	v_mfma_f32_16x16x32_bf16 v[36:39], v[200:203], v[192:195], v[36:39]
	v_mfma_f32_16x16x32_bf16 v[32:35], v[208:211], v[192:195], v[32:35]
	v_mfma_f32_16x16x32_bf16 v[68:71], v[204:207], v[172:175], v[68:71]
	v_mfma_f32_16x16x32_bf16 v[64:67], v[212:215], v[172:175], v[64:67]
	v_mfma_f32_16x16x32_bf16 v[52:55], v[204:207], v[180:183], v[52:55]
	v_mfma_f32_16x16x32_bf16 v[48:51], v[212:215], v[180:183], v[48:51]
	v_mfma_f32_16x16x32_bf16 v[44:47], v[204:207], v[188:191], v[44:47]
	v_mfma_f32_16x16x32_bf16 v[40:43], v[212:215], v[188:191], v[40:43]
	v_mfma_f32_16x16x32_bf16 v[36:39], v[204:207], v[196:199], v[36:39]
	v_mfma_f32_16x16x32_bf16 v[32:35], v[212:215], v[196:199], v[32:35]
	s_setprio 0
	s_mov_b32 m0, s38
	v_lshl_add_u64 v[216:217], s[8:9], 0, v[140:141]
	s_barrier
	ds_read_b128 v[154:157], v170 offset:16384
	ds_read_b128 v[172:175], v170 offset:17408
	ds_read_b128 v[176:179], v170 offset:18432
	ds_read_b128 v[180:183], v170 offset:19456
	ds_read_b128 v[184:187], v170 offset:20480
	ds_read_b128 v[188:191], v170 offset:21504
	ds_read_b128 v[192:195], v170 offset:22528
	ds_read_b128 v[196:199], v170 offset:23552
	global_load_lds_dwordx4 v[216:217], off
	v_lshl_add_u64 v[218:219], s[8:9], 0, v[138:139]
	s_mov_b32 m0, s39
	s_nop 0
	global_load_lds_dwordx4 v[218:219], off
	s_barrier
	s_waitcnt lgkmcnt(0)
	s_setprio 1
	s_waitcnt lgkmcnt(0)
	v_mfma_f32_16x16x32_bf16 v[92:95], v[128:131], v[154:157], v[92:95]
	v_mfma_f32_16x16x32_bf16 v[88:91], v[146:149], v[154:157], v[88:91]
	v_mfma_f32_16x16x32_bf16 v[84:87], v[128:131], v[176:179], v[84:87]
	v_mfma_f32_16x16x32_bf16 v[80:83], v[146:149], v[176:179], v[80:83]
	v_mfma_f32_16x16x32_bf16 v[76:79], v[128:131], v[184:187], v[76:79]
	v_mfma_f32_16x16x32_bf16 v[72:75], v[146:149], v[184:187], v[72:75]
	v_mfma_f32_16x16x32_bf16 v[60:63], v[128:131], v[192:195], v[60:63]
	v_mfma_f32_16x16x32_bf16 v[56:59], v[146:149], v[192:195], v[56:59]
	v_mfma_f32_16x16x32_bf16 v[92:95], v[132:135], v[172:175], v[92:95]
	v_mfma_f32_16x16x32_bf16 v[88:91], v[150:153], v[172:175], v[88:91]
	v_mfma_f32_16x16x32_bf16 v[84:87], v[132:135], v[180:183], v[84:87]
	v_mfma_f32_16x16x32_bf16 v[80:83], v[150:153], v[180:183], v[80:83]
	v_mfma_f32_16x16x32_bf16 v[76:79], v[132:135], v[188:191], v[76:79]
	v_mfma_f32_16x16x32_bf16 v[72:75], v[150:153], v[188:191], v[72:75]
	v_mfma_f32_16x16x32_bf16 v[60:63], v[132:135], v[196:199], v[60:63]
	v_mfma_f32_16x16x32_bf16 v[56:59], v[150:153], v[196:199], v[56:59]
	s_setprio 0
	s_barrier
	s_add_u32 s16, s62, 0x40000
	s_addc_u32 s17, s63, 0
	s_add_i32 s18, s18, s37
	v_lshl_add_u64 v[128:129], s[16:17], 0, v[160:161]
	s_mov_b32 m0, s18
	s_nop 0
	global_load_lds_dwordx4 v[128:129], off
	v_lshl_add_u64 v[128:129], s[16:17], 0, v[136:137]
	s_add_i32 m0, s18, 0x2000
	s_nop 0
	global_load_lds_dwordx4 v[128:129], off
	s_waitcnt vmcnt(6)
	s_barrier
	s_setprio 1
	v_mfma_f32_16x16x32_bf16 v[28:31], v[200:203], v[154:157], v[28:31]
	v_mfma_f32_16x16x32_bf16 v[24:27], v[208:211], v[154:157], v[24:27]
	v_mfma_f32_16x16x32_bf16 v[20:23], v[200:203], v[176:179], v[20:23]
	v_mfma_f32_16x16x32_bf16 v[16:19], v[208:211], v[176:179], v[16:19]
	v_mfma_f32_16x16x32_bf16 v[12:15], v[200:203], v[184:187], v[12:15]
	v_mfma_f32_16x16x32_bf16 v[8:11], v[208:211], v[184:187], v[8:11]
	v_mfma_f32_16x16x32_bf16 v[4:7], v[200:203], v[192:195], v[4:7]
	v_mfma_f32_16x16x32_bf16 v[0:3], v[208:211], v[192:195], v[0:3]
	v_mfma_f32_16x16x32_bf16 v[28:31], v[204:207], v[172:175], v[28:31]
	v_mfma_f32_16x16x32_bf16 v[24:27], v[212:215], v[172:175], v[24:27]
	v_mfma_f32_16x16x32_bf16 v[20:23], v[204:207], v[180:183], v[20:23]
	v_mfma_f32_16x16x32_bf16 v[16:19], v[212:215], v[180:183], v[16:19]
	v_mfma_f32_16x16x32_bf16 v[12:15], v[204:207], v[188:191], v[12:15]
	v_mfma_f32_16x16x32_bf16 v[8:11], v[212:215], v[188:191], v[8:11]
	v_mfma_f32_16x16x32_bf16 v[4:7], v[204:207], v[196:199], v[4:7]
	v_mfma_f32_16x16x32_bf16 v[0:3], v[212:215], v[196:199], v[0:3]
	s_setprio 0
	s_add_i32 s16, 0, 0x18000
	v_add_u32_e32 v150, s16, v168
	s_barrier
	ds_read_b128 v[128:131], v150
	ds_read_b128 v[132:135], v150 offset:1024
	ds_read_b128 v[146:149], v150 offset:2048
	ds_read_b128 v[150:153], v150 offset:3072
	s_add_u32 s8, s8, 0x40000
	s_addc_u32 s9, s9, 0
	s_mov_b32 m0, s40
	v_lshl_add_u64 v[200:201], s[8:9], 0, v[140:141]
	ds_read_b128 v[154:157], v170 offset:32768
	ds_read_b128 v[172:175], v170 offset:33792
	ds_read_b128 v[176:179], v170 offset:34816
	ds_read_b128 v[180:183], v170 offset:35840
	ds_read_b128 v[184:187], v170 offset:36864
	ds_read_b128 v[188:191], v170 offset:37888
	ds_read_b128 v[192:195], v170 offset:38912
	ds_read_b128 v[196:199], v170 offset:39936
	global_load_lds_dwordx4 v[200:201], off
	v_lshl_add_u64 v[200:201], s[8:9], 0, v[138:139]
	s_mov_b32 m0, s41
	s_nop 0
	global_load_lds_dwordx4 v[200:201], off
	s_waitcnt lgkmcnt(8)
	s_barrier
	s_waitcnt lgkmcnt(0)
	s_setprio 1
	s_waitcnt lgkmcnt(0)
	v_mfma_f32_16x16x32_bf16 v[124:127], v[128:131], v[154:157], v[124:127]
	v_mfma_f32_16x16x32_bf16 v[120:123], v[146:149], v[154:157], v[120:123]
	v_mfma_f32_16x16x32_bf16 v[116:119], v[128:131], v[176:179], v[116:119]
	v_mfma_f32_16x16x32_bf16 v[112:115], v[146:149], v[176:179], v[112:115]
	v_mfma_f32_16x16x32_bf16 v[108:111], v[128:131], v[184:187], v[108:111]
	v_mfma_f32_16x16x32_bf16 v[104:107], v[146:149], v[184:187], v[104:107]
	v_mfma_f32_16x16x32_bf16 v[100:103], v[128:131], v[192:195], v[100:103]
	v_mfma_f32_16x16x32_bf16 v[96:99], v[146:149], v[192:195], v[96:99]
	v_mfma_f32_16x16x32_bf16 v[124:127], v[132:135], v[172:175], v[124:127]
	v_mfma_f32_16x16x32_bf16 v[120:123], v[150:153], v[172:175], v[120:123]
	v_mfma_f32_16x16x32_bf16 v[116:119], v[132:135], v[180:183], v[116:119]
	v_mfma_f32_16x16x32_bf16 v[112:115], v[150:153], v[180:183], v[112:115]
	v_mfma_f32_16x16x32_bf16 v[108:111], v[132:135], v[188:191], v[108:111]
	v_mfma_f32_16x16x32_bf16 v[104:107], v[150:153], v[188:191], v[104:107]
	v_mfma_f32_16x16x32_bf16 v[100:103], v[132:135], v[196:199], v[100:103]
	v_mfma_f32_16x16x32_bf16 v[96:99], v[150:153], v[196:199], v[96:99]
	s_setprio 0
	s_barrier
	s_add_i32 s17, 0, 0x1c000
	s_add_i32 s8, s16, s37
	v_add_u32_e32 v158, s17, v168
	v_lshl_add_u64 v[164:165], v[164:165], 0, s[74:75]
	s_mov_b32 m0, s8
	ds_read_b128 v[200:203], v158
	ds_read_b128 v[204:207], v158 offset:1024
	ds_read_b128 v[208:211], v158 offset:2048
	ds_read_b128 v[212:215], v158 offset:3072
	global_load_lds_dwordx4 v[164:165], off
	v_lshl_add_u64 v[164:165], v[166:167], 0, s[74:75]
	s_add_i32 m0, s8, 0x2000
	s_nop 0
	global_load_lds_dwordx4 v[164:165], off
	s_barrier
	s_waitcnt lgkmcnt(0)
	s_setprio 1
	s_waitcnt lgkmcnt(0)
	v_mfma_f32_16x16x32_bf16 v[68:71], v[200:203], v[154:157], v[68:71]
	v_mfma_f32_16x16x32_bf16 v[64:67], v[208:211], v[154:157], v[64:67]
	v_mfma_f32_16x16x32_bf16 v[52:55], v[200:203], v[176:179], v[52:55]
	v_mfma_f32_16x16x32_bf16 v[48:51], v[208:211], v[176:179], v[48:51]
	v_mfma_f32_16x16x32_bf16 v[44:47], v[200:203], v[184:187], v[44:47]
	v_mfma_f32_16x16x32_bf16 v[40:43], v[208:211], v[184:187], v[40:43]
	v_mfma_f32_16x16x32_bf16 v[36:39], v[200:203], v[192:195], v[36:39]
	v_mfma_f32_16x16x32_bf16 v[32:35], v[208:211], v[192:195], v[32:35]
	v_mfma_f32_16x16x32_bf16 v[68:71], v[204:207], v[172:175], v[68:71]
	v_mfma_f32_16x16x32_bf16 v[64:67], v[212:215], v[172:175], v[64:67]
	v_mfma_f32_16x16x32_bf16 v[52:55], v[204:207], v[180:183], v[52:55]
	v_mfma_f32_16x16x32_bf16 v[48:51], v[212:215], v[180:183], v[48:51]
	v_mfma_f32_16x16x32_bf16 v[44:47], v[204:207], v[188:191], v[44:47]
	v_mfma_f32_16x16x32_bf16 v[40:43], v[212:215], v[188:191], v[40:43]
	v_mfma_f32_16x16x32_bf16 v[36:39], v[204:207], v[196:199], v[36:39]
	v_mfma_f32_16x16x32_bf16 v[32:35], v[212:215], v[196:199], v[32:35]
	s_setprio 0
	s_mov_b32 m0, s42
	v_lshl_add_u64 v[164:165], v[216:217], 0, s[74:75]
	s_barrier
	ds_read_b128 v[154:157], v170 offset:49152
	ds_read_b128 v[172:175], v170 offset:50176
	ds_read_b128 v[176:179], v170 offset:51200
	ds_read_b128 v[180:183], v170 offset:52224
	ds_read_b128 v[184:187], v170 offset:53248
	ds_read_b128 v[188:191], v170 offset:54272
	ds_read_b128 v[192:195], v170 offset:55296
	ds_read_b128 v[196:199], v170 offset:56320
	global_load_lds_dwordx4 v[164:165], off
	v_lshl_add_u64 v[164:165], v[218:219], 0, s[74:75]
	s_mov_b32 m0, s43
	s_nop 0
	global_load_lds_dwordx4 v[164:165], off
	s_barrier
	s_waitcnt lgkmcnt(0)
	s_setprio 1
	s_waitcnt lgkmcnt(0)
	v_mfma_f32_16x16x32_bf16 v[92:95], v[128:131], v[154:157], v[92:95]
	v_mfma_f32_16x16x32_bf16 v[88:91], v[146:149], v[154:157], v[88:91]
	v_mfma_f32_16x16x32_bf16 v[84:87], v[128:131], v[176:179], v[84:87]
	v_mfma_f32_16x16x32_bf16 v[80:83], v[146:149], v[176:179], v[80:83]
	v_mfma_f32_16x16x32_bf16 v[76:79], v[128:131], v[184:187], v[76:79]
	v_mfma_f32_16x16x32_bf16 v[72:75], v[146:149], v[184:187], v[72:75]
	v_mfma_f32_16x16x32_bf16 v[60:63], v[128:131], v[192:195], v[60:63]
	v_mfma_f32_16x16x32_bf16 v[56:59], v[146:149], v[192:195], v[56:59]
	v_mfma_f32_16x16x32_bf16 v[92:95], v[132:135], v[172:175], v[92:95]
	v_mfma_f32_16x16x32_bf16 v[88:91], v[150:153], v[172:175], v[88:91]
	v_mfma_f32_16x16x32_bf16 v[84:87], v[132:135], v[180:183], v[84:87]
	v_mfma_f32_16x16x32_bf16 v[80:83], v[150:153], v[180:183], v[80:83]
	v_mfma_f32_16x16x32_bf16 v[76:79], v[132:135], v[188:191], v[76:79]
	v_mfma_f32_16x16x32_bf16 v[72:75], v[150:153], v[188:191], v[72:75]
	v_mfma_f32_16x16x32_bf16 v[60:63], v[132:135], v[196:199], v[60:63]
	v_mfma_f32_16x16x32_bf16 v[56:59], v[150:153], v[196:199], v[56:59]
	s_setprio 0
	s_barrier
	s_add_u32 s8, s62, 0x40080
	s_addc_u32 s9, s63, 0
	s_add_i32 s16, s17, s37
	v_lshl_add_u64 v[128:129], s[8:9], 0, v[160:161]
	s_mov_b32 m0, s16
	s_nop 0
	global_load_lds_dwordx4 v[128:129], off
	v_lshl_add_u64 v[128:129], s[8:9], 0, v[136:137]
	s_add_i32 m0, s16, 0x2000
	s_nop 0
	global_load_lds_dwordx4 v[128:129], off
	s_waitcnt vmcnt(6)
	s_barrier
	s_setprio 1
	v_mfma_f32_16x16x32_bf16 v[28:31], v[200:203], v[154:157], v[28:31]
	v_mfma_f32_16x16x32_bf16 v[24:27], v[208:211], v[154:157], v[24:27]
	v_mfma_f32_16x16x32_bf16 v[20:23], v[200:203], v[176:179], v[20:23]
	v_mfma_f32_16x16x32_bf16 v[16:19], v[208:211], v[176:179], v[16:19]
	v_mfma_f32_16x16x32_bf16 v[12:15], v[200:203], v[184:187], v[12:15]
	v_mfma_f32_16x16x32_bf16 v[8:11], v[208:211], v[184:187], v[8:11]
	v_mfma_f32_16x16x32_bf16 v[4:7], v[200:203], v[192:195], v[4:7]
	v_mfma_f32_16x16x32_bf16 v[0:3], v[208:211], v[192:195], v[0:3]
	v_mfma_f32_16x16x32_bf16 v[28:31], v[204:207], v[172:175], v[28:31]
	v_mfma_f32_16x16x32_bf16 v[24:27], v[212:215], v[172:175], v[24:27]
	v_mfma_f32_16x16x32_bf16 v[20:23], v[204:207], v[180:183], v[20:23]
	v_mfma_f32_16x16x32_bf16 v[16:19], v[212:215], v[180:183], v[16:19]
	v_mfma_f32_16x16x32_bf16 v[12:15], v[204:207], v[188:191], v[12:15]
	v_mfma_f32_16x16x32_bf16 v[8:11], v[212:215], v[188:191], v[8:11]
	v_mfma_f32_16x16x32_bf16 v[4:7], v[204:207], v[196:199], v[4:7]
	v_mfma_f32_16x16x32_bf16 v[0:3], v[212:215], v[196:199], v[0:3]
	s_setprio 0
	s_add_i32 s15, s15, 2
	s_add_u32 s60, s60, 0x100
	s_addc_u32 s61, s61, 0
	s_add_u32 s13, s13, 0x100
	s_addc_u32 s14, s14, 0
	s_cmp_gt_u32 s15, 13
	s_barrier
	s_cbranch_scc0 .LBB0_130
	v_lshl_add_u32 v146, s65, 8, v159
	v_readlane_b32 s8, v250, 14
	v_ashrrev_i32_e32 v147, 31, v146
	v_readlane_b32 s9, v250, 15
	v_readlane_b32 s1, v250, 16
	v_lshl_or_b32 v156, s66, 8, v169
	v_lshl_add_u64 v[128:129], v[146:147], 3, s[8:9]
	global_load_dwordx2 v[130:131], v[128:129], off
	s_ashr_i32 s8, s65, 5
	s_ashr_i32 s9, s8, 31
	s_lshl_b64 s[8:9], s[8:9], 14
	s_add_u32 s8, s1, s8
	v_readlane_b32 s1, v250, 17
	v_ashrrev_i32_e32 v157, 31, v156
	s_addc_u32 s9, s1, s9
	v_lshl_add_u64 v[164:165], v[156:157], 2, s[8:9]
	v_readlane_b32 s8, v253, 29
	v_readlane_b32 s9, v253, 30
	s_mov_b32 s1, 0x100000
	s_mov_b32 s66, s0
	s_mov_b32 s65, s4
	s_mov_b64 s[20:21], s[6:7]
	v_readlane_b32 s62, v255, 4
	v_readlane_b32 s63, v255, 5
	s_waitcnt vmcnt(0)
	v_ffbh_u32_e32 v132, v131
	v_min_u32_e32 v132, 32, v132
	v_lshlrev_b64 v[130:131], v132, v[130:131]
	v_min_u32_e32 v130, 1, v130
	v_or_b32_e32 v130, v131, v130
	v_cvt_f32_u32_e32 v130, v130
	v_sub_u32_e32 v131, 32, v132
	v_ldexp_f32 v130, v130, v131
	v_mul_f32_e32 v130, 0x37800000, v130
	v_fmamk_f32 v158, v130, 0x3a800000, v240
	global_load_dwordx2 v[130:131], v[128:129], off offset:128
	v_cmp_gt_f32_e32 vcc, s53, v158
	v_mul_f32_e32 v162, 0x4b800000, v158
	s_waitcnt vmcnt(0)
	v_ffbh_u32_e32 v132, v131
	v_min_u32_e32 v132, 32, v132
	v_lshlrev_b64 v[130:131], v132, v[130:131]
	v_min_u32_e32 v130, 1, v130
	v_or_b32_e32 v130, v131, v130
	v_cvt_f32_u32_e32 v130, v130
	v_sub_u32_e32 v131, 32, v132
	v_cndmask_b32_e32 v158, v158, v162, vcc
	v_rsq_f32_e32 v158, v158
	v_ldexp_f32 v130, v130, v131
	v_mul_f32_e32 v130, 0x37800000, v130
	v_fmamk_f32 v171, v130, 0x3a800000, v240
	global_load_dwordx2 v[130:131], v[128:129], off offset:256
	v_mul_f32_e32 v162, 0x45800000, v158
	v_cndmask_b32_e32 v184, v158, v162, vcc
	v_cmp_gt_f32_e32 vcc, s53, v171
	v_mul_f32_e32 v158, 0x4b800000, v171
	s_waitcnt vmcnt(0)
	v_ffbh_u32_e32 v132, v131
	v_min_u32_e32 v132, 32, v132
	v_lshlrev_b64 v[130:131], v132, v[130:131]
	v_min_u32_e32 v130, 1, v130
	v_or_b32_e32 v130, v131, v130
	v_cvt_f32_u32_e32 v130, v130
	v_sub_u32_e32 v131, 32, v132
	v_cndmask_b32_e32 v158, v171, v158, vcc
	v_rsq_f32_e32 v158, v158
	v_ldexp_f32 v130, v130, v131
	v_mul_f32_e32 v130, 0x37800000, v130
	v_fmamk_f32 v172, v130, 0x3a800000, v240
	global_load_dwordx2 v[130:131], v[128:129], off offset:384
	v_mul_f32_e32 v162, 0x45800000, v158
	v_cndmask_b32_e32 v182, v158, v162, vcc
	v_cmp_gt_f32_e32 vcc, s53, v172
	v_mul_f32_e32 v158, 0x4b800000, v172
	s_waitcnt vmcnt(0)
	v_ffbh_u32_e32 v132, v131
	v_min_u32_e32 v132, 32, v132
	v_lshlrev_b64 v[130:131], v132, v[130:131]
	v_min_u32_e32 v130, 1, v130
	v_or_b32_e32 v130, v131, v130
	v_cvt_f32_u32_e32 v130, v130
	v_sub_u32_e32 v131, 32, v132
	v_cndmask_b32_e32 v158, v172, v158, vcc
	v_rsq_f32_e32 v158, v158
	v_ldexp_f32 v130, v130, v131
	v_mul_f32_e32 v130, 0x37800000, v130
	v_fmamk_f32 v173, v130, 0x3a800000, v240
	global_load_dwordx2 v[130:131], v[128:129], off offset:1024
	v_mul_f32_e32 v162, 0x45800000, v158
	v_cndmask_b32_e32 v180, v158, v162, vcc
	v_cmp_gt_f32_e32 vcc, s53, v173
	v_mul_f32_e32 v158, 0x4b800000, v173
	s_waitcnt vmcnt(0)
	v_ffbh_u32_e32 v132, v131
	v_min_u32_e32 v132, 32, v132
	v_lshlrev_b64 v[130:131], v132, v[130:131]
	v_min_u32_e32 v130, 1, v130
	v_or_b32_e32 v130, v131, v130
	v_cvt_f32_u32_e32 v130, v130
	v_sub_u32_e32 v131, 32, v132
	v_cndmask_b32_e32 v158, v173, v158, vcc
	v_rsq_f32_e32 v158, v158
	v_ldexp_f32 v130, v130, v131
	v_mul_f32_e32 v130, 0x37800000, v130
	v_fmamk_f32 v174, v130, 0x3a800000, v240
	global_load_dwordx2 v[130:131], v[128:129], off offset:1152
	v_mul_f32_e32 v162, 0x45800000, v158
	v_cndmask_b32_e32 v178, v158, v162, vcc
	v_cmp_gt_f32_e32 vcc, s53, v174
	v_mul_f32_e32 v158, 0x4b800000, v174
	s_waitcnt vmcnt(0)
	v_ffbh_u32_e32 v132, v131
	v_min_u32_e32 v132, 32, v132
	v_lshlrev_b64 v[130:131], v132, v[130:131]
	v_min_u32_e32 v130, 1, v130
	v_or_b32_e32 v130, v131, v130
	v_cvt_f32_u32_e32 v130, v130
	v_sub_u32_e32 v131, 32, v132
	v_cndmask_b32_e32 v158, v174, v158, vcc
	v_rsq_f32_e32 v158, v158
	v_ldexp_f32 v130, v130, v131
	v_mul_f32_e32 v130, 0x37800000, v130
	v_fmamk_f32 v175, v130, 0x3a800000, v240
	global_load_dwordx2 v[130:131], v[128:129], off offset:1280
	v_mul_f32_e32 v162, 0x45800000, v158
	global_load_dwordx2 v[128:129], v[128:129], off offset:1408
	v_cndmask_b32_e32 v176, v158, v162, vcc
	v_cmp_gt_f32_e32 vcc, s53, v175
	v_mul_f32_e32 v158, 0x4b800000, v175
	s_waitcnt vmcnt(0)
	v_ffbh_u32_e32 v132, v131
	v_min_u32_e32 v132, 32, v132
	v_lshlrev_b64 v[130:131], v132, v[130:131]
	v_min_u32_e32 v130, 1, v130
	v_or_b32_e32 v130, v131, v130
	v_cvt_f32_u32_e32 v130, v130
	v_sub_u32_e32 v131, 32, v132
	v_cndmask_b32_e32 v158, v175, v158, vcc
	v_rsq_f32_e32 v158, v158
	v_ldexp_f32 v130, v130, v131
	v_mul_f32_e32 v130, 0x37800000, v130
	v_fmamk_f32 v177, v130, 0x3a800000, v240
	v_ffbh_u32_e32 v130, v129
	v_min_u32_e32 v130, 32, v130
	v_lshlrev_b64 v[128:129], v130, v[128:129]
	v_min_u32_e32 v128, 1, v128
	v_or_b32_e32 v128, v129, v128
	v_cvt_f32_u32_e32 v128, v128
	v_sub_u32_e32 v129, 32, v130
	v_mul_f32_e32 v162, 0x45800000, v158
	v_cndmask_b32_e32 v174, v158, v162, vcc
	v_ldexp_f32 v128, v128, v129
	v_mul_f32_e32 v128, 0x37800000, v128
	v_fmamk_f32 v179, v128, 0x3a800000, v240
	global_load_dwordx4 v[128:131], v[164:165], off offset:16
	global_load_dwordx4 v[132:135], v[164:165], off
	v_cmp_gt_f32_e32 vcc, s53, v177
	v_mul_f32_e32 v158, 0x4b800000, v177
	s_waitcnt vmcnt(0)
	v_pk_add_f32 v[148:149], v[130:131], 0 op_sel_hi:[1,0]
	v_pk_add_f32 v[152:153], v[134:135], 0 op_sel_hi:[1,0]
	v_pk_add_f32 v[154:155], v[132:133], 0 op_sel_hi:[1,0]
	v_pk_add_f32 v[150:151], v[128:129], 0 op_sel_hi:[1,0]
	global_load_dwordx4 v[128:131], v[164:165], off offset:528
	global_load_dwordx4 v[132:135], v[164:165], off offset:512
	v_cndmask_b32_e32 v158, v177, v158, vcc
	v_rsq_f32_e32 v158, v158
	v_pk_fma_f32 v[122:123], v[122:123], v[184:185], v[148:149] op_sel_hi:[1,0,1]
	v_pk_fma_f32 v[126:127], v[126:127], v[184:185], v[152:153] op_sel_hi:[1,0,1]
	v_pk_fma_f32 v[124:125], v[124:125], v[184:185], v[154:155] op_sel_hi:[1,0,1]
	v_mul_f32_e32 v162, 0x45800000, v158
	v_cndmask_b32_e32 v172, v158, v162, vcc
	v_cmp_gt_f32_e32 vcc, s53, v179
	v_mul_f32_e32 v158, 0x4b800000, v179
	v_pk_fma_f32 v[120:121], v[120:121], v[184:185], v[150:151] op_sel_hi:[1,0,1]
	v_cndmask_b32_e32 v158, v179, v158, vcc
	v_rsq_f32_e32 v158, v158
	v_max_f32_e32 v122, 0, v122
	v_max_f32_e32 v124, 0, v124
	v_max_f32_e32 v120, 0, v120
	v_mul_f32_e32 v162, 0x45800000, v158
	v_cndmask_b32_e32 v158, v158, v162, vcc
	v_max_f32_e32 v121, 0, v121
	v_mul_f32_e32 v162, v122, v122
	v_max_f32_e32 v122, 0, v127
	v_mul_f32_e32 v124, v124, v124
	v_mul_f32_e32 v120, v120, v120
	v_max_f32_e32 v125, 0, v125
	v_mul_f32_e32 v121, v121, v121
	v_max_f32_e32 v126, 0, v126
	v_mul_f32_e32 v127, v122, v122
	v_max_f32_e32 v122, 0, v123
	v_mul_f32_e32 v125, v125, v125
	v_mul_f32_e32 v126, v126, v126
	v_mul_f32_e32 v164, v122, v122
	v_cvt_pk_bf16_f32 v122, v124, v125
	v_cvt_pk_bf16_f32 v123, v126, v127
	v_cvt_pk_bf16_f32 v124, v120, v121
	v_lshlrev_b64 v[120:121], 13, v[146:147]
	v_lshl_add_u64 v[120:121], s[8:9], 0, v[120:121]
	v_lshlrev_b64 v[126:127], 1, v[156:157]
	v_pk_fma_f32 v[114:115], v[114:115], v[182:183], v[148:149] op_sel_hi:[1,0,1]
	v_lshl_add_u64 v[120:121], v[120:121], 0, v[126:127]
	v_pk_fma_f32 v[118:119], v[118:119], v[182:183], v[152:153] op_sel_hi:[1,0,1]
	v_pk_fma_f32 v[116:117], v[116:117], v[182:183], v[154:155] op_sel_hi:[1,0,1]
	v_pk_fma_f32 v[112:113], v[112:113], v[182:183], v[150:151] op_sel_hi:[1,0,1]
	v_max_f32_e32 v114, 0, v114
	v_cvt_pk_bf16_f32 v125, v162, v164
	global_store_dwordx4 v[120:121], v[122:125], off
	v_max_f32_e32 v116, 0, v116
	v_max_f32_e32 v112, 0, v112
	v_mul_f32_e32 v122, v114, v114
	v_max_f32_e32 v114, 0, v119
	v_mul_f32_e32 v116, v116, v116
	v_mul_f32_e32 v112, v112, v112
	v_max_f32_e32 v117, 0, v117
	v_max_f32_e32 v113, 0, v113
	v_max_f32_e32 v118, 0, v118
	v_mul_f32_e32 v119, v114, v114
	v_max_f32_e32 v114, 0, v115
	v_mul_f32_e32 v117, v117, v117
	v_mul_f32_e32 v113, v113, v113
	v_mul_f32_e32 v118, v118, v118
	v_mul_f32_e32 v123, v114, v114
	v_cvt_pk_bf16_f32 v114, v116, v117
	v_cvt_pk_bf16_f32 v115, v118, v119
	v_cvt_pk_bf16_f32 v116, v112, v113
	v_or_b32_e32 v112, 16, v146
	v_ashrrev_i32_e32 v113, 31, v112
	v_lshlrev_b64 v[112:113], 13, v[112:113]
	v_lshl_add_u64 v[112:113], s[8:9], 0, v[112:113]
	v_pk_fma_f32 v[106:107], v[106:107], v[180:181], v[148:149] op_sel_hi:[1,0,1]
	v_lshl_add_u64 v[112:113], v[112:113], 0, v[126:127]
	v_pk_fma_f32 v[110:111], v[110:111], v[180:181], v[152:153] op_sel_hi:[1,0,1]
	v_pk_fma_f32 v[108:109], v[108:109], v[180:181], v[154:155] op_sel_hi:[1,0,1]
	v_pk_fma_f32 v[104:105], v[104:105], v[180:181], v[150:151] op_sel_hi:[1,0,1]
	v_max_f32_e32 v106, 0, v106
	v_cvt_pk_bf16_f32 v117, v122, v123
	global_store_dwordx4 v[112:113], v[114:117], off
	v_max_f32_e32 v108, 0, v108
	v_max_f32_e32 v104, 0, v104
	v_mul_f32_e32 v114, v106, v106
	v_max_f32_e32 v106, 0, v111
	v_mul_f32_e32 v108, v108, v108
	v_mul_f32_e32 v104, v104, v104
	v_max_f32_e32 v109, 0, v109
	v_max_f32_e32 v105, 0, v105
	v_max_f32_e32 v110, 0, v110
	v_mul_f32_e32 v111, v106, v106
	v_max_f32_e32 v106, 0, v107
	v_mul_f32_e32 v109, v109, v109
	v_mul_f32_e32 v105, v105, v105
	v_mul_f32_e32 v110, v110, v110
	v_mul_f32_e32 v115, v106, v106
	v_cvt_pk_bf16_f32 v106, v108, v109
	v_cvt_pk_bf16_f32 v107, v110, v111
	v_cvt_pk_bf16_f32 v108, v104, v105
	v_or_b32_e32 v104, 32, v146
	v_ashrrev_i32_e32 v105, 31, v104
	v_lshlrev_b64 v[104:105], 13, v[104:105]
	v_lshl_add_u64 v[104:105], s[8:9], 0, v[104:105]
	v_pk_fma_f32 v[98:99], v[98:99], v[178:179], v[148:149] op_sel_hi:[1,0,1]
	v_lshl_add_u64 v[104:105], v[104:105], 0, v[126:127]
	v_pk_fma_f32 v[102:103], v[102:103], v[178:179], v[152:153] op_sel_hi:[1,0,1]
	v_pk_fma_f32 v[100:101], v[100:101], v[178:179], v[154:155] op_sel_hi:[1,0,1]
	v_pk_fma_f32 v[96:97], v[96:97], v[178:179], v[150:151] op_sel_hi:[1,0,1]
	v_max_f32_e32 v98, 0, v98
	v_cvt_pk_bf16_f32 v109, v114, v115
	global_store_dwordx4 v[104:105], v[106:109], off
	v_max_f32_e32 v100, 0, v100
	v_max_f32_e32 v96, 0, v96
	v_mul_f32_e32 v106, v98, v98
	v_max_f32_e32 v98, 0, v103
	v_mul_f32_e32 v100, v100, v100
	v_mul_f32_e32 v96, v96, v96
	v_max_f32_e32 v101, 0, v101
	v_max_f32_e32 v97, 0, v97
	v_max_f32_e32 v102, 0, v102
	v_mul_f32_e32 v103, v98, v98
	v_max_f32_e32 v98, 0, v99
	v_mul_f32_e32 v101, v101, v101
	v_mul_f32_e32 v97, v97, v97
	v_mul_f32_e32 v102, v102, v102
	v_mul_f32_e32 v107, v98, v98
	v_cvt_pk_bf16_f32 v98, v100, v101
	v_cvt_pk_bf16_f32 v99, v102, v103
	v_cvt_pk_bf16_f32 v100, v96, v97
	v_or_b32_e32 v96, 48, v146
	v_ashrrev_i32_e32 v97, 31, v96
	v_lshlrev_b64 v[96:97], 13, v[96:97]
	v_lshl_add_u64 v[96:97], s[8:9], 0, v[96:97]
	v_pk_fma_f32 v[90:91], v[90:91], v[176:177], v[148:149] op_sel_hi:[1,0,1]
	v_lshl_add_u64 v[96:97], v[96:97], 0, v[126:127]
	v_pk_fma_f32 v[94:95], v[94:95], v[176:177], v[152:153] op_sel_hi:[1,0,1]
	v_max_f32_e32 v90, 0, v90
	v_cvt_pk_bf16_f32 v101, v106, v107
	global_store_dwordx4 v[96:97], v[98:101], off
	v_pk_fma_f32 v[92:93], v[92:93], v[176:177], v[154:155] op_sel_hi:[1,0,1]
	v_max_f32_e32 v94, 0, v94
	v_mul_f32_e32 v98, v90, v90
	v_max_f32_e32 v90, 0, v95
	v_max_f32_e32 v92, 0, v92
	v_max_f32_e32 v93, 0, v93
	v_mul_f32_e32 v94, v94, v94
	v_mul_f32_e32 v95, v90, v90
	v_max_f32_e32 v90, 0, v91
	v_pk_fma_f32 v[88:89], v[88:89], v[176:177], v[150:151] op_sel_hi:[1,0,1]
	v_mul_f32_e32 v92, v92, v92
	v_mul_f32_e32 v93, v93, v93
	v_mul_f32_e32 v99, v90, v90
	v_cvt_pk_bf16_f32 v90, v92, v93
	v_cvt_pk_bf16_f32 v91, v94, v95
	v_add_co_u32_e32 v94, vcc, s1, v120
	v_pk_fma_f32 v[82:83], v[82:83], v[174:175], v[148:149] op_sel_hi:[1,0,1]
	v_max_f32_e32 v88, 0, v88
	v_max_f32_e32 v89, 0, v89
	v_addc_co_u32_e32 v95, vcc, 0, v121, vcc
	v_pk_fma_f32 v[86:87], v[86:87], v[174:175], v[152:153] op_sel_hi:[1,0,1]
	v_max_f32_e32 v82, 0, v82
	v_mul_f32_e32 v88, v88, v88
	v_mul_f32_e32 v89, v89, v89
	v_cvt_pk_bf16_f32 v92, v88, v89
	v_cvt_pk_bf16_f32 v93, v98, v99
	global_store_dwordx4 v[94:95], v[90:93], off
	v_pk_fma_f32 v[84:85], v[84:85], v[174:175], v[154:155] op_sel_hi:[1,0,1]
	v_max_f32_e32 v86, 0, v86
	v_mul_f32_e32 v90, v82, v82
	v_max_f32_e32 v82, 0, v87
	v_max_f32_e32 v84, 0, v84
	v_max_f32_e32 v85, 0, v85
	v_mul_f32_e32 v86, v86, v86
	v_mul_f32_e32 v87, v82, v82
	v_max_f32_e32 v82, 0, v83
	s_mov_b32 s1, 0x120000
	v_pk_fma_f32 v[80:81], v[80:81], v[174:175], v[150:151] op_sel_hi:[1,0,1]
	v_mul_f32_e32 v84, v84, v84
	v_mul_f32_e32 v85, v85, v85
	v_mul_f32_e32 v91, v82, v82
	v_cvt_pk_bf16_f32 v82, v84, v85
	v_cvt_pk_bf16_f32 v83, v86, v87
	v_add_co_u32_e32 v86, vcc, s1, v120
	v_pk_fma_f32 v[74:75], v[74:75], v[172:173], v[148:149] op_sel_hi:[1,0,1]
	v_max_f32_e32 v80, 0, v80
	v_max_f32_e32 v81, 0, v81
	v_addc_co_u32_e32 v87, vcc, 0, v121, vcc
	v_pk_fma_f32 v[78:79], v[78:79], v[172:173], v[152:153] op_sel_hi:[1,0,1]
	v_max_f32_e32 v74, 0, v74
	v_mul_f32_e32 v80, v80, v80
	v_mul_f32_e32 v81, v81, v81
	v_cvt_pk_bf16_f32 v84, v80, v81
	v_cvt_pk_bf16_f32 v85, v90, v91
	global_store_dwordx4 v[86:87], v[82:85], off
	v_pk_fma_f32 v[76:77], v[76:77], v[172:173], v[154:155] op_sel_hi:[1,0,1]
	v_max_f32_e32 v78, 0, v78
	v_mul_f32_e32 v82, v74, v74
	v_max_f32_e32 v74, 0, v79
	v_max_f32_e32 v76, 0, v76
	v_max_f32_e32 v77, 0, v77
	v_mul_f32_e32 v78, v78, v78
	v_mul_f32_e32 v79, v74, v74
	v_max_f32_e32 v74, 0, v75
	s_mov_b32 s1, 0x140000
	v_pk_fma_f32 v[72:73], v[72:73], v[172:173], v[150:151] op_sel_hi:[1,0,1]
	v_mul_f32_e32 v76, v76, v76
	v_mul_f32_e32 v77, v77, v77
	v_mul_f32_e32 v83, v74, v74
	v_cvt_pk_bf16_f32 v74, v76, v77
	v_cvt_pk_bf16_f32 v75, v78, v79
	v_add_co_u32_e32 v78, vcc, s1, v120
	v_pk_fma_f32 v[58:59], v[58:59], v[158:159], v[148:149] op_sel_hi:[1,0,1]
	v_max_f32_e32 v72, 0, v72
	v_max_f32_e32 v73, 0, v73
	v_addc_co_u32_e32 v79, vcc, 0, v121, vcc
	v_pk_fma_f32 v[62:63], v[62:63], v[158:159], v[152:153] op_sel_hi:[1,0,1]
	v_max_f32_e32 v58, 0, v58
	v_mul_f32_e32 v72, v72, v72
	v_mul_f32_e32 v73, v73, v73
	v_cvt_pk_bf16_f32 v76, v72, v73
	v_cvt_pk_bf16_f32 v77, v82, v83
	global_store_dwordx4 v[78:79], v[74:77], off
	v_pk_fma_f32 v[60:61], v[60:61], v[158:159], v[154:155] op_sel_hi:[1,0,1]
	v_max_f32_e32 v62, 0, v62
	v_mul_f32_e32 v74, v58, v58
	v_max_f32_e32 v58, 0, v63
	v_max_f32_e32 v60, 0, v60
	v_max_f32_e32 v61, 0, v61
	v_mul_f32_e32 v62, v62, v62
	v_mul_f32_e32 v63, v58, v58
	v_max_f32_e32 v58, 0, v59
	s_mov_b32 s1, 0x160000
	v_pk_fma_f32 v[56:57], v[56:57], v[158:159], v[150:151] op_sel_hi:[1,0,1]
	v_mul_f32_e32 v60, v60, v60
	v_mul_f32_e32 v61, v61, v61
	v_mul_f32_e32 v75, v58, v58
	v_cvt_pk_bf16_f32 v58, v60, v61
	v_cvt_pk_bf16_f32 v59, v62, v63
	v_add_co_u32_e32 v62, vcc, s1, v120
	s_waitcnt vmcnt(7)
	v_pk_add_f32 v[134:135], v[134:135], 0 op_sel_hi:[1,0]
	v_max_f32_e32 v56, 0, v56
	v_max_f32_e32 v57, 0, v57
	v_addc_co_u32_e32 v63, vcc, 0, v121, vcc
	v_pk_add_f32 v[130:131], v[130:131], 0 op_sel_hi:[1,0]
	v_mul_f32_e32 v56, v56, v56
	v_mul_f32_e32 v57, v57, v57
	v_cvt_pk_bf16_f32 v60, v56, v57
	v_cvt_pk_bf16_f32 v61, v74, v75
	global_store_dwordx4 v[62:63], v[58:61], off
	v_pk_fma_f32 v[62:63], v[66:67], v[184:185], v[130:131] op_sel_hi:[1,0,1]
	v_pk_add_f32 v[132:133], v[132:133], 0 op_sel_hi:[1,0]
	v_pk_fma_f32 v[58:59], v[70:71], v[184:185], v[134:135] op_sel_hi:[1,0,1]
	v_pk_add_f32 v[128:129], v[128:129], 0 op_sel_hi:[1,0]
	v_max_f32_e32 v58, 0, v58
	v_mul_f32_e32 v66, v58, v58
	v_max_f32_e32 v58, 0, v62
	v_pk_fma_f32 v[60:61], v[68:69], v[184:185], v[132:133] op_sel_hi:[1,0,1]
	v_mul_f32_e32 v62, v58, v58
	v_max_f32_e32 v58, 0, v59
	v_pk_fma_f32 v[64:65], v[64:65], v[184:185], v[128:129] op_sel_hi:[1,0,1]
	v_max_f32_e32 v60, 0, v60
	v_max_f32_e32 v61, 0, v61
	v_mul_f32_e32 v59, v58, v58
	v_max_f32_e32 v58, 0, v63
	v_pk_fma_f32 v[48:49], v[48:49], v[182:183], v[128:129] op_sel_hi:[1,0,1]
	v_mul_f32_e32 v60, v60, v60
	v_max_f32_e32 v64, 0, v64
	v_mul_f32_e32 v61, v61, v61
	v_max_f32_e32 v65, 0, v65
	v_mul_f32_e32 v63, v58, v58
	v_cvt_pk_bf16_f32 v58, v60, v61
	v_pk_fma_f32 v[52:53], v[52:53], v[182:183], v[132:133] op_sel_hi:[1,0,1]
	v_pk_fma_f32 v[50:51], v[50:51], v[182:183], v[130:131] op_sel_hi:[1,0,1]
	v_max_f32_e32 v48, 0, v48
	v_mul_f32_e32 v64, v64, v64
	v_mul_f32_e32 v65, v65, v65
	v_cvt_pk_bf16_f32 v59, v66, v59
	v_cvt_pk_bf16_f32 v60, v64, v65
	v_cvt_pk_bf16_f32 v61, v62, v63
	global_store_dwordx4 v[120:121], v[58:61], off offset:256
	v_pk_fma_f32 v[54:55], v[54:55], v[182:183], v[134:135] op_sel_hi:[1,0,1]
	v_max_f32_e32 v49, 0, v49
	v_mul_f32_e32 v58, v48, v48
	v_max_f32_e32 v48, 0, v53
	v_max_f32_e32 v50, 0, v50
	v_max_f32_e32 v52, 0, v52
	v_mul_f32_e32 v48, v48, v48
	v_mul_f32_e32 v53, v49, v49
	v_max_f32_e32 v49, 0, v54
	v_mul_f32_e32 v54, v50, v50
	v_max_f32_e32 v50, 0, v55
	v_max_f32_e32 v51, 0, v51
	v_pk_fma_f32 v[40:41], v[40:41], v[180:181], v[128:129] op_sel_hi:[1,0,1]
	v_mul_f32_e32 v52, v52, v52
	v_mul_f32_e32 v49, v49, v49
	v_mul_f32_e32 v50, v50, v50
	v_mul_f32_e32 v51, v51, v51
	v_cvt_pk_bf16_f32 v48, v52, v48
	v_pk_fma_f32 v[44:45], v[44:45], v[180:181], v[132:133] op_sel_hi:[1,0,1]
	v_pk_fma_f32 v[42:43], v[42:43], v[180:181], v[130:131] op_sel_hi:[1,0,1]
	v_max_f32_e32 v40, 0, v40
	v_cvt_pk_bf16_f32 v49, v49, v50
	v_cvt_pk_bf16_f32 v50, v58, v53
	v_cvt_pk_bf16_f32 v51, v54, v51
	global_store_dwordx4 v[112:113], v[48:51], off offset:256
	v_pk_fma_f32 v[46:47], v[46:47], v[180:181], v[134:135] op_sel_hi:[1,0,1]
	v_max_f32_e32 v41, 0, v41
	v_mul_f32_e32 v48, v40, v40
	v_max_f32_e32 v40, 0, v45
	v_max_f32_e32 v42, 0, v42
	v_max_f32_e32 v44, 0, v44
	v_mul_f32_e32 v40, v40, v40
	v_mul_f32_e32 v45, v41, v41
	v_max_f32_e32 v41, 0, v46
	v_mul_f32_e32 v46, v42, v42
	v_max_f32_e32 v42, 0, v47
	v_max_f32_e32 v43, 0, v43
	v_pk_fma_f32 v[32:33], v[32:33], v[178:179], v[128:129] op_sel_hi:[1,0,1]
	v_mul_f32_e32 v44, v44, v44
	v_mul_f32_e32 v41, v41, v41
	v_mul_f32_e32 v42, v42, v42
	v_mul_f32_e32 v43, v43, v43
	v_cvt_pk_bf16_f32 v40, v44, v40
	v_pk_fma_f32 v[36:37], v[36:37], v[178:179], v[132:133] op_sel_hi:[1,0,1]
	v_pk_fma_f32 v[34:35], v[34:35], v[178:179], v[130:131] op_sel_hi:[1,0,1]
	v_max_f32_e32 v32, 0, v32
	v_cvt_pk_bf16_f32 v41, v41, v42
	v_cvt_pk_bf16_f32 v42, v48, v45
	v_cvt_pk_bf16_f32 v43, v46, v43
	global_store_dwordx4 v[104:105], v[40:43], off offset:256
	v_pk_fma_f32 v[38:39], v[38:39], v[178:179], v[134:135] op_sel_hi:[1,0,1]
	v_max_f32_e32 v33, 0, v33
	v_mul_f32_e32 v40, v32, v32
	v_max_f32_e32 v32, 0, v37
	v_max_f32_e32 v34, 0, v34
	v_max_f32_e32 v36, 0, v36
	v_mul_f32_e32 v32, v32, v32
	v_mul_f32_e32 v37, v33, v33
	v_max_f32_e32 v33, 0, v38
	v_mul_f32_e32 v38, v34, v34
	v_max_f32_e32 v34, 0, v39
	v_max_f32_e32 v35, 0, v35
	v_pk_fma_f32 v[24:25], v[24:25], v[176:177], v[128:129] op_sel_hi:[1,0,1]
	v_mul_f32_e32 v36, v36, v36
	v_mul_f32_e32 v33, v33, v33
	v_mul_f32_e32 v34, v34, v34
	v_mul_f32_e32 v35, v35, v35
	v_cvt_pk_bf16_f32 v32, v36, v32
	v_pk_fma_f32 v[28:29], v[28:29], v[176:177], v[132:133] op_sel_hi:[1,0,1]
	v_pk_fma_f32 v[26:27], v[26:27], v[176:177], v[130:131] op_sel_hi:[1,0,1]
	v_max_f32_e32 v24, 0, v24
	v_cvt_pk_bf16_f32 v33, v33, v34
	v_cvt_pk_bf16_f32 v34, v40, v37
	v_cvt_pk_bf16_f32 v35, v38, v35
	global_store_dwordx4 v[96:97], v[32:35], off offset:256
	v_pk_fma_f32 v[30:31], v[30:31], v[176:177], v[134:135] op_sel_hi:[1,0,1]
	v_max_f32_e32 v25, 0, v25
	v_mul_f32_e32 v32, v24, v24
	v_max_f32_e32 v24, 0, v29
	v_max_f32_e32 v26, 0, v26
	s_mov_b64 s[8:9], 0x100000
	v_max_f32_e32 v28, 0, v28
	v_mul_f32_e32 v24, v24, v24
	v_mul_f32_e32 v29, v25, v25
	v_max_f32_e32 v25, 0, v30
	v_mul_f32_e32 v30, v26, v26
	v_max_f32_e32 v26, 0, v31
	v_max_f32_e32 v27, 0, v27
	v_pk_fma_f32 v[16:17], v[16:17], v[174:175], v[128:129] op_sel_hi:[1,0,1]
	v_lshl_add_u64 v[88:89], v[120:121], 0, s[8:9]
	v_mul_f32_e32 v28, v28, v28
	v_mul_f32_e32 v25, v25, v25
	v_mul_f32_e32 v26, v26, v26
	v_mul_f32_e32 v27, v27, v27
	v_cvt_pk_bf16_f32 v24, v28, v24
	v_pk_fma_f32 v[20:21], v[20:21], v[174:175], v[132:133] op_sel_hi:[1,0,1]
	v_pk_fma_f32 v[18:19], v[18:19], v[174:175], v[130:131] op_sel_hi:[1,0,1]
	v_max_f32_e32 v16, 0, v16
	v_cvt_pk_bf16_f32 v25, v25, v26
	v_cvt_pk_bf16_f32 v26, v32, v29
	v_cvt_pk_bf16_f32 v27, v30, v27
	global_store_dwordx4 v[88:89], v[24:27], off offset:256
	v_pk_fma_f32 v[22:23], v[22:23], v[174:175], v[134:135] op_sel_hi:[1,0,1]
	v_max_f32_e32 v17, 0, v17
	v_mul_f32_e32 v24, v16, v16
	v_max_f32_e32 v16, 0, v21
	v_max_f32_e32 v18, 0, v18
	s_mov_b64 s[8:9], 0x120000
	v_max_f32_e32 v20, 0, v20
	v_mul_f32_e32 v16, v16, v16
	v_mul_f32_e32 v21, v17, v17
	v_max_f32_e32 v17, 0, v22
	v_mul_f32_e32 v22, v18, v18
	v_max_f32_e32 v18, 0, v23
	v_max_f32_e32 v19, 0, v19
	v_pk_fma_f32 v[8:9], v[8:9], v[172:173], v[128:129] op_sel_hi:[1,0,1]
	v_lshl_add_u64 v[80:81], v[120:121], 0, s[8:9]
	v_mul_f32_e32 v20, v20, v20
	v_mul_f32_e32 v17, v17, v17
	v_mul_f32_e32 v18, v18, v18
	v_mul_f32_e32 v19, v19, v19
	v_cvt_pk_bf16_f32 v16, v20, v16
	v_pk_fma_f32 v[12:13], v[12:13], v[172:173], v[132:133] op_sel_hi:[1,0,1]
	v_pk_fma_f32 v[10:11], v[10:11], v[172:173], v[130:131] op_sel_hi:[1,0,1]
	v_max_f32_e32 v8, 0, v8
	v_cvt_pk_bf16_f32 v17, v17, v18
	v_cvt_pk_bf16_f32 v18, v24, v21
	v_cvt_pk_bf16_f32 v19, v22, v19
	global_store_dwordx4 v[80:81], v[16:19], off offset:256
	v_pk_fma_f32 v[14:15], v[14:15], v[172:173], v[134:135] op_sel_hi:[1,0,1]
	v_max_f32_e32 v9, 0, v9
	v_mul_f32_e32 v16, v8, v8
	v_max_f32_e32 v8, 0, v13
	v_max_f32_e32 v10, 0, v10
	s_mov_b64 s[8:9], 0x140000
	v_max_f32_e32 v12, 0, v12
	v_mul_f32_e32 v8, v8, v8
	v_mul_f32_e32 v13, v9, v9
	v_max_f32_e32 v9, 0, v14
	v_mul_f32_e32 v14, v10, v10
	v_max_f32_e32 v10, 0, v15
	v_max_f32_e32 v11, 0, v11
	v_pk_fma_f32 v[2:3], v[2:3], v[158:159], v[130:131] op_sel_hi:[1,0,1]
	v_pk_fma_f32 v[0:1], v[0:1], v[158:159], v[128:129] op_sel_hi:[1,0,1]
	v_lshl_add_u64 v[72:73], v[120:121], 0, s[8:9]
	v_mul_f32_e32 v12, v12, v12
	v_mul_f32_e32 v9, v9, v9
	v_mul_f32_e32 v10, v10, v10
	v_mul_f32_e32 v11, v11, v11
	v_cvt_pk_bf16_f32 v8, v12, v8
	v_pk_fma_f32 v[6:7], v[6:7], v[158:159], v[134:135] op_sel_hi:[1,0,1]
	v_pk_fma_f32 v[4:5], v[4:5], v[158:159], v[132:133] op_sel_hi:[1,0,1]
	v_max_f32_e32 v0, 0, v0
	v_max_f32_e32 v1, 0, v1
	v_max_f32_e32 v2, 0, v2
	s_mov_b64 s[8:9], 0x160000
	v_cvt_pk_bf16_f32 v9, v9, v10
	v_cvt_pk_bf16_f32 v10, v16, v13
	v_cvt_pk_bf16_f32 v11, v14, v11
	global_store_dwordx4 v[72:73], v[8:11], off offset:256
	v_max_f32_e32 v3, 0, v3
	v_lshl_add_u64 v[56:57], v[120:121], 0, s[8:9]
	v_mul_f32_e32 v8, v0, v0
	v_max_f32_e32 v0, 0, v5
	v_mul_f32_e32 v5, v1, v1
	v_max_f32_e32 v1, 0, v6
	v_mul_f32_e32 v6, v2, v2
	v_max_f32_e32 v2, 0, v7
	v_max_f32_e32 v4, 0, v4
	v_mul_f32_e32 v0, v0, v0
	v_mul_f32_e32 v1, v1, v1
	v_mul_f32_e32 v2, v2, v2
	v_mul_f32_e32 v3, v3, v3
	s_and_b64 vcc, exec, s[2:3]
	s_mov_b64 s[8:9], s[58:59]
	v_mul_f32_e32 v4, v4, v4
	v_cvt_pk_bf16_f32 v0, v4, v0
	v_cvt_pk_bf16_f32 v1, v1, v2
	v_cvt_pk_bf16_f32 v2, v8, v5
	v_cvt_pk_bf16_f32 v3, v6, v3
	global_store_dwordx4 v[56:57], v[0:3], off offset:256
	s_cbranch_vccz .LBB0_123
	s_waitcnt vmcnt(0)
	s_mov_b32 s90, s62
	s_cmpk_gt_u32 s36, 0xff
	s_cbranch_scc1 .LBB0_134
	s_barrier

.LBB0_158:
	s_lshr_b32 s7, s10, 5
	s_mul_i32 s8, s7, 0x1800
	s_ashr_i32 s9, s8, 31
	s_lshl_b64 s[8:9], s[8:9], 2
	v_readlane_b32 s7, v250, 22
	s_add_u32 s12, s7, s8
	v_readlane_b32 s7, v250, 23
	s_addc_u32 s13, s7, s9
	v_lshlrev_b64 v[164:165], 2, v[208:209]
	v_readlane_b32 s7, v250, 24
	v_lshl_add_u64 v[224:225], s[12:13], 0, v[164:165]
	v_readlane_b32 s12, v250, 20
	s_add_u32 s8, s7, s8
	v_readlane_b32 s7, v250, 25
	v_readlane_b32 s13, v250, 21
	s_addc_u32 s9, s7, s9
	v_lshl_add_u64 v[210:211], s[8:9], 0, v[164:165]
	v_lshl_add_u64 v[166:167], s[12:13], 0, v[164:165]
	global_load_dwordx4 v[132:135], v[224:225], off offset:16
	global_load_dwordx4 v[136:139], v[224:225], off
	global_load_dwordx4 v[148:151], v[166:167], off offset:16
	global_load_dwordx4 v[200:203], v[166:167], off
	global_load_dwordx4 v[212:215], v[210:211], off offset:16
	global_load_dwordx4 v[226:229], v[210:211], off
	v_or_b32_e32 v220, 16, v218
	v_ashrrev_i32_e32 v221, 31, v220
	v_readlane_b32 s12, v249, 12
	v_readlane_b32 s13, v249, 13
	v_or_b32_e32 v244, 32, v218
	v_ashrrev_i32_e32 v245, 31, v244
	v_or_b32_e32 v246, 48, v218
	v_ashrrev_i32_e32 v247, 31, v246
	v_lshlrev_b64 v[216:217], 10, v[196:197]
	v_lshlrev_b64 v[218:219], 10, v[218:219]
	s_and_b64 vcc, exec, s[0:1]
	v_readlane_b32 s14, v249, 14
	v_readlane_b32 s15, v249, 15
	v_readlane_b32 s16, v249, 16
	v_readlane_b32 s17, v249, 17
	v_readlane_b32 s18, v249, 18
	v_readlane_b32 s19, v249, 19
	s_waitcnt vmcnt(0)
	v_pk_add_f32 v[166:167], v[226:227], 1.0 op_sel_hi:[1,0]
	s_nop 0
	v_pk_mul_f32 v[238:239], v[200:201], v[166:167]
	v_pk_add_f32 v[166:167], v[212:213], 1.0 op_sel_hi:[1,0]
	v_pk_add_f32 v[164:165], v[228:229], 1.0 op_sel_hi:[1,0]
	v_pk_mul_f32 v[242:243], v[148:149], v[166:167]
	v_lshlrev_b64 v[148:149], 11, v[220:221]
	v_lshl_add_u64 v[148:149], s[12:13], 0, v[148:149]
	v_lshlrev_b64 v[200:201], 1, v[208:209]
	v_pk_mul_f32 v[236:237], v[202:203], v[164:165]
	v_pk_add_f32 v[164:165], v[214:215], 1.0 op_sel_hi:[1,0]
	v_lshl_add_u64 v[190:191], v[148:149], 0, v[200:201]
	v_lshlrev_b32_e32 v166, 16, v156
	v_and_b32_e32 v167, 0xffff0000, v156
	v_lshlrev_b32_e32 v156, 16, v157
	v_and_b32_e32 v157, 0xffff0000, v157
	v_lshlrev_b32_e32 v202, 16, v158
	v_and_b32_e32 v203, 0xffff0000, v158
	v_lshlrev_b32_e32 v158, 16, v159
	v_and_b32_e32 v159, 0xffff0000, v159
	v_pk_mul_f32 v[240:241], v[150:151], v[164:165]
	global_load_dwordx4 v[148:151], v[190:191], off
	v_lshlrev_b64 v[212:213], 10, v[182:183]
	v_pk_fma_f32 v[230:231], v[126:127], v[138:139], v[156:157]
	v_pk_fma_f32 v[234:235], v[124:125], v[136:137], v[166:167]
	v_pk_fma_f32 v[228:229], v[122:123], v[134:135], v[158:159]
	v_pk_fma_f32 v[232:233], v[120:121], v[132:133], v[202:203]
	v_cvt_pk_bf16_f32 v120, v234, v235
	v_cvt_pk_bf16_f32 v121, v230, v231
	v_lshl_add_u64 v[164:165], v[212:213], 0, v[208:209]
	v_cvt_pk_bf16_f32 v122, v232, v233
	v_cvt_pk_bf16_f32 v123, v228, v229
	global_store_dwordx4 v[204:205], v[120:123], off
	v_pk_mul_f32 v[124:125], v[228:229], v[240:241]
	v_pk_mul_f32 v[126:127], v[232:233], v[242:243]
	v_pk_mul_f32 v[122:123], v[230:231], v[236:237]
	v_pk_mul_f32 v[120:121], v[234:235], v[238:239]
	v_lshlrev_b64 v[226:227], 10, v[198:199]
	v_cvt_pk_bf16_f32 v120, v120, v121
	v_cvt_pk_bf16_f32 v121, v122, v123
	v_cvt_pk_bf16_f32 v122, v126, v127
	v_cvt_pk_bf16_f32 v123, v124, v125
	v_lshl_add_u64 v[124:125], v[164:165], 1, s[28:29]
	global_store_dwordx4 v[124:125], v[120:123], off
	v_lshlrev_b32_e32 v126, 16, v152
	v_and_b32_e32 v127, 0xffff0000, v152
	v_lshlrev_b64 v[120:121], 11, v[244:245]
	v_lshl_add_u64 v[120:121], s[12:13], 0, v[120:121]
	v_lshl_add_u64 v[156:157], v[120:121], 0, v[200:201]
	v_lshlrev_b32_e32 v124, 16, v153
	v_and_b32_e32 v125, 0xffff0000, v153
	v_lshlrev_b32_e32 v152, 16, v154
	v_and_b32_e32 v153, 0xffff0000, v154
	v_lshlrev_b32_e32 v154, 16, v155
	v_and_b32_e32 v155, 0xffff0000, v155
	global_load_dwordx4 v[120:123], v[156:157], off
	v_pk_fma_f32 v[124:125], v[118:119], v[138:139], v[124:125]
	v_pk_fma_f32 v[126:127], v[116:117], v[136:137], v[126:127]
	v_pk_fma_f32 v[116:117], v[114:115], v[134:135], v[154:155]
	v_pk_fma_f32 v[118:119], v[112:113], v[132:133], v[152:153]
	v_cvt_pk_bf16_f32 v112, v126, v127
	v_cvt_pk_bf16_f32 v113, v124, v125
	v_lshl_add_u64 v[158:159], v[226:227], 0, v[208:209]
	v_cvt_pk_bf16_f32 v114, v118, v119
	v_cvt_pk_bf16_f32 v115, v116, v117
	global_store_dwordx4 v[192:193], v[112:115], off
	v_pk_mul_f32 v[152:153], v[116:117], v[240:241]
	v_pk_mul_f32 v[154:155], v[118:119], v[242:243]
	v_pk_mul_f32 v[114:115], v[124:125], v[236:237]
	v_pk_mul_f32 v[112:113], v[126:127], v[238:239]
	v_lshlrev_b32_e32 v164, 16, v146
	v_cvt_pk_bf16_f32 v112, v112, v113
	v_cvt_pk_bf16_f32 v113, v114, v115
	v_cvt_pk_bf16_f32 v114, v154, v155
	v_cvt_pk_bf16_f32 v115, v152, v153
	v_lshl_add_u64 v[152:153], v[158:159], 1, s[28:29]
	global_store_dwordx4 v[152:153], v[112:115], off
	v_lshlrev_b32_e32 v154, 16, v144
	v_and_b32_e32 v155, 0xffff0000, v144
	v_lshlrev_b64 v[112:113], 11, v[246:247]
	v_lshl_add_u64 v[112:113], s[12:13], 0, v[112:113]
	v_lshl_add_u64 v[206:207], v[112:113], 0, v[200:201]
	global_load_dwordx4 v[112:115], v[206:207], off
	v_lshlrev_b32_e32 v144, 16, v145
	v_and_b32_e32 v145, 0xffff0000, v145
	v_and_b32_e32 v165, 0xffff0000, v146
	v_lshlrev_b32_e32 v146, 16, v147
	v_and_b32_e32 v147, 0xffff0000, v147
	v_lshlrev_b64 v[214:215], 10, v[194:195]
	v_pk_fma_f32 v[158:159], v[110:111], v[138:139], v[144:145]
	v_pk_fma_f32 v[200:201], v[108:109], v[136:137], v[154:155]
	v_pk_fma_f32 v[194:195], v[106:107], v[134:135], v[146:147]
	v_pk_fma_f32 v[202:203], v[104:105], v[132:133], v[164:165]
	v_cvt_pk_bf16_f32 v104, v200, v201
	v_cvt_pk_bf16_f32 v105, v158, v159
	v_lshl_add_u64 v[152:153], v[214:215], 0, v[208:209]
	v_cvt_pk_bf16_f32 v106, v202, v203
	v_cvt_pk_bf16_f32 v107, v194, v195
	global_store_dwordx4 v[188:189], v[104:107], off
	v_pk_mul_f32 v[108:109], v[194:195], v[240:241]
	v_pk_mul_f32 v[110:111], v[202:203], v[242:243]
	v_pk_mul_f32 v[106:107], v[158:159], v[236:237]
	v_pk_mul_f32 v[104:105], v[200:201], v[238:239]
	v_lshlrev_b64 v[220:221], 10, v[220:221]
	v_cvt_pk_bf16_f32 v104, v104, v105
	v_cvt_pk_bf16_f32 v105, v106, v107
	v_cvt_pk_bf16_f32 v106, v110, v111
	v_cvt_pk_bf16_f32 v107, v108, v109
	v_lshl_add_u64 v[108:109], v[152:153], 1, s[28:29]
	global_store_dwordx4 v[108:109], v[104:107], off
	v_lshlrev_b32_e32 v108, 16, v141
	v_and_b32_e32 v109, 0xffff0000, v141
	v_lshlrev_b32_e32 v106, 16, v140
	v_and_b32_e32 v107, 0xffff0000, v140
	v_lshlrev_b32_e32 v110, 16, v142
	v_and_b32_e32 v111, 0xffff0000, v142
	v_lshlrev_b32_e32 v140, 16, v143
	v_and_b32_e32 v141, 0xffff0000, v143
	v_pk_fma_f32 v[144:145], v[102:103], v[138:139], v[108:109]
	v_pk_fma_f32 v[196:197], v[100:101], v[136:137], v[106:107]
	v_pk_fma_f32 v[146:147], v[98:99], v[134:135], v[140:141]
	v_pk_fma_f32 v[198:199], v[96:97], v[132:133], v[110:111]
	v_cvt_pk_bf16_f32 v96, v196, v197
	v_cvt_pk_bf16_f32 v97, v144, v145
	v_lshl_add_u64 v[104:105], v[216:217], 0, v[208:209]
	v_cvt_pk_bf16_f32 v98, v198, v199
	v_cvt_pk_bf16_f32 v99, v146, v147
	global_store_dwordx4 v[186:187], v[96:99], off
	v_pk_mul_f32 v[100:101], v[146:147], v[240:241]
	v_pk_mul_f32 v[102:103], v[198:199], v[242:243]
	v_pk_mul_f32 v[98:99], v[144:145], v[236:237]
	v_pk_mul_f32 v[96:97], v[196:197], v[238:239]
	s_nop 0
	v_cvt_pk_bf16_f32 v96, v96, v97
	v_cvt_pk_bf16_f32 v97, v98, v99
	v_cvt_pk_bf16_f32 v98, v102, v103
	v_cvt_pk_bf16_f32 v99, v100, v101
	v_lshl_add_u64 v[100:101], v[104:105], 1, s[28:29]
	global_store_dwordx4 v[100:101], v[96:99], off
	v_lshlrev_b32_e32 v100, 16, v129
	v_and_b32_e32 v101, 0xffff0000, v129
	v_lshlrev_b32_e32 v98, 16, v128
	v_and_b32_e32 v99, 0xffff0000, v128
	v_lshlrev_b32_e32 v102, 16, v130
	v_and_b32_e32 v103, 0xffff0000, v130
	v_lshlrev_b32_e32 v104, 16, v131
	v_and_b32_e32 v105, 0xffff0000, v131
	v_pk_fma_f32 v[128:129], v[94:95], v[138:139], v[100:101]
	v_pk_fma_f32 v[152:153], v[92:93], v[136:137], v[98:99]
	v_pk_fma_f32 v[130:131], v[90:91], v[134:135], v[104:105]
	v_pk_fma_f32 v[154:155], v[88:89], v[132:133], v[102:103]
	v_cvt_pk_bf16_f32 v88, v152, v153
	v_cvt_pk_bf16_f32 v89, v128, v129
	v_lshl_add_u64 v[96:97], v[218:219], 0, v[208:209]
	v_cvt_pk_bf16_f32 v90, v154, v155
	v_cvt_pk_bf16_f32 v91, v130, v131
	global_store_dwordx4 v[184:185], v[88:91], off
	v_pk_mul_f32 v[92:93], v[130:131], v[240:241]
	v_pk_mul_f32 v[94:95], v[154:155], v[242:243]
	v_pk_mul_f32 v[90:91], v[128:129], v[236:237]
	v_pk_mul_f32 v[88:89], v[152:153], v[238:239]
	s_nop 0
	v_cvt_pk_bf16_f32 v88, v88, v89
	v_cvt_pk_bf16_f32 v89, v90, v91
	v_cvt_pk_bf16_f32 v90, v94, v95
	v_cvt_pk_bf16_f32 v91, v92, v93
	v_lshl_add_u64 v[92:93], v[96:97], 1, s[28:29]
	global_store_dwordx4 v[92:93], v[88:91], off
	s_waitcnt vmcnt(6)
	v_lshlrev_b32_e32 v92, 16, v149
	v_and_b32_e32 v93, 0xffff0000, v149
	v_lshlrev_b32_e32 v90, 16, v148
	v_and_b32_e32 v91, 0xffff0000, v148
	v_lshlrev_b32_e32 v94, 16, v150
	v_and_b32_e32 v95, 0xffff0000, v150
	v_lshlrev_b32_e32 v96, 16, v151
	v_and_b32_e32 v97, 0xffff0000, v151
	v_pk_fma_f32 v[108:109], v[86:87], v[138:139], v[92:93]
	v_pk_fma_f32 v[140:141], v[84:85], v[136:137], v[90:91]
	v_pk_fma_f32 v[110:111], v[82:83], v[134:135], v[96:97]
	v_pk_fma_f32 v[142:143], v[80:81], v[132:133], v[94:95]
	v_cvt_pk_bf16_f32 v80, v140, v141
	v_cvt_pk_bf16_f32 v81, v108, v109
	v_lshl_add_u64 v[88:89], v[220:221], 0, v[208:209]
	v_cvt_pk_bf16_f32 v82, v142, v143
	v_cvt_pk_bf16_f32 v83, v110, v111
	global_store_dwordx4 v[190:191], v[80:83], off
	v_pk_mul_f32 v[84:85], v[240:241], v[110:111]
	v_pk_mul_f32 v[86:87], v[242:243], v[142:143]
	v_pk_mul_f32 v[82:83], v[236:237], v[108:109]
	v_pk_mul_f32 v[80:81], v[238:239], v[140:141]
	v_lshlrev_b64 v[148:149], 10, v[244:245]
	v_cvt_pk_bf16_f32 v80, v80, v81
	v_cvt_pk_bf16_f32 v81, v82, v83
	v_cvt_pk_bf16_f32 v82, v86, v87
	v_cvt_pk_bf16_f32 v83, v84, v85
	v_lshl_add_u64 v[84:85], v[88:89], 1, s[28:29]
	global_store_dwordx4 v[84:85], v[80:83], off
	v_lshlrev_b32_e32 v84, 16, v121
	v_and_b32_e32 v85, 0xffff0000, v121
	v_lshlrev_b32_e32 v82, 16, v120
	v_and_b32_e32 v83, 0xffff0000, v120
	v_lshlrev_b32_e32 v86, 16, v122
	v_and_b32_e32 v87, 0xffff0000, v122
	v_lshlrev_b32_e32 v88, 16, v123
	v_and_b32_e32 v89, 0xffff0000, v123
	v_pk_fma_f32 v[100:101], v[78:79], v[138:139], v[84:85]
	v_pk_fma_f32 v[120:121], v[76:77], v[136:137], v[82:83]
	v_pk_fma_f32 v[102:103], v[74:75], v[134:135], v[88:89]
	v_pk_fma_f32 v[122:123], v[72:73], v[132:133], v[86:87]
	v_cvt_pk_bf16_f32 v72, v120, v121
	v_cvt_pk_bf16_f32 v73, v100, v101
	v_lshl_add_u64 v[80:81], v[148:149], 0, v[208:209]
	v_cvt_pk_bf16_f32 v74, v122, v123
	v_cvt_pk_bf16_f32 v75, v102, v103
	global_store_dwordx4 v[156:157], v[72:75], off
	v_pk_mul_f32 v[76:77], v[240:241], v[102:103]
	v_pk_mul_f32 v[78:79], v[242:243], v[122:123]
	v_pk_mul_f32 v[74:75], v[236:237], v[100:101]
	v_pk_mul_f32 v[72:73], v[238:239], v[120:121]
	v_lshlrev_b64 v[150:151], 10, v[246:247]
	v_cvt_pk_bf16_f32 v72, v72, v73
	v_cvt_pk_bf16_f32 v73, v74, v75
	v_cvt_pk_bf16_f32 v74, v78, v79
	v_cvt_pk_bf16_f32 v75, v76, v77
	v_lshl_add_u64 v[76:77], v[80:81], 1, s[28:29]
	global_store_dwordx4 v[76:77], v[72:75], off
	v_lshlrev_b32_e32 v76, 16, v113
	v_and_b32_e32 v77, 0xffff0000, v113
	v_lshlrev_b32_e32 v74, 16, v112
	v_and_b32_e32 v75, 0xffff0000, v112
	v_lshlrev_b32_e32 v78, 16, v114
	v_and_b32_e32 v79, 0xffff0000, v114
	v_lshlrev_b32_e32 v80, 16, v115
	v_and_b32_e32 v81, 0xffff0000, v115
	v_pk_fma_f32 v[96:97], v[70:71], v[138:139], v[76:77]
	v_pk_fma_f32 v[104:105], v[68:69], v[136:137], v[74:75]
	v_pk_fma_f32 v[98:99], v[66:67], v[134:135], v[80:81]
	v_pk_fma_f32 v[106:107], v[64:65], v[132:133], v[78:79]
	v_cvt_pk_bf16_f32 v64, v104, v105
	v_cvt_pk_bf16_f32 v65, v96, v97
	v_lshl_add_u64 v[72:73], v[150:151], 0, v[208:209]
	v_cvt_pk_bf16_f32 v66, v106, v107
	v_cvt_pk_bf16_f32 v67, v98, v99
	global_store_dwordx4 v[206:207], v[64:67], off
	v_pk_mul_f32 v[68:69], v[240:241], v[98:99]
	v_pk_mul_f32 v[70:71], v[242:243], v[106:107]
	v_pk_mul_f32 v[66:67], v[236:237], v[96:97]
	v_pk_mul_f32 v[64:65], v[238:239], v[104:105]
	s_nop 0
	v_cvt_pk_bf16_f32 v64, v64, v65
	v_cvt_pk_bf16_f32 v65, v66, v67
	v_cvt_pk_bf16_f32 v66, v70, v71
	v_cvt_pk_bf16_f32 v67, v68, v69
	v_lshl_add_u64 v[68:69], v[72:73], 1, s[28:29]
	global_store_dwordx4 v[68:69], v[64:67], off
	global_load_dwordx4 v[92:95], v[204:205], off offset:256
	global_load_dwordx4 v[88:91], v[192:193], off offset:256
	global_load_dwordx4 v[80:83], v[188:189], off offset:256
	global_load_dwordx4 v[76:79], v[186:187], off offset:256
	s_nop 0
	global_load_dwordx4 v[68:71], v[184:185], off offset:256
	s_cbranch_vccnz .LBB0_160
	global_load_dwordx4 v[64:67], v[222:223], off offset:512
	global_load_dwordx4 v[72:75], v[222:223], off offset:528
	s_waitcnt vmcnt(0)
	v_pk_add_f32 v[62:63], v[62:63], v[66:67]
	v_pk_add_f32 v[60:61], v[60:61], v[64:65]
	v_pk_add_f32 v[58:59], v[58:59], v[74:75]
	v_pk_add_f32 v[56:57], v[56:57], v[72:73]
	v_pk_add_f32 v[54:55], v[54:55], v[66:67]
	v_pk_add_f32 v[52:53], v[52:53], v[64:65]
	v_pk_add_f32 v[50:51], v[50:51], v[74:75]
	v_pk_add_f32 v[48:49], v[48:49], v[72:73]
	v_pk_add_f32 v[46:47], v[46:47], v[66:67]
	v_pk_add_f32 v[44:45], v[44:45], v[64:65]
	v_pk_add_f32 v[42:43], v[42:43], v[74:75]
	v_pk_add_f32 v[40:41], v[40:41], v[72:73]
	v_pk_add_f32 v[38:39], v[38:39], v[66:67]
	v_pk_add_f32 v[36:37], v[36:37], v[64:65]
	v_pk_add_f32 v[34:35], v[34:35], v[74:75]
	v_pk_add_f32 v[32:33], v[32:33], v[72:73]
	v_pk_add_f32 v[30:31], v[30:31], v[66:67]
	v_pk_add_f32 v[28:29], v[28:29], v[64:65]
	v_pk_add_f32 v[26:27], v[26:27], v[74:75]
	v_pk_add_f32 v[24:25], v[24:25], v[72:73]
	v_pk_add_f32 v[22:23], v[22:23], v[66:67]
	v_pk_add_f32 v[20:21], v[20:21], v[64:65]
	v_pk_add_f32 v[18:19], v[18:19], v[74:75]
	v_pk_add_f32 v[16:17], v[16:17], v[72:73]
	v_pk_add_f32 v[14:15], v[14:15], v[66:67]
	v_pk_add_f32 v[12:13], v[12:13], v[64:65]
	v_pk_add_f32 v[10:11], v[10:11], v[74:75]
	v_pk_add_f32 v[8:9], v[8:9], v[72:73]
	v_pk_add_f32 v[6:7], v[6:7], v[66:67]
	v_pk_add_f32 v[4:5], v[4:5], v[64:65]
	v_pk_add_f32 v[2:3], v[2:3], v[74:75]
	v_pk_add_f32 v[0:1], v[0:1], v[72:73]
.LBB0_160:
	v_mul_f32_e32 v64, v235, v235
	v_mul_f32_e32 v65, v231, v231
	v_fmac_f32_e32 v64, v234, v234
	v_fmac_f32_e32 v65, v230, v230
	v_add_f32_e32 v64, v64, v65
	v_mul_f32_e32 v65, v233, v233
	v_fmac_f32_e32 v65, v232, v232
	v_or_b32_e32 v112, 0x80, v208
	v_readlane_b32 s0, v250, 20
	v_add_f32_e32 v64, v65, v64
	v_mul_f32_e32 v65, v229, v229
	v_ashrrev_i32_e32 v113, 31, v112
	v_readlane_b32 s1, v250, 21
	v_fmac_f32_e32 v65, v228, v228
	v_add_f32_e32 v162, v65, v64
	v_lshl_add_u64 v[114:115], v[112:113], 2, s[0:1]
	global_load_dwordx4 v[64:67], v[224:225], off offset:528
	global_load_dwordx4 v[72:75], v[224:225], off offset:512
	global_load_dwordx4 v[84:87], v[114:115], off offset:16
	global_load_dwordx4 v[132:135], v[114:115], off
	global_load_dwordx4 v[136:139], v[210:211], off offset:528
	s_nop 0
	global_load_dwordx4 v[208:211], v[210:211], off offset:512
	s_waitcnt vmcnt(0)
	v_lshlrev_b32_e32 v166, 16, v94
	v_and_b32_e32 v167, 0xffff0000, v94
	v_lshlrev_b32_e32 v94, 16, v95
	v_and_b32_e32 v95, 0xffff0000, v95
	v_readlane_b32 s0, v250, 14
	v_readlane_b32 s1, v250, 15
	v_pk_add_f32 v[136:137], v[136:137], 1.0 op_sel_hi:[1,0]
	v_pk_add_f32 v[114:115], v[210:211], 1.0 op_sel_hi:[1,0]
	v_pk_add_f32 v[164:165], v[208:209], 1.0 op_sel_hi:[1,0]
	v_pk_mul_f32 v[114:115], v[134:135], v[114:115]
	v_pk_mul_f32 v[132:133], v[132:133], v[164:165]
	v_pk_add_f32 v[134:135], v[138:139], 1.0 op_sel_hi:[1,0]
	v_lshlrev_b32_e32 v164, 16, v92
	v_and_b32_e32 v165, 0xffff0000, v92
	v_lshlrev_b32_e32 v92, 16, v93
	v_and_b32_e32 v93, 0xffff0000, v93
	v_pk_mul_f32 v[134:135], v[86:87], v[134:135]
	v_pk_mul_f32 v[136:137], v[84:85], v[136:137]
	global_load_dwordx4 v[84:87], v[190:191], off offset:256
	v_pk_fma_f32 v[62:63], v[62:63], v[74:75], v[92:93]
	v_pk_fma_f32 v[60:61], v[60:61], v[72:73], v[164:165]
	v_pk_fma_f32 v[164:165], v[56:57], v[64:65], v[166:167]
	v_cvt_pk_bf16_f32 v56, v60, v61
	v_cvt_pk_bf16_f32 v57, v62, v63
	v_pk_fma_f32 v[92:93], v[58:59], v[66:67], v[94:95]
	v_cvt_pk_bf16_f32 v58, v164, v165
	v_lshl_add_u64 v[138:139], v[212:213], 0, v[112:113]
	v_cvt_pk_bf16_f32 v59, v92, v93
	global_store_dwordx4 v[204:205], v[56:59], off offset:256
	s_nop 1
	v_mul_f32_e32 v56, v61, v61
	v_mul_f32_e32 v57, v63, v63
	v_fmac_f32_e32 v56, v60, v60
	v_fmac_f32_e32 v57, v62, v62
	v_add_f32_e32 v56, v56, v57
	v_mul_f32_e32 v57, v165, v165
	v_fmac_f32_e32 v57, v164, v164
	v_add_f32_e32 v56, v57, v56
	v_mul_f32_e32 v57, v93, v93
	v_fmac_f32_e32 v57, v92, v92
	v_add_f32_e32 v56, v57, v56
	v_add_f32_e32 v94, v162, v56
	v_pk_mul_f32 v[58:59], v[62:63], v[114:115]
	v_pk_mul_f32 v[56:57], v[60:61], v[132:133]
	v_pk_mul_f32 v[60:61], v[92:93], v[134:135]
	v_pk_mul_f32 v[62:63], v[164:165], v[136:137]
	v_cvt_pk_bf16_f32 v56, v56, v57
	v_cvt_pk_bf16_f32 v57, v58, v59
	v_lshl_add_u64 v[92:93], v[226:227], 0, v[112:113]
	v_cvt_pk_bf16_f32 v58, v62, v63
	v_cvt_pk_bf16_f32 v59, v60, v61
	v_lshl_add_u64 v[60:61], v[138:139], 1, s[28:29]
	global_store_dwordx4 v[60:61], v[56:59], off
	v_lshlrev_b32_e32 v60, 16, v88
	v_and_b32_e32 v61, 0xffff0000, v88
	v_lshlrev_b32_e32 v62, 16, v89
	v_and_b32_e32 v63, 0xffff0000, v89
	v_lshlrev_b32_e32 v88, 16, v90
	v_and_b32_e32 v89, 0xffff0000, v90
	v_lshlrev_b32_e32 v90, 16, v91
	v_and_b32_e32 v91, 0xffff0000, v91
	global_load_dwordx4 v[56:59], v[156:157], off offset:256
	v_pk_fma_f32 v[54:55], v[54:55], v[74:75], v[62:63]
	v_pk_fma_f32 v[60:61], v[52:53], v[72:73], v[60:61]
	v_pk_fma_f32 v[52:53], v[50:51], v[66:67], v[90:91]
	v_pk_fma_f32 v[62:63], v[48:49], v[64:65], v[88:89]
	v_cvt_pk_bf16_f32 v48, v60, v61
	v_cvt_pk_bf16_f32 v49, v54, v55
	v_pk_mul_f32 v[88:89], v[52:53], v[134:135]
	v_cvt_pk_bf16_f32 v50, v62, v63
	v_cvt_pk_bf16_f32 v51, v52, v53
	global_store_dwordx4 v[192:193], v[48:51], off offset:256
	v_pk_mul_f32 v[90:91], v[62:63], v[136:137]
	s_nop 0
	v_pk_mul_f32 v[50:51], v[54:55], v[114:115]
	v_pk_mul_f32 v[48:49], v[60:61], v[132:133]
	s_nop 0
	v_cvt_pk_bf16_f32 v48, v48, v49
	v_cvt_pk_bf16_f32 v49, v50, v51
	v_cvt_pk_bf16_f32 v50, v90, v91
	v_cvt_pk_bf16_f32 v51, v88, v89
	v_lshl_add_u64 v[88:89], v[92:93], 1, s[28:29]
	global_store_dwordx4 v[88:89], v[48:51], off
	global_load_dwordx4 v[48:51], v[206:207], off offset:256
	v_lshlrev_b32_e32 v88, 16, v80
	v_and_b32_e32 v89, 0xffff0000, v80
	v_lshlrev_b32_e32 v80, 16, v81
	v_and_b32_e32 v81, 0xffff0000, v81
	v_lshlrev_b32_e32 v90, 16, v82
	v_and_b32_e32 v91, 0xffff0000, v82
	v_lshlrev_b32_e32 v82, 16, v83
	v_and_b32_e32 v83, 0xffff0000, v83
	v_pk_fma_f32 v[46:47], v[46:47], v[74:75], v[80:81]
	v_lshl_add_u64 v[92:93], v[214:215], 0, v[112:113]
	v_pk_fma_f32 v[44:45], v[44:45], v[72:73], v[88:89]
	v_pk_fma_f32 v[42:43], v[42:43], v[66:67], v[82:83]
	v_pk_fma_f32 v[80:81], v[40:41], v[64:65], v[90:91]
	v_cvt_pk_bf16_f32 v88, v44, v45
	v_cvt_pk_bf16_f32 v89, v46, v47
	v_pk_mul_f32 v[40:41], v[46:47], v[114:115]
	v_cvt_pk_bf16_f32 v90, v80, v81
	v_cvt_pk_bf16_f32 v91, v42, v43
	global_store_dwordx4 v[188:189], v[88:91], off offset:256
	v_pk_mul_f32 v[82:83], v[44:45], v[132:133]
	v_pk_mul_f32 v[138:139], v[42:43], v[134:135]
	v_pk_mul_f32 v[90:91], v[80:81], v[136:137]
	v_cvt_pk_bf16_f32 v88, v82, v83
	v_cvt_pk_bf16_f32 v89, v40, v41
	v_lshl_add_u64 v[40:41], v[92:93], 1, s[28:29]
	v_cvt_pk_bf16_f32 v90, v90, v91
	v_cvt_pk_bf16_f32 v91, v138, v139
	global_store_dwordx4 v[40:41], v[88:91], off
	v_lshlrev_b32_e32 v40, 16, v76
	v_and_b32_e32 v41, 0xffff0000, v76
	v_lshlrev_b32_e32 v76, 16, v77
	v_and_b32_e32 v77, 0xffff0000, v77
	v_lshlrev_b32_e32 v88, 16, v78
	v_and_b32_e32 v89, 0xffff0000, v78
	v_lshlrev_b32_e32 v78, 16, v79
	v_and_b32_e32 v79, 0xffff0000, v79
	v_pk_fma_f32 v[38:39], v[38:39], v[74:75], v[76:77]
	v_pk_fma_f32 v[36:37], v[36:37], v[72:73], v[40:41]
	v_pk_fma_f32 v[34:35], v[34:35], v[66:67], v[78:79]
	v_pk_fma_f32 v[40:41], v[32:33], v[64:65], v[88:89]
	v_cvt_pk_bf16_f32 v76, v36, v37
	v_cvt_pk_bf16_f32 v77, v38, v39
	v_lshl_add_u64 v[82:83], v[216:217], 0, v[112:113]
	v_cvt_pk_bf16_f32 v78, v40, v41
	v_cvt_pk_bf16_f32 v79, v34, v35
	global_store_dwordx4 v[186:187], v[76:79], off offset:256
	v_pk_mul_f32 v[32:33], v[38:39], v[114:115]
	v_pk_mul_f32 v[88:89], v[34:35], v[134:135]
	v_pk_mul_f32 v[76:77], v[36:37], v[132:133]
	v_pk_mul_f32 v[78:79], v[40:41], v[136:137]
	v_cvt_pk_bf16_f32 v76, v76, v77
	v_cvt_pk_bf16_f32 v77, v32, v33
	v_lshl_add_u64 v[32:33], v[82:83], 1, s[28:29]
	v_cvt_pk_bf16_f32 v78, v78, v79
	v_cvt_pk_bf16_f32 v79, v88, v89
	global_store_dwordx4 v[32:33], v[76:79], off
	v_lshlrev_b32_e32 v32, 16, v68
	v_and_b32_e32 v33, 0xffff0000, v68
	v_lshlrev_b32_e32 v68, 16, v69
	v_and_b32_e32 v69, 0xffff0000, v69
	v_lshlrev_b32_e32 v78, 16, v70
	v_and_b32_e32 v79, 0xffff0000, v70
	v_lshlrev_b32_e32 v70, 16, v71
	v_and_b32_e32 v71, 0xffff0000, v71
	v_pk_fma_f32 v[30:31], v[30:31], v[74:75], v[68:69]
	v_pk_fma_f32 v[28:29], v[28:29], v[72:73], v[32:33]
	v_pk_fma_f32 v[26:27], v[26:27], v[66:67], v[70:71]
	v_pk_fma_f32 v[32:33], v[24:25], v[64:65], v[78:79]
	v_cvt_pk_bf16_f32 v68, v28, v29
	v_cvt_pk_bf16_f32 v69, v30, v31
	v_lshl_add_u64 v[76:77], v[218:219], 0, v[112:113]
	v_cvt_pk_bf16_f32 v70, v32, v33
	v_cvt_pk_bf16_f32 v71, v26, v27
	global_store_dwordx4 v[184:185], v[68:71], off offset:256
	v_pk_mul_f32 v[24:25], v[30:31], v[114:115]
	v_pk_mul_f32 v[78:79], v[26:27], v[134:135]
	v_pk_mul_f32 v[68:69], v[28:29], v[132:133]
	v_pk_mul_f32 v[70:71], v[32:33], v[136:137]
	v_cvt_pk_bf16_f32 v68, v68, v69
	v_cvt_pk_bf16_f32 v69, v24, v25
	v_lshl_add_u64 v[24:25], v[76:77], 1, s[28:29]
	v_cvt_pk_bf16_f32 v70, v70, v71
	v_cvt_pk_bf16_f32 v71, v78, v79
	global_store_dwordx4 v[24:25], v[68:71], off
	s_waitcnt vmcnt(6)
	v_lshlrev_b32_e32 v76, 16, v86
	v_and_b32_e32 v77, 0xffff0000, v86
	v_lshlrev_b32_e32 v68, 16, v84
	v_and_b32_e32 v69, 0xffff0000, v84
	v_lshlrev_b32_e32 v70, 16, v85
	v_and_b32_e32 v71, 0xffff0000, v85
	v_lshlrev_b32_e32 v78, 16, v87
	v_and_b32_e32 v79, 0xffff0000, v87
	v_pk_fma_f32 v[22:23], v[22:23], v[74:75], v[70:71]
	v_pk_fma_f32 v[20:21], v[20:21], v[72:73], v[68:69]
	v_pk_fma_f32 v[18:19], v[18:19], v[66:67], v[78:79]
	v_pk_fma_f32 v[16:17], v[16:17], v[64:65], v[76:77]
	v_cvt_pk_bf16_f32 v68, v20, v21
	v_cvt_pk_bf16_f32 v69, v22, v23
	v_lshl_add_u64 v[24:25], v[220:221], 0, v[112:113]
	v_cvt_pk_bf16_f32 v70, v16, v17
	v_cvt_pk_bf16_f32 v71, v18, v19
	global_store_dwordx4 v[190:191], v[68:71], off offset:256
	v_pk_mul_f32 v[76:77], v[134:135], v[18:19]
	v_pk_mul_f32 v[78:79], v[136:137], v[16:17]
	v_pk_mul_f32 v[70:71], v[114:115], v[22:23]
	v_pk_mul_f32 v[68:69], v[132:133], v[20:21]
	v_lshl_add_u64 v[24:25], v[24:25], 1, s[28:29]
	v_cvt_pk_bf16_f32 v68, v68, v69
	v_cvt_pk_bf16_f32 v69, v70, v71
	v_cvt_pk_bf16_f32 v70, v78, v79
	v_cvt_pk_bf16_f32 v71, v76, v77
	global_store_dwordx4 v[24:25], v[68:71], off
	v_lshl_add_u64 v[24:25], v[148:149], 0, v[112:113]
	v_lshl_add_u64 v[24:25], v[24:25], 1, s[28:29]
	v_lshlrev_b32_e32 v68, 16, v56
	v_and_b32_e32 v69, 0xffff0000, v56
	v_lshlrev_b32_e32 v56, 16, v57
	v_and_b32_e32 v57, 0xffff0000, v57
	v_lshlrev_b32_e32 v70, 16, v58
	v_and_b32_e32 v71, 0xffff0000, v58
	v_lshlrev_b32_e32 v58, 16, v59
	v_and_b32_e32 v59, 0xffff0000, v59
	v_pk_fma_f32 v[14:15], v[14:15], v[74:75], v[56:57]
	v_pk_fma_f32 v[12:13], v[12:13], v[72:73], v[68:69]
	v_pk_fma_f32 v[10:11], v[10:11], v[66:67], v[58:59]
	v_pk_fma_f32 v[8:9], v[8:9], v[64:65], v[70:71]
	v_cvt_pk_bf16_f32 v56, v12, v13
	v_cvt_pk_bf16_f32 v57, v14, v15
	v_pk_mul_f32 v[68:69], v[134:135], v[10:11]
	v_cvt_pk_bf16_f32 v58, v8, v9
	v_cvt_pk_bf16_f32 v59, v10, v11
	global_store_dwordx4 v[156:157], v[56:59], off offset:256
	v_pk_mul_f32 v[70:71], v[136:137], v[8:9]
	s_nop 0
	v_pk_mul_f32 v[58:59], v[114:115], v[14:15]
	v_pk_mul_f32 v[56:57], v[132:133], v[12:13]
	s_nop 0
	v_cvt_pk_bf16_f32 v56, v56, v57
	v_cvt_pk_bf16_f32 v57, v58, v59
	v_cvt_pk_bf16_f32 v58, v70, v71
	v_cvt_pk_bf16_f32 v59, v68, v69
	global_store_dwordx4 v[24:25], v[56:59], off
	v_lshl_add_u64 v[24:25], v[150:151], 0, v[112:113]
	v_lshl_add_u64 v[24:25], v[24:25], 1, s[28:29]
	v_lshlrev_b32_e32 v56, 16, v48
	v_and_b32_e32 v57, 0xffff0000, v48
	v_lshlrev_b32_e32 v48, 16, v49
	v_and_b32_e32 v49, 0xffff0000, v49
	v_lshlrev_b32_e32 v58, 16, v50
	v_and_b32_e32 v59, 0xffff0000, v50
	v_lshlrev_b32_e32 v50, 16, v51
	v_and_b32_e32 v51, 0xffff0000, v51
	v_pk_fma_f32 v[6:7], v[6:7], v[74:75], v[48:49]
	v_pk_fma_f32 v[4:5], v[4:5], v[72:73], v[56:57]
	v_pk_fma_f32 v[2:3], v[2:3], v[66:67], v[50:51]
	v_pk_fma_f32 v[0:1], v[0:1], v[64:65], v[58:59]
	v_cvt_pk_bf16_f32 v48, v4, v5
	v_cvt_pk_bf16_f32 v49, v6, v7
	v_pk_mul_f32 v[56:57], v[134:135], v[2:3]
	v_cvt_pk_bf16_f32 v50, v0, v1
	v_cvt_pk_bf16_f32 v51, v2, v3
	global_store_dwordx4 v[206:207], v[48:51], off offset:256
	v_pk_mul_f32 v[58:59], v[136:137], v[0:1]
	s_nop 0
	v_pk_mul_f32 v[50:51], v[114:115], v[6:7]
	v_pk_mul_f32 v[48:49], v[132:133], v[4:5]
	s_nop 0
	v_cvt_pk_bf16_f32 v48, v48, v49
	v_cvt_pk_bf16_f32 v49, v50, v51
	v_cvt_pk_bf16_f32 v50, v58, v59
	v_cvt_pk_bf16_f32 v51, v56, v57
	global_store_dwordx4 v[24:25], v[48:51], off
	v_mov_b32_e32 v24, v163
	s_nop 0
	v_lshlrev_b32_e32 v24, 2, v24
	v_bitop3_b32 v24, v24, 64, v248 bitop3:0x6c
	ds_bpermute_b32 v24, v24, v94
	s_waitcnt lgkmcnt(0)
	v_add_f32_e32 v48, v94, v24
	v_mov_b32_e32 v24, v163
	s_nop 0
	v_lshlrev_b32_e32 v24, 2, v24
	v_bitop3_b32 v24, v24, s46, v248 bitop3:0x6c
	ds_bpermute_b32 v49, v24, v48
	v_lshl_add_u64 v[24:25], v[182:183], 3, s[0:1]
	s_mov_b64 s[0:1], exec
	s_and_b64 s[8:9], s[0:1], s[2:3]
	v_mov_b32_e32 v240, 0x358637bd
	s_mov_b64 exec, s[8:9]
	s_cbranch_execz .LBB0_162
	s_waitcnt lgkmcnt(0)
	v_add_f32_e32 v48, v48, v49
	v_mul_f32_e32 v48, 0x47800000, v48
	v_rndne_f32_e32 v48, v48
	s_mov_b32 s7, 0x2f800000
	v_mul_f32_e64 v49, |v48|, s7
	v_floor_f32_e32 v49, v49
	s_mov_b32 s7, 0xcf800000
	v_fma_f32 v50, v49, s7, |v48|
	v_cvt_u32_f32_e32 v50, v50
	v_cvt_u32_f32_e32 v49, v49
	v_ashrrev_i32_e32 v51, 31, v48
	v_xor_b32_e32 v48, v50, v51
	v_xor_b32_e32 v49, v49, v51
	v_sub_co_u32_e32 v48, vcc, v48, v51
	s_nop 1
	v_subb_co_u32_e32 v49, vcc, v49, v51, vcc
	global_atomic_add_x2 v[24:25], v[48:49], off

.LBB0_317:
	s_add_u32 s8, s60, 0xfff00080
	s_addc_u32 s9, s61, -1
	s_add_i32 s16, 0, 0x10000
	v_add_u32_e32 v140, s16, v169
	ds_read_b128 v[120:123], v140
	ds_read_b128 v[124:127], v140 offset:1024
	ds_read_b128 v[136:139], v140 offset:2048
	ds_read_b128 v[140:143], v140 offset:3072
	s_cmp_eq_u32 s15, 60
	s_cselect_b32 s9, s7, s9
	s_cselect_b32 s8, s36, s8
	s_cselect_b32 s63, s1, s14
	s_cselect_b32 s62, s12, s13
	v_lshl_add_u64 v[198:199], s[60:61], 0, v[178:179]
	s_add_i32 m0, s40, 0xc000
	ds_read_b128 v[144:147], v171
	ds_read_b128 v[148:151], v171 offset:1024
	ds_read_b128 v[152:155], v171 offset:2048
	ds_read_b128 v[156:159], v171 offset:3072
	ds_read_b128 v[182:185], v171 offset:4096
	ds_read_b128 v[186:189], v171 offset:5120
	ds_read_b128 v[190:193], v171 offset:6144
	ds_read_b128 v[194:197], v171 offset:7168
	global_load_lds_dwordx4 v[198:199], off
	v_lshl_add_u64 v[198:199], s[60:61], 0, v[180:181]
	s_add_i32 m0, s40, 0xe000
	s_nop 0
	global_load_lds_dwordx4 v[198:199], off
	s_waitcnt lgkmcnt(8)
	s_barrier
	s_waitcnt lgkmcnt(0)
	s_setprio 1
	s_waitcnt lgkmcnt(0)
	v_mfma_f32_16x16x32_bf16 v[132:135], v[120:123], v[144:147], v[132:135]
	v_mfma_f32_16x16x32_bf16 v[128:131], v[136:139], v[144:147], v[128:131]
	v_mfma_f32_16x16x32_bf16 v[116:119], v[120:123], v[152:155], v[116:119]
	v_mfma_f32_16x16x32_bf16 v[112:115], v[136:139], v[152:155], v[112:115]
	v_mfma_f32_16x16x32_bf16 v[108:111], v[120:123], v[182:185], v[108:111]
	v_mfma_f32_16x16x32_bf16 v[104:107], v[136:139], v[182:185], v[104:107]
	v_mfma_f32_16x16x32_bf16 v[100:103], v[120:123], v[190:193], v[100:103]
	v_mfma_f32_16x16x32_bf16 v[96:99], v[136:139], v[190:193], v[96:99]
	v_mfma_f32_16x16x32_bf16 v[132:135], v[124:127], v[148:151], v[132:135]
	v_mfma_f32_16x16x32_bf16 v[128:131], v[140:143], v[148:151], v[128:131]
	v_mfma_f32_16x16x32_bf16 v[116:119], v[124:127], v[156:159], v[116:119]
	v_mfma_f32_16x16x32_bf16 v[112:115], v[140:143], v[156:159], v[112:115]
	v_mfma_f32_16x16x32_bf16 v[108:111], v[124:127], v[186:189], v[108:111]
	v_mfma_f32_16x16x32_bf16 v[104:107], v[140:143], v[186:189], v[104:107]
	v_mfma_f32_16x16x32_bf16 v[100:103], v[124:127], v[194:197], v[100:103]
	v_mfma_f32_16x16x32_bf16 v[96:99], v[140:143], v[194:197], v[96:99]
	s_setprio 0
	s_barrier
	s_add_i32 s18, 0, 0x14000
	s_add_i32 s16, s16, s39
	v_add_u32_e32 v164, s18, v169
	v_lshl_add_u64 v[214:215], s[62:63], 0, v[160:161]
	s_mov_b32 m0, s16
	ds_read_b128 v[198:201], v164
	ds_read_b128 v[202:205], v164 offset:1024
	ds_read_b128 v[206:209], v164 offset:2048
	ds_read_b128 v[210:213], v164 offset:3072
	global_load_lds_dwordx4 v[214:215], off
	v_lshl_add_u64 v[216:217], s[62:63], 0, v[172:173]
	s_add_i32 m0, s16, 0x2000
	s_nop 0
	global_load_lds_dwordx4 v[216:217], off
	s_barrier
	s_waitcnt lgkmcnt(0)
	s_setprio 1
	s_waitcnt lgkmcnt(0)
	v_mfma_f32_16x16x32_bf16 v[60:63], v[198:201], v[144:147], v[60:63]
	v_mfma_f32_16x16x32_bf16 v[56:59], v[206:209], v[144:147], v[56:59]
	v_mfma_f32_16x16x32_bf16 v[52:55], v[198:201], v[152:155], v[52:55]
	v_mfma_f32_16x16x32_bf16 v[48:51], v[206:209], v[152:155], v[48:51]
	v_mfma_f32_16x16x32_bf16 v[44:47], v[198:201], v[182:185], v[44:47]
	v_mfma_f32_16x16x32_bf16 v[40:43], v[206:209], v[182:185], v[40:43]
	v_mfma_f32_16x16x32_bf16 v[36:39], v[198:201], v[190:193], v[36:39]
	v_mfma_f32_16x16x32_bf16 v[32:35], v[206:209], v[190:193], v[32:35]
	v_mfma_f32_16x16x32_bf16 v[60:63], v[202:205], v[148:151], v[60:63]
	v_mfma_f32_16x16x32_bf16 v[56:59], v[210:213], v[148:151], v[56:59]
	v_mfma_f32_16x16x32_bf16 v[52:55], v[202:205], v[156:159], v[52:55]
	v_mfma_f32_16x16x32_bf16 v[48:51], v[210:213], v[156:159], v[48:51]
	v_mfma_f32_16x16x32_bf16 v[44:47], v[202:205], v[186:189], v[44:47]
	v_mfma_f32_16x16x32_bf16 v[40:43], v[210:213], v[186:189], v[40:43]
	v_mfma_f32_16x16x32_bf16 v[36:39], v[202:205], v[194:197], v[36:39]
	v_mfma_f32_16x16x32_bf16 v[32:35], v[210:213], v[194:197], v[32:35]
	s_setprio 0
	s_mov_b32 m0, s40
	v_lshl_add_u64 v[218:219], s[8:9], 0, v[176:177]
	s_barrier
	ds_read_b128 v[144:147], v171 offset:16384
	ds_read_b128 v[148:151], v171 offset:17408
	ds_read_b128 v[152:155], v171 offset:18432
	ds_read_b128 v[156:159], v171 offset:19456
	ds_read_b128 v[182:185], v171 offset:20480
	ds_read_b128 v[186:189], v171 offset:21504
	ds_read_b128 v[190:193], v171 offset:22528
	ds_read_b128 v[194:197], v171 offset:23552
	global_load_lds_dwordx4 v[218:219], off
	v_lshl_add_u64 v[220:221], s[8:9], 0, v[174:175]
	s_mov_b32 m0, s41
	s_nop 0
	global_load_lds_dwordx4 v[220:221], off
	s_barrier
	s_waitcnt lgkmcnt(0)
	s_setprio 1
	s_waitcnt lgkmcnt(0)
	v_mfma_f32_16x16x32_bf16 v[92:95], v[120:123], v[144:147], v[92:95]
	v_mfma_f32_16x16x32_bf16 v[88:91], v[136:139], v[144:147], v[88:91]
	v_mfma_f32_16x16x32_bf16 v[84:87], v[120:123], v[152:155], v[84:87]
	v_mfma_f32_16x16x32_bf16 v[80:83], v[136:139], v[152:155], v[80:83]
	v_mfma_f32_16x16x32_bf16 v[76:79], v[120:123], v[182:185], v[76:79]
	v_mfma_f32_16x16x32_bf16 v[72:75], v[136:139], v[182:185], v[72:75]
	v_mfma_f32_16x16x32_bf16 v[68:71], v[120:123], v[190:193], v[68:71]
	v_mfma_f32_16x16x32_bf16 v[64:67], v[136:139], v[190:193], v[64:67]
	v_mfma_f32_16x16x32_bf16 v[92:95], v[124:127], v[148:151], v[92:95]
	v_mfma_f32_16x16x32_bf16 v[88:91], v[140:143], v[148:151], v[88:91]
	v_mfma_f32_16x16x32_bf16 v[84:87], v[124:127], v[156:159], v[84:87]
	v_mfma_f32_16x16x32_bf16 v[80:83], v[140:143], v[156:159], v[80:83]
	v_mfma_f32_16x16x32_bf16 v[76:79], v[124:127], v[186:189], v[76:79]
	v_mfma_f32_16x16x32_bf16 v[72:75], v[140:143], v[186:189], v[72:75]
	v_mfma_f32_16x16x32_bf16 v[68:71], v[124:127], v[194:197], v[68:71]
	v_mfma_f32_16x16x32_bf16 v[64:67], v[140:143], v[194:197], v[64:67]
	s_setprio 0
	s_barrier
	s_add_u32 s16, s62, 0x100000
	s_addc_u32 s17, s63, 0
	s_add_i32 s18, s18, s39
	v_lshl_add_u64 v[120:121], s[16:17], 0, v[160:161]
	s_mov_b32 m0, s18
	s_nop 0
	global_load_lds_dwordx4 v[120:121], off
	v_lshl_add_u64 v[120:121], s[16:17], 0, v[172:173]
	s_add_i32 m0, s18, 0x2000
	s_nop 0
	global_load_lds_dwordx4 v[120:121], off
	s_waitcnt vmcnt(6)
	s_barrier
	s_setprio 1
	v_mfma_f32_16x16x32_bf16 v[28:31], v[198:201], v[144:147], v[28:31]
	v_mfma_f32_16x16x32_bf16 v[24:27], v[206:209], v[144:147], v[24:27]
	v_mfma_f32_16x16x32_bf16 v[20:23], v[198:201], v[152:155], v[20:23]
	v_mfma_f32_16x16x32_bf16 v[16:19], v[206:209], v[152:155], v[16:19]
	v_mfma_f32_16x16x32_bf16 v[12:15], v[198:201], v[182:185], v[12:15]
	v_mfma_f32_16x16x32_bf16 v[8:11], v[206:209], v[182:185], v[8:11]
	v_mfma_f32_16x16x32_bf16 v[4:7], v[198:201], v[190:193], v[4:7]
	v_mfma_f32_16x16x32_bf16 v[0:3], v[206:209], v[190:193], v[0:3]
	v_mfma_f32_16x16x32_bf16 v[28:31], v[202:205], v[148:151], v[28:31]
	v_mfma_f32_16x16x32_bf16 v[24:27], v[210:213], v[148:151], v[24:27]
	v_mfma_f32_16x16x32_bf16 v[20:23], v[202:205], v[156:159], v[20:23]
	v_mfma_f32_16x16x32_bf16 v[16:19], v[210:213], v[156:159], v[16:19]
	v_mfma_f32_16x16x32_bf16 v[12:15], v[202:205], v[186:189], v[12:15]
	v_mfma_f32_16x16x32_bf16 v[8:11], v[210:213], v[186:189], v[8:11]
	v_mfma_f32_16x16x32_bf16 v[4:7], v[202:205], v[194:197], v[4:7]
	v_mfma_f32_16x16x32_bf16 v[0:3], v[210:213], v[194:197], v[0:3]
	s_setprio 0
	s_add_i32 s16, 0, 0x18000
	v_add_u32_e32 v140, s16, v169
	s_barrier
	ds_read_b128 v[120:123], v140
	ds_read_b128 v[124:127], v140 offset:1024
	ds_read_b128 v[136:139], v140 offset:2048
	ds_read_b128 v[140:143], v140 offset:3072
	s_add_u32 s8, s8, 0x100000
	s_addc_u32 s9, s9, 0
	s_mov_b32 m0, s42
	v_lshl_add_u64 v[198:199], s[8:9], 0, v[176:177]
	ds_read_b128 v[144:147], v171 offset:32768
	ds_read_b128 v[148:151], v171 offset:33792
	ds_read_b128 v[152:155], v171 offset:34816
	ds_read_b128 v[156:159], v171 offset:35840
	ds_read_b128 v[182:185], v171 offset:36864
	ds_read_b128 v[186:189], v171 offset:37888
	ds_read_b128 v[190:193], v171 offset:38912
	ds_read_b128 v[194:197], v171 offset:39936
	global_load_lds_dwordx4 v[198:199], off
	v_lshl_add_u64 v[198:199], s[8:9], 0, v[174:175]
	s_mov_b32 m0, s43
	s_nop 0
	global_load_lds_dwordx4 v[198:199], off
	s_waitcnt lgkmcnt(8)
	s_barrier
	s_waitcnt lgkmcnt(0)
	s_setprio 1
	s_waitcnt lgkmcnt(0)
	v_mfma_f32_16x16x32_bf16 v[132:135], v[120:123], v[144:147], v[132:135]
	v_mfma_f32_16x16x32_bf16 v[128:131], v[136:139], v[144:147], v[128:131]
	v_mfma_f32_16x16x32_bf16 v[116:119], v[120:123], v[152:155], v[116:119]
	v_mfma_f32_16x16x32_bf16 v[112:115], v[136:139], v[152:155], v[112:115]
	v_mfma_f32_16x16x32_bf16 v[108:111], v[120:123], v[182:185], v[108:111]
	v_mfma_f32_16x16x32_bf16 v[104:107], v[136:139], v[182:185], v[104:107]
	v_mfma_f32_16x16x32_bf16 v[100:103], v[120:123], v[190:193], v[100:103]
	v_mfma_f32_16x16x32_bf16 v[96:99], v[136:139], v[190:193], v[96:99]
	v_mfma_f32_16x16x32_bf16 v[132:135], v[124:127], v[148:151], v[132:135]
	v_mfma_f32_16x16x32_bf16 v[128:131], v[140:143], v[148:151], v[128:131]
	v_mfma_f32_16x16x32_bf16 v[116:119], v[124:127], v[156:159], v[116:119]
	v_mfma_f32_16x16x32_bf16 v[112:115], v[140:143], v[156:159], v[112:115]
	v_mfma_f32_16x16x32_bf16 v[108:111], v[124:127], v[186:189], v[108:111]
	v_mfma_f32_16x16x32_bf16 v[104:107], v[140:143], v[186:189], v[104:107]
	v_mfma_f32_16x16x32_bf16 v[100:103], v[124:127], v[194:197], v[100:103]
	v_mfma_f32_16x16x32_bf16 v[96:99], v[140:143], v[194:197], v[96:99]
	s_setprio 0
	s_barrier
	s_add_i32 s17, 0, 0x1c000
	s_add_i32 s8, s16, s39
	v_add_u32_e32 v164, s17, v169
	v_lshl_add_u64 v[214:215], v[214:215], 0, s[74:75]
	s_mov_b32 m0, s8
	ds_read_b128 v[198:201], v164
	ds_read_b128 v[202:205], v164 offset:1024
	ds_read_b128 v[206:209], v164 offset:2048
	ds_read_b128 v[210:213], v164 offset:3072
	global_load_lds_dwordx4 v[214:215], off
	v_lshl_add_u64 v[214:215], v[216:217], 0, s[74:75]
	s_add_i32 m0, s8, 0x2000
	s_nop 0
	global_load_lds_dwordx4 v[214:215], off
	s_barrier
	s_waitcnt lgkmcnt(0)
	s_setprio 1
	s_waitcnt lgkmcnt(0)
	v_mfma_f32_16x16x32_bf16 v[60:63], v[198:201], v[144:147], v[60:63]
	v_mfma_f32_16x16x32_bf16 v[56:59], v[206:209], v[144:147], v[56:59]
	v_mfma_f32_16x16x32_bf16 v[52:55], v[198:201], v[152:155], v[52:55]
	v_mfma_f32_16x16x32_bf16 v[48:51], v[206:209], v[152:155], v[48:51]
	v_mfma_f32_16x16x32_bf16 v[44:47], v[198:201], v[182:185], v[44:47]
	v_mfma_f32_16x16x32_bf16 v[40:43], v[206:209], v[182:185], v[40:43]
	v_mfma_f32_16x16x32_bf16 v[36:39], v[198:201], v[190:193], v[36:39]
	v_mfma_f32_16x16x32_bf16 v[32:35], v[206:209], v[190:193], v[32:35]
	v_mfma_f32_16x16x32_bf16 v[60:63], v[202:205], v[148:151], v[60:63]
	v_mfma_f32_16x16x32_bf16 v[56:59], v[210:213], v[148:151], v[56:59]
	v_mfma_f32_16x16x32_bf16 v[52:55], v[202:205], v[156:159], v[52:55]
	v_mfma_f32_16x16x32_bf16 v[48:51], v[210:213], v[156:159], v[48:51]
	v_mfma_f32_16x16x32_bf16 v[44:47], v[202:205], v[186:189], v[44:47]
	v_mfma_f32_16x16x32_bf16 v[40:43], v[210:213], v[186:189], v[40:43]
	v_mfma_f32_16x16x32_bf16 v[36:39], v[202:205], v[194:197], v[36:39]
	v_mfma_f32_16x16x32_bf16 v[32:35], v[210:213], v[194:197], v[32:35]
	s_setprio 0
	s_mov_b32 m0, s66
	v_lshl_add_u64 v[214:215], v[218:219], 0, s[74:75]
	s_barrier
	ds_read_b128 v[144:147], v171 offset:49152
	ds_read_b128 v[148:151], v171 offset:50176
	ds_read_b128 v[152:155], v171 offset:51200
	ds_read_b128 v[156:159], v171 offset:52224
	ds_read_b128 v[182:185], v171 offset:53248
	ds_read_b128 v[186:189], v171 offset:54272
	ds_read_b128 v[190:193], v171 offset:55296
	ds_read_b128 v[194:197], v171 offset:56320
	global_load_lds_dwordx4 v[214:215], off
	v_lshl_add_u64 v[214:215], v[220:221], 0, s[74:75]
	s_mov_b32 m0, s67
	s_nop 0
	global_load_lds_dwordx4 v[214:215], off
	s_barrier
	s_waitcnt lgkmcnt(0)
	s_setprio 1
	s_waitcnt lgkmcnt(0)
	v_mfma_f32_16x16x32_bf16 v[92:95], v[120:123], v[144:147], v[92:95]
	v_mfma_f32_16x16x32_bf16 v[88:91], v[136:139], v[144:147], v[88:91]
	v_mfma_f32_16x16x32_bf16 v[84:87], v[120:123], v[152:155], v[84:87]
	v_mfma_f32_16x16x32_bf16 v[80:83], v[136:139], v[152:155], v[80:83]
	v_mfma_f32_16x16x32_bf16 v[76:79], v[120:123], v[182:185], v[76:79]
	v_mfma_f32_16x16x32_bf16 v[72:75], v[136:139], v[182:185], v[72:75]
	v_mfma_f32_16x16x32_bf16 v[68:71], v[120:123], v[190:193], v[68:71]
	v_mfma_f32_16x16x32_bf16 v[64:67], v[136:139], v[190:193], v[64:67]
	v_mfma_f32_16x16x32_bf16 v[92:95], v[124:127], v[148:151], v[92:95]
	v_mfma_f32_16x16x32_bf16 v[88:91], v[140:143], v[148:151], v[88:91]
	v_mfma_f32_16x16x32_bf16 v[84:87], v[124:127], v[156:159], v[84:87]
	v_mfma_f32_16x16x32_bf16 v[80:83], v[140:143], v[156:159], v[80:83]
	v_mfma_f32_16x16x32_bf16 v[76:79], v[124:127], v[186:189], v[76:79]
	v_mfma_f32_16x16x32_bf16 v[72:75], v[140:143], v[186:189], v[72:75]
	v_mfma_f32_16x16x32_bf16 v[68:71], v[124:127], v[194:197], v[68:71]
	v_mfma_f32_16x16x32_bf16 v[64:67], v[140:143], v[194:197], v[64:67]
	s_setprio 0
	s_barrier
	s_add_u32 s8, s62, 0x100080
	s_addc_u32 s9, s63, 0
	s_add_i32 s16, s17, s39
	v_lshl_add_u64 v[120:121], s[8:9], 0, v[160:161]
	s_mov_b32 m0, s16
	s_nop 0
	global_load_lds_dwordx4 v[120:121], off
	v_lshl_add_u64 v[120:121], s[8:9], 0, v[172:173]
	s_add_i32 m0, s16, 0x2000
	s_nop 0
	global_load_lds_dwordx4 v[120:121], off
	s_waitcnt vmcnt(6)
	s_barrier
	s_setprio 1
	v_mfma_f32_16x16x32_bf16 v[28:31], v[198:201], v[144:147], v[28:31]
	v_mfma_f32_16x16x32_bf16 v[24:27], v[206:209], v[144:147], v[24:27]
	v_mfma_f32_16x16x32_bf16 v[20:23], v[198:201], v[152:155], v[20:23]
	v_mfma_f32_16x16x32_bf16 v[16:19], v[206:209], v[152:155], v[16:19]
	v_mfma_f32_16x16x32_bf16 v[12:15], v[198:201], v[182:185], v[12:15]
	v_mfma_f32_16x16x32_bf16 v[8:11], v[206:209], v[182:185], v[8:11]
	v_mfma_f32_16x16x32_bf16 v[4:7], v[198:201], v[190:193], v[4:7]
	v_mfma_f32_16x16x32_bf16 v[0:3], v[206:209], v[190:193], v[0:3]
	v_mfma_f32_16x16x32_bf16 v[28:31], v[202:205], v[148:151], v[28:31]
	v_mfma_f32_16x16x32_bf16 v[24:27], v[210:213], v[148:151], v[24:27]
	v_mfma_f32_16x16x32_bf16 v[20:23], v[202:205], v[156:159], v[20:23]
	v_mfma_f32_16x16x32_bf16 v[16:19], v[210:213], v[156:159], v[16:19]
	v_mfma_f32_16x16x32_bf16 v[12:15], v[202:205], v[186:189], v[12:15]
	v_mfma_f32_16x16x32_bf16 v[8:11], v[210:213], v[186:189], v[8:11]
	v_mfma_f32_16x16x32_bf16 v[4:7], v[202:205], v[194:197], v[4:7]
	v_mfma_f32_16x16x32_bf16 v[0:3], v[210:213], v[194:197], v[0:3]
	s_setprio 0
	s_add_i32 s15, s15, 2
	s_add_u32 s60, s60, 0x100
	s_addc_u32 s61, s61, 0
	s_add_u32 s13, s13, 0x100
	s_addc_u32 s14, s14, 0
	s_cmp_gt_u32 s15, 61
	s_barrier
	s_cbranch_scc0 .LBB0_317
	v_lshl_or_b32 v196, s10, 8, v170
	s_lshr_b32 s1, s92, 5
	v_lshl_add_u32 v182, s92, 8, v168
	s_mul_i32 s8, s1, 0x1800
	v_ashrrev_i32_e32 v197, 31, v196
	v_readlane_b32 s20, v249, 12
	s_ashr_i32 s9, s8, 31
	v_lshlrev_b64 v[202:203], 1, v[196:197]
	v_readlane_b32 s21, v249, 13
	v_ashrrev_i32_e32 v183, 31, v182
	v_or_b32_e32 v198, 16, v182
	v_lshl_add_u64 v[120:121], s[20:21], 0, v[202:203]
	v_lshlrev_b64 v[122:123], 11, v[182:183]
	v_ashrrev_i32_e32 v199, 31, v198
	v_or_b32_e32 v204, 32, v182
	s_lshl_b64 s[8:9], s[8:9], 2
	v_readlane_b32 s1, v250, 52
	v_lshl_add_u64 v[194:195], v[120:121], 0, v[122:123]
	v_lshlrev_b64 v[122:123], 11, v[198:199]
	v_ashrrev_i32_e32 v205, 31, v204
	v_or_b32_e32 v200, 48, v182
	s_add_u32 s12, s1, s8
	v_readlane_b32 s1, v250, 53
	v_lshl_add_u64 v[190:191], v[120:121], 0, v[122:123]
	v_lshlrev_b64 v[122:123], 11, v[204:205]
	v_ashrrev_i32_e32 v201, 31, v200
	v_add_u32_e32 v224, 0x80, v182
	s_addc_u32 s13, s1, s9
	v_lshlrev_b64 v[192:193], 2, v[196:197]
	v_lshl_add_u64 v[188:189], v[120:121], 0, v[122:123]
	v_lshlrev_b64 v[122:123], 11, v[200:201]
	v_ashrrev_i32_e32 v225, 31, v224
	v_lshl_add_u64 v[210:211], s[12:13], 0, v[192:193]
	v_readlane_b32 s12, v250, 50
	v_readlane_b32 s1, v250, 54
	v_lshl_add_u64 v[186:187], v[120:121], 0, v[122:123]
	v_lshlrev_b64 v[122:123], 11, v[224:225]
	v_readlane_b32 s13, v250, 51
	s_add_u32 s8, s1, s8
	v_readlane_b32 s1, v250, 55
	v_lshl_add_u64 v[184:185], v[120:121], 0, v[122:123]
	v_lshl_add_u64 v[206:207], s[12:13], 0, v[192:193]
	s_addc_u32 s9, s1, s9
	global_load_dwordx4 v[156:159], v[194:195], off
	global_load_dwordx4 v[152:155], v[190:191], off
	global_load_dwordx4 v[144:147], v[188:189], off
	global_load_dwordx4 v[140:143], v[186:187], off
	global_load_dwordx4 v[136:139], v[184:185], off
	global_load_dwordx4 v[120:123], v[210:211], off offset:16
	global_load_dwordx4 v[124:127], v[210:211], off
	global_load_dwordx4 v[148:151], v[206:207], off offset:16
	global_load_dwordx4 v[212:215], v[206:207], off
	v_lshl_add_u64 v[206:207], s[8:9], 0, v[192:193]
	global_load_dwordx4 v[220:223], v[206:207], off offset:16
	global_load_dwordx4 v[216:219], v[206:207], off
	v_add_u32_e32 v226, 0x90, v182
	v_ashrrev_i32_e32 v227, 31, v226
	v_add_u32_e32 v234, 0xa0, v182
	v_ashrrev_i32_e32 v235, 31, v234
	v_add_u32_e32 v236, 0xb0, v182
	v_ashrrev_i32_e32 v237, 31, v236
	v_lshlrev_b64 v[230:231], 10, v[204:205]
	v_lshlrev_b64 v[232:233], 10, v[200:201]
	v_lshlrev_b64 v[224:225], 10, v[224:225]
	v_readlane_b32 s8, v250, 42
	v_readlane_b32 s9, v250, 43
	v_readlane_b32 s22, v249, 14
	v_readlane_b32 s23, v249, 15
	v_readlane_b32 s24, v249, 16
	v_readlane_b32 s25, v249, 17
	v_readlane_b32 s26, v249, 18
	v_readlane_b32 s27, v249, 19
	s_waitcnt vmcnt(0)
	v_lshlrev_b32_e32 v228, 16, v158
	v_and_b32_e32 v229, 0xffff0000, v158
	v_lshlrev_b32_e32 v158, 16, v159
	v_and_b32_e32 v159, 0xffff0000, v159
	v_pk_add_f32 v[208:209], v[216:217], 1.0 op_sel_hi:[1,0]
	v_pk_add_f32 v[192:193], v[218:219], 1.0 op_sel_hi:[1,0]
	v_pk_mul_f32 v[218:219], v[212:213], v[208:209]
	v_pk_add_f32 v[208:209], v[220:221], 1.0 op_sel_hi:[1,0]
	v_pk_mul_f32 v[216:217], v[214:215], v[192:193]
	v_pk_add_f32 v[192:193], v[222:223], 1.0 op_sel_hi:[1,0]
	v_pk_mul_f32 v[222:223], v[148:149], v[208:209]
	v_lshlrev_b64 v[148:149], 11, v[226:227]
	v_lshl_add_u64 v[148:149], s[20:21], 0, v[148:149]
	v_pk_mul_f32 v[220:221], v[150:151], v[192:193]
	v_lshl_add_u64 v[192:193], v[148:149], 0, v[202:203]
	v_lshlrev_b32_e32 v214, 16, v156
	v_and_b32_e32 v215, 0xffff0000, v156
	v_lshlrev_b32_e32 v156, 16, v157
	v_and_b32_e32 v157, 0xffff0000, v157
	global_load_dwordx4 v[148:151], v[192:193], off
	v_pk_fma_f32 v[134:135], v[134:135], v[126:127], v[156:157]
	v_pk_fma_f32 v[132:133], v[132:133], v[124:125], v[214:215]
	v_pk_fma_f32 v[156:157], v[130:131], v[122:123], v[158:159]
	v_pk_fma_f32 v[158:159], v[128:129], v[120:121], v[228:229]
	v_cvt_pk_bf16_f32 v128, v132, v133
	v_cvt_pk_bf16_f32 v129, v134, v135
	v_lshlrev_b64 v[208:209], 10, v[182:183]
	v_cvt_pk_bf16_f32 v130, v158, v159
	v_cvt_pk_bf16_f32 v131, v156, v157
	global_store_dwordx4 v[194:195], v[128:131], off
	v_lshl_add_u64 v[212:213], v[208:209], 0, v[196:197]
	v_lshlrev_b64 v[228:229], 10, v[198:199]
	v_mul_f32_e32 v128, v133, v133
	v_mul_f32_e32 v129, v135, v135
	v_fmac_f32_e32 v128, v132, v132
	v_fmac_f32_e32 v129, v134, v134
	v_add_f32_e32 v128, v128, v129
	v_mul_f32_e32 v129, v159, v159
	v_fmac_f32_e32 v129, v158, v158
	v_add_f32_e32 v128, v129, v128
	v_mul_f32_e32 v129, v157, v157
	v_fmac_f32_e32 v129, v156, v156
	v_add_f32_e32 v238, v129, v128
	v_pk_mul_f32 v[130:131], v[134:135], v[216:217]
	v_pk_mul_f32 v[128:129], v[132:133], v[218:219]
	v_pk_mul_f32 v[132:133], v[156:157], v[220:221]
	v_pk_mul_f32 v[134:135], v[158:159], v[222:223]
	v_cvt_pk_bf16_f32 v128, v128, v129
	v_cvt_pk_bf16_f32 v129, v130, v131
	v_lshlrev_b32_e32 v158, 16, v154
	v_cvt_pk_bf16_f32 v130, v134, v135
	v_cvt_pk_bf16_f32 v131, v132, v133
	v_lshl_add_u64 v[132:133], v[212:213], 1, s[28:29]
	global_store_dwordx4 v[132:133], v[128:131], off
	v_lshlrev_b32_e32 v134, 16, v152
	v_and_b32_e32 v135, 0xffff0000, v152
	v_lshlrev_b64 v[128:129], 11, v[234:235]
	v_lshl_add_u64 v[128:129], s[20:21], 0, v[128:129]
	v_lshl_add_u64 v[212:213], v[128:129], 0, v[202:203]
	v_lshlrev_b32_e32 v152, 16, v153
	v_and_b32_e32 v153, 0xffff0000, v153
	v_and_b32_e32 v159, 0xffff0000, v154
	v_lshlrev_b32_e32 v154, 16, v155
	v_and_b32_e32 v155, 0xffff0000, v155
	global_load_dwordx4 v[128:131], v[212:213], off
	v_pk_fma_f32 v[152:153], v[118:119], v[126:127], v[152:153]
	v_pk_fma_f32 v[156:157], v[116:117], v[124:125], v[134:135]
	v_pk_fma_f32 v[154:155], v[114:115], v[122:123], v[154:155]
	v_pk_fma_f32 v[198:199], v[112:113], v[120:121], v[158:159]
	v_cvt_pk_bf16_f32 v112, v156, v157
	v_cvt_pk_bf16_f32 v113, v152, v153
	v_lshl_add_u64 v[132:133], v[228:229], 0, v[196:197]
	v_cvt_pk_bf16_f32 v114, v198, v199
	v_cvt_pk_bf16_f32 v115, v154, v155
	global_store_dwordx4 v[190:191], v[112:115], off
	v_pk_mul_f32 v[116:117], v[154:155], v[220:221]
	v_pk_mul_f32 v[118:119], v[198:199], v[222:223]
	v_pk_mul_f32 v[114:115], v[152:153], v[216:217]
	v_pk_mul_f32 v[112:113], v[156:157], v[218:219]
	v_lshlrev_b32_e32 v134, 16, v146
	v_cvt_pk_bf16_f32 v112, v112, v113
	v_cvt_pk_bf16_f32 v113, v114, v115
	v_cvt_pk_bf16_f32 v114, v118, v119
	v_cvt_pk_bf16_f32 v115, v116, v117
	v_lshl_add_u64 v[116:117], v[132:133], 1, s[28:29]
	global_store_dwordx4 v[116:117], v[112:115], off
	v_lshlrev_b32_e32 v118, 16, v144
	v_and_b32_e32 v119, 0xffff0000, v144
	v_lshlrev_b64 v[112:113], 11, v[236:237]
	v_lshl_add_u64 v[112:113], s[20:21], 0, v[112:113]
	v_lshl_add_u64 v[214:215], v[112:113], 0, v[202:203]
	global_load_dwordx4 v[112:115], v[214:215], off
	v_lshlrev_b32_e32 v132, 16, v145
	v_and_b32_e32 v133, 0xffff0000, v145
	v_and_b32_e32 v135, 0xffff0000, v146
	v_lshlrev_b32_e32 v146, 16, v147
	v_and_b32_e32 v147, 0xffff0000, v147
	v_pk_fma_f32 v[144:145], v[110:111], v[126:127], v[132:133]
	v_pk_fma_f32 v[202:203], v[108:109], v[124:125], v[118:119]
	v_pk_fma_f32 v[146:147], v[106:107], v[122:123], v[146:147]
	v_pk_fma_f32 v[204:205], v[104:105], v[120:121], v[134:135]
	v_cvt_pk_bf16_f32 v104, v202, v203
	v_cvt_pk_bf16_f32 v105, v144, v145
	v_lshl_add_u64 v[116:117], v[230:231], 0, v[196:197]
	v_cvt_pk_bf16_f32 v106, v204, v205
	v_cvt_pk_bf16_f32 v107, v146, v147
	global_store_dwordx4 v[188:189], v[104:107], off
	v_pk_mul_f32 v[108:109], v[146:147], v[220:221]
	v_pk_mul_f32 v[110:111], v[204:205], v[222:223]
	v_pk_mul_f32 v[106:107], v[216:217], v[144:145]
	v_pk_mul_f32 v[104:105], v[218:219], v[202:203]
	v_lshlrev_b64 v[226:227], 10, v[226:227]
	v_cvt_pk_bf16_f32 v104, v104, v105
	v_cvt_pk_bf16_f32 v105, v106, v107
	v_cvt_pk_bf16_f32 v106, v110, v111
	v_cvt_pk_bf16_f32 v107, v108, v109
	v_lshl_add_u64 v[108:109], v[116:117], 1, s[28:29]
	global_store_dwordx4 v[108:109], v[104:107], off
	v_lshlrev_b32_e32 v108, 16, v141
	v_and_b32_e32 v109, 0xffff0000, v141
	v_lshlrev_b32_e32 v106, 16, v140
	v_and_b32_e32 v107, 0xffff0000, v140
	v_lshlrev_b32_e32 v110, 16, v142
	v_and_b32_e32 v111, 0xffff0000, v142
	v_lshlrev_b32_e32 v116, 16, v143
	v_and_b32_e32 v117, 0xffff0000, v143
	v_pk_fma_f32 v[140:141], v[102:103], v[126:127], v[108:109]
	v_pk_fma_f32 v[158:159], v[100:101], v[124:125], v[106:107]
	v_pk_fma_f32 v[142:143], v[98:99], v[122:123], v[116:117]
	v_pk_fma_f32 v[200:201], v[96:97], v[120:121], v[110:111]
	v_cvt_pk_bf16_f32 v96, v158, v159
	v_cvt_pk_bf16_f32 v97, v140, v141
	v_lshl_add_u64 v[104:105], v[232:233], 0, v[196:197]
	v_cvt_pk_bf16_f32 v98, v200, v201
	v_cvt_pk_bf16_f32 v99, v142, v143
	global_store_dwordx4 v[186:187], v[96:99], off
	v_pk_mul_f32 v[100:101], v[142:143], v[220:221]
	v_pk_mul_f32 v[102:103], v[200:201], v[222:223]
	v_pk_mul_f32 v[98:99], v[216:217], v[140:141]
	v_pk_mul_f32 v[96:97], v[218:219], v[158:159]
	s_nop 0
	v_cvt_pk_bf16_f32 v96, v96, v97
	v_cvt_pk_bf16_f32 v97, v98, v99
	v_cvt_pk_bf16_f32 v98, v102, v103
	v_cvt_pk_bf16_f32 v99, v100, v101
	v_lshl_add_u64 v[100:101], v[104:105], 1, s[28:29]
	global_store_dwordx4 v[100:101], v[96:99], off
	v_lshlrev_b32_e32 v100, 16, v137
	v_and_b32_e32 v101, 0xffff0000, v137
	v_lshlrev_b32_e32 v98, 16, v136
	v_and_b32_e32 v99, 0xffff0000, v136
	v_lshlrev_b32_e32 v102, 16, v138
	v_and_b32_e32 v103, 0xffff0000, v138
	v_lshlrev_b32_e32 v104, 16, v139
	v_and_b32_e32 v105, 0xffff0000, v139
	v_pk_fma_f32 v[116:117], v[94:95], v[126:127], v[100:101]
	v_pk_fma_f32 v[136:137], v[92:93], v[124:125], v[98:99]
	v_pk_fma_f32 v[118:119], v[90:91], v[122:123], v[104:105]
	v_pk_fma_f32 v[138:139], v[88:89], v[120:121], v[102:103]
	v_cvt_pk_bf16_f32 v88, v136, v137
	v_cvt_pk_bf16_f32 v89, v116, v117
	v_lshl_add_u64 v[96:97], v[224:225], 0, v[196:197]
	v_cvt_pk_bf16_f32 v90, v138, v139
	v_cvt_pk_bf16_f32 v91, v118, v119
	global_store_dwordx4 v[184:185], v[88:91], off
	v_pk_mul_f32 v[92:93], v[220:221], v[118:119]
	v_pk_mul_f32 v[94:95], v[222:223], v[138:139]
	v_pk_mul_f32 v[90:91], v[216:217], v[116:117]
	v_pk_mul_f32 v[88:89], v[218:219], v[136:137]
	s_nop 0
	v_cvt_pk_bf16_f32 v88, v88, v89
	v_cvt_pk_bf16_f32 v89, v90, v91
	v_cvt_pk_bf16_f32 v90, v94, v95
	v_cvt_pk_bf16_f32 v91, v92, v93
	v_lshl_add_u64 v[92:93], v[96:97], 1, s[28:29]
	global_store_dwordx4 v[92:93], v[88:91], off
	s_waitcnt vmcnt(6)
	v_lshlrev_b32_e32 v92, 16, v149
	v_and_b32_e32 v93, 0xffff0000, v149
	v_lshlrev_b32_e32 v90, 16, v148
	v_and_b32_e32 v91, 0xffff0000, v148
	v_lshlrev_b32_e32 v94, 16, v150
	v_and_b32_e32 v95, 0xffff0000, v150
	v_lshlrev_b32_e32 v96, 16, v151
	v_and_b32_e32 v97, 0xffff0000, v151
	v_pk_fma_f32 v[104:105], v[86:87], v[126:127], v[92:93]
	v_pk_fma_f32 v[132:133], v[84:85], v[124:125], v[90:91]
	v_pk_fma_f32 v[106:107], v[82:83], v[122:123], v[96:97]
	v_pk_fma_f32 v[134:135], v[80:81], v[120:121], v[94:95]
	v_cvt_pk_bf16_f32 v80, v132, v133
	v_cvt_pk_bf16_f32 v81, v104, v105
	v_lshl_add_u64 v[88:89], v[226:227], 0, v[196:197]
	v_cvt_pk_bf16_f32 v82, v134, v135
	v_cvt_pk_bf16_f32 v83, v106, v107
	global_store_dwordx4 v[192:193], v[80:83], off
	v_pk_mul_f32 v[84:85], v[220:221], v[106:107]
	v_pk_mul_f32 v[86:87], v[222:223], v[134:135]
	v_pk_mul_f32 v[82:83], v[216:217], v[104:105]
	v_pk_mul_f32 v[80:81], v[218:219], v[132:133]
	v_lshlrev_b64 v[148:149], 10, v[234:235]
	v_cvt_pk_bf16_f32 v80, v80, v81
	v_cvt_pk_bf16_f32 v81, v82, v83
	v_cvt_pk_bf16_f32 v82, v86, v87
	v_cvt_pk_bf16_f32 v83, v84, v85
	v_lshl_add_u64 v[84:85], v[88:89], 1, s[28:29]
	global_store_dwordx4 v[84:85], v[80:83], off
	v_lshlrev_b32_e32 v84, 16, v129
	v_and_b32_e32 v85, 0xffff0000, v129
	v_lshlrev_b32_e32 v82, 16, v128
	v_and_b32_e32 v83, 0xffff0000, v128
	v_lshlrev_b32_e32 v86, 16, v130
	v_and_b32_e32 v87, 0xffff0000, v130
	v_lshlrev_b32_e32 v88, 16, v131
	v_and_b32_e32 v89, 0xffff0000, v131
	v_pk_fma_f32 v[96:97], v[78:79], v[126:127], v[84:85]
	v_pk_fma_f32 v[108:109], v[76:77], v[124:125], v[82:83]
	v_pk_fma_f32 v[98:99], v[74:75], v[122:123], v[88:89]
	v_pk_fma_f32 v[110:111], v[72:73], v[120:121], v[86:87]
	v_cvt_pk_bf16_f32 v72, v108, v109
	v_cvt_pk_bf16_f32 v73, v96, v97
	v_lshl_add_u64 v[80:81], v[148:149], 0, v[196:197]
	v_cvt_pk_bf16_f32 v74, v110, v111
	v_cvt_pk_bf16_f32 v75, v98, v99
	global_store_dwordx4 v[212:213], v[72:75], off
	v_pk_mul_f32 v[76:77], v[220:221], v[98:99]
	v_pk_mul_f32 v[78:79], v[222:223], v[110:111]
	v_pk_mul_f32 v[74:75], v[216:217], v[96:97]
	v_pk_mul_f32 v[72:73], v[218:219], v[108:109]
	v_lshlrev_b64 v[128:129], 10, v[236:237]
	v_cvt_pk_bf16_f32 v72, v72, v73
	v_cvt_pk_bf16_f32 v73, v74, v75
	v_cvt_pk_bf16_f32 v74, v78, v79
	v_cvt_pk_bf16_f32 v75, v76, v77
	v_lshl_add_u64 v[76:77], v[80:81], 1, s[28:29]
	global_store_dwordx4 v[76:77], v[72:75], off
	v_lshlrev_b32_e32 v76, 16, v113
	v_and_b32_e32 v77, 0xffff0000, v113
	v_lshlrev_b32_e32 v74, 16, v112
	v_and_b32_e32 v75, 0xffff0000, v112
	v_lshlrev_b32_e32 v78, 16, v114
	v_and_b32_e32 v79, 0xffff0000, v114
	v_lshlrev_b32_e32 v80, 16, v115
	v_and_b32_e32 v81, 0xffff0000, v115
	v_pk_fma_f32 v[92:93], v[70:71], v[126:127], v[76:77]
	v_pk_fma_f32 v[100:101], v[68:69], v[124:125], v[74:75]
	v_pk_fma_f32 v[94:95], v[66:67], v[122:123], v[80:81]
	v_pk_fma_f32 v[102:103], v[64:65], v[120:121], v[78:79]
	v_cvt_pk_bf16_f32 v64, v100, v101
	v_cvt_pk_bf16_f32 v65, v92, v93
	v_lshl_add_u64 v[72:73], v[128:129], 0, v[196:197]
	v_cvt_pk_bf16_f32 v66, v102, v103
	v_cvt_pk_bf16_f32 v67, v94, v95
	global_store_dwordx4 v[214:215], v[64:67], off
	v_pk_mul_f32 v[68:69], v[220:221], v[94:95]
	v_or_b32_e32 v112, 0x80, v196
	v_pk_mul_f32 v[66:67], v[216:217], v[92:93]
	v_pk_mul_f32 v[64:65], v[218:219], v[100:101]
	v_pk_mul_f32 v[70:71], v[222:223], v[102:103]
	v_cvt_pk_bf16_f32 v64, v64, v65
	v_cvt_pk_bf16_f32 v65, v66, v67
	v_ashrrev_i32_e32 v113, 31, v112
	v_cvt_pk_bf16_f32 v66, v70, v71
	v_cvt_pk_bf16_f32 v67, v68, v69
	v_lshl_add_u64 v[68:69], v[72:73], 1, s[28:29]
	global_store_dwordx4 v[68:69], v[64:67], off
	v_lshl_add_u64 v[114:115], v[112:113], 2, s[12:13]
	global_load_dwordx4 v[216:219], v[194:195], off offset:256
	global_load_dwordx4 v[88:91], v[190:191], off offset:256
	global_load_dwordx4 v[84:87], v[188:189], off offset:256
	global_load_dwordx4 v[76:79], v[186:187], off offset:256
	global_load_dwordx4 v[72:75], v[184:185], off offset:256
	global_load_dwordx4 v[64:67], v[210:211], off offset:528
	global_load_dwordx4 v[68:71], v[210:211], off offset:512
	global_load_dwordx4 v[80:83], v[114:115], off offset:16
	global_load_dwordx4 v[120:123], v[114:115], off
	global_load_dwordx4 v[124:127], v[206:207], off offset:528
	global_load_dwordx4 v[220:223], v[206:207], off offset:512
	s_waitcnt vmcnt(0)
	v_lshlrev_b32_e32 v150, 16, v217
	v_and_b32_e32 v151, 0xffff0000, v217
	v_lshlrev_b32_e32 v196, 16, v218
	v_and_b32_e32 v197, 0xffff0000, v218
	v_lshlrev_b32_e32 v206, 16, v219
	v_and_b32_e32 v207, 0xffff0000, v219
	v_pk_add_f32 v[124:125], v[124:125], 1.0 op_sel_hi:[1,0]
	v_pk_add_f32 v[114:115], v[222:223], 1.0 op_sel_hi:[1,0]
	v_pk_add_f32 v[130:131], v[220:221], 1.0 op_sel_hi:[1,0]
	v_pk_mul_f32 v[114:115], v[122:123], v[114:115]
	v_pk_mul_f32 v[120:121], v[120:121], v[130:131]
	v_pk_add_f32 v[122:123], v[126:127], 1.0 op_sel_hi:[1,0]
	v_lshlrev_b32_e32 v130, 16, v216
	v_and_b32_e32 v131, 0xffff0000, v216
	v_pk_mul_f32 v[122:123], v[82:83], v[122:123]
	v_pk_mul_f32 v[124:125], v[80:81], v[124:125]
	global_load_dwordx4 v[80:83], v[192:193], off offset:256
	v_pk_fma_f32 v[62:63], v[62:63], v[70:71], v[150:151]
	v_pk_fma_f32 v[60:61], v[60:61], v[68:69], v[130:131]
	v_pk_fma_f32 v[150:151], v[56:57], v[64:65], v[196:197]
	v_cvt_pk_bf16_f32 v56, v60, v61
	v_cvt_pk_bf16_f32 v57, v62, v63
	v_pk_fma_f32 v[130:131], v[58:59], v[66:67], v[206:207]
	v_cvt_pk_bf16_f32 v58, v150, v151
	v_lshl_add_u64 v[126:127], v[208:209], 0, v[112:113]
	v_cvt_pk_bf16_f32 v59, v130, v131
	global_store_dwordx4 v[194:195], v[56:59], off offset:256
	s_nop 1
	v_mul_f32_e32 v56, v61, v61
	v_mul_f32_e32 v57, v63, v63
	v_fmac_f32_e32 v56, v60, v60
	v_fmac_f32_e32 v57, v62, v62
	v_add_f32_e32 v56, v56, v57
	v_mul_f32_e32 v57, v151, v151
	v_fmac_f32_e32 v57, v150, v150
	v_add_f32_e32 v56, v57, v56
	v_mul_f32_e32 v57, v131, v131
	v_fmac_f32_e32 v57, v130, v130
	v_add_f32_e32 v56, v57, v56
	v_add_f32_e32 v164, v238, v56
	v_pk_mul_f32 v[58:59], v[62:63], v[114:115]
	v_pk_mul_f32 v[56:57], v[60:61], v[120:121]
	v_pk_mul_f32 v[60:61], v[130:131], v[122:123]
	v_pk_mul_f32 v[62:63], v[150:151], v[124:125]
	v_cvt_pk_bf16_f32 v56, v56, v57
	v_cvt_pk_bf16_f32 v57, v58, v59
	s_nop 0
	v_cvt_pk_bf16_f32 v58, v62, v63
	v_cvt_pk_bf16_f32 v59, v60, v61
	v_lshl_add_u64 v[60:61], v[126:127], 1, s[28:29]
	global_store_dwordx4 v[60:61], v[56:59], off
	global_load_dwordx4 v[56:59], v[212:213], off offset:256
	v_lshlrev_b32_e32 v62, 16, v88
	v_and_b32_e32 v63, 0xffff0000, v88
	v_lshlrev_b32_e32 v88, 16, v89
	v_and_b32_e32 v89, 0xffff0000, v89
	v_lshlrev_b32_e32 v126, 16, v90
	v_and_b32_e32 v127, 0xffff0000, v90
	v_lshlrev_b32_e32 v90, 16, v91
	v_and_b32_e32 v91, 0xffff0000, v91
	v_lshl_add_u64 v[60:61], v[228:229], 0, v[112:113]
	v_pk_fma_f32 v[54:55], v[54:55], v[70:71], v[88:89]
	v_pk_fma_f32 v[62:63], v[52:53], v[68:69], v[62:63]
	v_pk_fma_f32 v[52:53], v[50:51], v[66:67], v[90:91]
	v_pk_fma_f32 v[88:89], v[48:49], v[64:65], v[126:127]
	v_cvt_pk_bf16_f32 v48, v62, v63
	v_cvt_pk_bf16_f32 v49, v54, v55
	v_lshl_add_u64 v[60:61], v[60:61], 1, s[28:29]
	v_cvt_pk_bf16_f32 v50, v88, v89
	v_cvt_pk_bf16_f32 v51, v52, v53
	global_store_dwordx4 v[190:191], v[48:51], off offset:256
	v_pk_mul_f32 v[90:91], v[52:53], v[122:123]
	v_pk_mul_f32 v[126:127], v[88:89], v[124:125]
	v_pk_mul_f32 v[50:51], v[54:55], v[114:115]
	v_pk_mul_f32 v[48:49], v[62:63], v[120:121]
	s_nop 0
	v_cvt_pk_bf16_f32 v48, v48, v49
	v_cvt_pk_bf16_f32 v49, v50, v51
	v_cvt_pk_bf16_f32 v50, v126, v127
	v_cvt_pk_bf16_f32 v51, v90, v91
	global_store_dwordx4 v[60:61], v[48:51], off
	global_load_dwordx4 v[48:51], v[214:215], off offset:256
	v_lshlrev_b32_e32 v60, 16, v84
	v_and_b32_e32 v61, 0xffff0000, v84
	v_lshlrev_b32_e32 v84, 16, v85
	v_and_b32_e32 v85, 0xffff0000, v85
	v_lshlrev_b32_e32 v126, 16, v86
	v_and_b32_e32 v127, 0xffff0000, v86
	v_lshlrev_b32_e32 v86, 16, v87
	v_and_b32_e32 v87, 0xffff0000, v87
	v_pk_fma_f32 v[46:47], v[46:47], v[70:71], v[84:85]
	v_pk_fma_f32 v[44:45], v[44:45], v[68:69], v[60:61]
	v_pk_fma_f32 v[42:43], v[42:43], v[66:67], v[86:87]
	v_pk_fma_f32 v[60:61], v[40:41], v[64:65], v[126:127]
	v_cvt_pk_bf16_f32 v84, v44, v45
	v_cvt_pk_bf16_f32 v85, v46, v47
	v_lshl_add_u64 v[90:91], v[230:231], 0, v[112:113]
	v_cvt_pk_bf16_f32 v86, v60, v61
	v_cvt_pk_bf16_f32 v87, v42, v43
	global_store_dwordx4 v[188:189], v[84:87], off offset:256
	v_pk_mul_f32 v[40:41], v[114:115], v[46:47]
	v_pk_mul_f32 v[126:127], v[42:43], v[122:123]
	v_pk_mul_f32 v[84:85], v[120:121], v[44:45]
	v_pk_mul_f32 v[86:87], v[60:61], v[124:125]
	v_cvt_pk_bf16_f32 v84, v84, v85
	v_cvt_pk_bf16_f32 v85, v40, v41
	v_lshl_add_u64 v[40:41], v[90:91], 1, s[28:29]
	v_cvt_pk_bf16_f32 v86, v86, v87
	v_cvt_pk_bf16_f32 v87, v126, v127
	global_store_dwordx4 v[40:41], v[84:87], off
	v_lshlrev_b32_e32 v40, 16, v76
	v_and_b32_e32 v41, 0xffff0000, v76
	v_lshlrev_b32_e32 v76, 16, v77
	v_and_b32_e32 v77, 0xffff0000, v77
	v_lshlrev_b32_e32 v86, 16, v78
	v_and_b32_e32 v87, 0xffff0000, v78
	v_lshlrev_b32_e32 v78, 16, v79
	v_and_b32_e32 v79, 0xffff0000, v79
	v_pk_fma_f32 v[38:39], v[38:39], v[70:71], v[76:77]
	v_pk_fma_f32 v[36:37], v[36:37], v[68:69], v[40:41]
	v_pk_fma_f32 v[34:35], v[34:35], v[66:67], v[78:79]
	v_pk_fma_f32 v[40:41], v[32:33], v[64:65], v[86:87]
	v_cvt_pk_bf16_f32 v76, v36, v37
	v_cvt_pk_bf16_f32 v77, v38, v39
	v_lshl_add_u64 v[84:85], v[232:233], 0, v[112:113]
	v_cvt_pk_bf16_f32 v78, v40, v41
	v_cvt_pk_bf16_f32 v79, v34, v35
	global_store_dwordx4 v[186:187], v[76:79], off offset:256
	v_pk_mul_f32 v[32:33], v[114:115], v[38:39]
	v_pk_mul_f32 v[86:87], v[34:35], v[122:123]
	v_pk_mul_f32 v[76:77], v[120:121], v[36:37]
	v_pk_mul_f32 v[78:79], v[40:41], v[124:125]
	v_cvt_pk_bf16_f32 v76, v76, v77
	v_cvt_pk_bf16_f32 v77, v32, v33
	v_lshl_add_u64 v[32:33], v[84:85], 1, s[28:29]
	v_cvt_pk_bf16_f32 v78, v78, v79
	v_cvt_pk_bf16_f32 v79, v86, v87
	global_store_dwordx4 v[32:33], v[76:79], off
	v_lshlrev_b32_e32 v32, 16, v72
	v_and_b32_e32 v33, 0xffff0000, v72
	v_lshlrev_b32_e32 v72, 16, v73
	v_and_b32_e32 v73, 0xffff0000, v73
	v_lshlrev_b32_e32 v78, 16, v74
	v_and_b32_e32 v79, 0xffff0000, v74
	v_lshlrev_b32_e32 v74, 16, v75
	v_and_b32_e32 v75, 0xffff0000, v75
	v_pk_fma_f32 v[30:31], v[30:31], v[70:71], v[72:73]
	v_pk_fma_f32 v[28:29], v[28:29], v[68:69], v[32:33]
	v_pk_fma_f32 v[26:27], v[26:27], v[66:67], v[74:75]
	v_pk_fma_f32 v[32:33], v[24:25], v[64:65], v[78:79]
	v_cvt_pk_bf16_f32 v72, v28, v29
	v_cvt_pk_bf16_f32 v73, v30, v31
	v_lshl_add_u64 v[76:77], v[224:225], 0, v[112:113]
	v_cvt_pk_bf16_f32 v74, v32, v33
	v_cvt_pk_bf16_f32 v75, v26, v27
	global_store_dwordx4 v[184:185], v[72:75], off offset:256
	v_pk_mul_f32 v[24:25], v[114:115], v[30:31]
	v_pk_mul_f32 v[78:79], v[122:123], v[26:27]
	v_pk_mul_f32 v[72:73], v[120:121], v[28:29]
	v_pk_mul_f32 v[74:75], v[124:125], v[32:33]
	v_cvt_pk_bf16_f32 v72, v72, v73
	v_cvt_pk_bf16_f32 v73, v24, v25
	v_lshl_add_u64 v[24:25], v[76:77], 1, s[28:29]
	v_cvt_pk_bf16_f32 v74, v74, v75
	v_cvt_pk_bf16_f32 v75, v78, v79
	global_store_dwordx4 v[24:25], v[72:75], off
	s_waitcnt vmcnt(6)
	v_lshlrev_b32_e32 v76, 16, v82
	v_and_b32_e32 v77, 0xffff0000, v82
	v_lshlrev_b32_e32 v72, 16, v80
	v_and_b32_e32 v73, 0xffff0000, v80
	v_lshlrev_b32_e32 v74, 16, v81
	v_and_b32_e32 v75, 0xffff0000, v81
	v_lshlrev_b32_e32 v78, 16, v83
	v_and_b32_e32 v79, 0xffff0000, v83
	v_pk_fma_f32 v[22:23], v[22:23], v[70:71], v[74:75]
	v_pk_fma_f32 v[20:21], v[20:21], v[68:69], v[72:73]
	v_pk_fma_f32 v[18:19], v[18:19], v[66:67], v[78:79]
	v_pk_fma_f32 v[16:17], v[16:17], v[64:65], v[76:77]
	v_cvt_pk_bf16_f32 v72, v20, v21
	v_cvt_pk_bf16_f32 v73, v22, v23
	v_lshl_add_u64 v[24:25], v[226:227], 0, v[112:113]
	v_cvt_pk_bf16_f32 v74, v16, v17
	v_cvt_pk_bf16_f32 v75, v18, v19
	global_store_dwordx4 v[192:193], v[72:75], off offset:256
	v_pk_mul_f32 v[76:77], v[122:123], v[18:19]
	v_pk_mul_f32 v[78:79], v[124:125], v[16:17]
	v_pk_mul_f32 v[74:75], v[114:115], v[22:23]
	v_pk_mul_f32 v[72:73], v[120:121], v[20:21]
	v_lshl_add_u64 v[24:25], v[24:25], 1, s[28:29]
	v_cvt_pk_bf16_f32 v72, v72, v73
	v_cvt_pk_bf16_f32 v73, v74, v75
	v_cvt_pk_bf16_f32 v74, v78, v79
	v_cvt_pk_bf16_f32 v75, v76, v77
	global_store_dwordx4 v[24:25], v[72:75], off
	v_lshl_add_u64 v[24:25], v[148:149], 0, v[112:113]
	v_lshl_add_u64 v[24:25], v[24:25], 1, s[28:29]
	v_lshlrev_b32_e32 v72, 16, v56
	v_and_b32_e32 v73, 0xffff0000, v56
	v_lshlrev_b32_e32 v56, 16, v57
	v_and_b32_e32 v57, 0xffff0000, v57
	v_lshlrev_b32_e32 v74, 16, v58
	v_and_b32_e32 v75, 0xffff0000, v58
	v_lshlrev_b32_e32 v58, 16, v59
	v_and_b32_e32 v59, 0xffff0000, v59
	v_pk_fma_f32 v[14:15], v[14:15], v[70:71], v[56:57]
	v_pk_fma_f32 v[12:13], v[12:13], v[68:69], v[72:73]
	v_pk_fma_f32 v[10:11], v[10:11], v[66:67], v[58:59]
	v_pk_fma_f32 v[8:9], v[8:9], v[64:65], v[74:75]
	v_cvt_pk_bf16_f32 v56, v12, v13
	v_cvt_pk_bf16_f32 v57, v14, v15
	v_pk_mul_f32 v[72:73], v[122:123], v[10:11]
	v_cvt_pk_bf16_f32 v58, v8, v9
	v_cvt_pk_bf16_f32 v59, v10, v11
	global_store_dwordx4 v[212:213], v[56:59], off offset:256
	v_pk_mul_f32 v[74:75], v[124:125], v[8:9]
	s_nop 0
	v_pk_mul_f32 v[58:59], v[114:115], v[14:15]
	v_pk_mul_f32 v[56:57], v[120:121], v[12:13]
	s_nop 0
	v_cvt_pk_bf16_f32 v56, v56, v57
	v_cvt_pk_bf16_f32 v57, v58, v59
	v_cvt_pk_bf16_f32 v58, v74, v75
	v_cvt_pk_bf16_f32 v59, v72, v73
	global_store_dwordx4 v[24:25], v[56:59], off
	v_lshl_add_u64 v[24:25], v[128:129], 0, v[112:113]
	v_lshl_add_u64 v[24:25], v[24:25], 1, s[28:29]
	v_lshlrev_b32_e32 v56, 16, v48
	v_and_b32_e32 v57, 0xffff0000, v48
	v_lshlrev_b32_e32 v48, 16, v49
	v_and_b32_e32 v49, 0xffff0000, v49
	v_lshlrev_b32_e32 v58, 16, v50
	v_and_b32_e32 v59, 0xffff0000, v50
	v_lshlrev_b32_e32 v50, 16, v51
	v_and_b32_e32 v51, 0xffff0000, v51
	v_pk_fma_f32 v[6:7], v[6:7], v[70:71], v[48:49]
	v_pk_fma_f32 v[4:5], v[4:5], v[68:69], v[56:57]
	v_pk_fma_f32 v[2:3], v[2:3], v[66:67], v[50:51]
	v_pk_fma_f32 v[0:1], v[0:1], v[64:65], v[58:59]
	v_cvt_pk_bf16_f32 v48, v4, v5
	v_cvt_pk_bf16_f32 v49, v6, v7
	v_pk_mul_f32 v[56:57], v[122:123], v[2:3]
	v_cvt_pk_bf16_f32 v50, v0, v1
	v_cvt_pk_bf16_f32 v51, v2, v3
	global_store_dwordx4 v[214:215], v[48:51], off offset:256
	v_pk_mul_f32 v[58:59], v[124:125], v[0:1]
	s_nop 0
	v_pk_mul_f32 v[50:51], v[114:115], v[6:7]
	v_pk_mul_f32 v[48:49], v[120:121], v[4:5]
	s_nop 0
	v_cvt_pk_bf16_f32 v48, v48, v49
	v_cvt_pk_bf16_f32 v49, v50, v51
	v_cvt_pk_bf16_f32 v50, v58, v59
	v_cvt_pk_bf16_f32 v51, v56, v57
	global_store_dwordx4 v[24:25], v[48:51], off
	v_mov_b32_e32 v24, v163
	s_nop 0
	v_lshlrev_b32_e32 v24, 2, v24
	v_bitop3_b32 v24, v24, 64, v248 bitop3:0x6c
	ds_bpermute_b32 v24, v24, v164
	s_waitcnt lgkmcnt(0)
	v_add_f32_e32 v48, v164, v24
	v_mov_b32_e32 v24, v163
	s_nop 0
	v_lshlrev_b32_e32 v24, 2, v24
	v_bitop3_b32 v24, v24, s46, v248 bitop3:0x6c
	ds_bpermute_b32 v49, v24, v48
	v_lshl_add_u64 v[24:25], v[182:183], 3, s[8:9]
	s_and_saveexec_b64 s[8:9], s[2:3]
	s_cbranch_execz .LBB0_320
	s_waitcnt lgkmcnt(0)
	v_add_f32_e32 v48, v48, v49
	v_mul_f32_e32 v48, 0x47800000, v48
	v_rndne_f32_e32 v48, v48
	s_mov_b32 s1, 0x2f800000
	v_mul_f32_e64 v49, |v48|, s1
	v_floor_f32_e32 v49, v49
	s_mov_b32 s1, 0xcf800000
	v_fma_f32 v50, v49, s1, |v48|
	v_cvt_u32_f32_e32 v50, v50
	v_cvt_u32_f32_e32 v49, v49
	v_ashrrev_i32_e32 v51, 31, v48
	v_xor_b32_e32 v48, v50, v51
	v_xor_b32_e32 v49, v49, v51
	v_sub_co_u32_e32 v48, vcc, v48, v51
	s_nop 1
	v_subb_co_u32_e32 v49, vcc, v49, v51, vcc
	global_atomic_add_x2 v[24:25], v[48:49], off

.LBB0_350:
	s_add_u32 s8, s60, 0xfffc0080
	s_addc_u32 s9, s61, -1
	s_add_i32 s16, 0, 0x10000
	v_add_u32_e32 v150, s16, v168
	ds_read_b128 v[128:131], v150
	ds_read_b128 v[132:135], v150 offset:1024
	ds_read_b128 v[146:149], v150 offset:2048
	ds_read_b128 v[150:153], v150 offset:3072
	s_cmp_eq_u32 s15, 12
	s_cselect_b32 s9, s5, s9
	s_cselect_b32 s8, s10, s8
	s_cselect_b32 s63, s1, s14
	s_cselect_b32 s62, s12, s13
	v_lshl_add_u64 v[200:201], s[60:61], 0, v[142:143]
	s_add_i32 m0, s38, 0xc000
	ds_read_b128 v[154:157], v170
	ds_read_b128 v[172:175], v170 offset:1024
	ds_read_b128 v[176:179], v170 offset:2048
	ds_read_b128 v[180:183], v170 offset:3072
	ds_read_b128 v[184:187], v170 offset:4096
	ds_read_b128 v[188:191], v170 offset:5120
	ds_read_b128 v[192:195], v170 offset:6144
	ds_read_b128 v[196:199], v170 offset:7168
	global_load_lds_dwordx4 v[200:201], off
	v_lshl_add_u64 v[200:201], s[60:61], 0, v[144:145]
	s_add_i32 m0, s38, 0xe000
	s_nop 0
	global_load_lds_dwordx4 v[200:201], off
	s_waitcnt lgkmcnt(8)
	s_barrier
	s_waitcnt lgkmcnt(0)
	s_setprio 1
	s_waitcnt lgkmcnt(0)
	v_mfma_f32_16x16x32_bf16 v[124:127], v[128:131], v[154:157], v[124:127]
	v_mfma_f32_16x16x32_bf16 v[120:123], v[146:149], v[154:157], v[120:123]
	v_mfma_f32_16x16x32_bf16 v[116:119], v[128:131], v[176:179], v[116:119]
	v_mfma_f32_16x16x32_bf16 v[112:115], v[146:149], v[176:179], v[112:115]
	v_mfma_f32_16x16x32_bf16 v[108:111], v[128:131], v[184:187], v[108:111]
	v_mfma_f32_16x16x32_bf16 v[104:107], v[146:149], v[184:187], v[104:107]
	v_mfma_f32_16x16x32_bf16 v[100:103], v[128:131], v[192:195], v[100:103]
	v_mfma_f32_16x16x32_bf16 v[96:99], v[146:149], v[192:195], v[96:99]
	v_mfma_f32_16x16x32_bf16 v[124:127], v[132:135], v[172:175], v[124:127]
	v_mfma_f32_16x16x32_bf16 v[120:123], v[150:153], v[172:175], v[120:123]
	v_mfma_f32_16x16x32_bf16 v[116:119], v[132:135], v[180:183], v[116:119]
	v_mfma_f32_16x16x32_bf16 v[112:115], v[150:153], v[180:183], v[112:115]
	v_mfma_f32_16x16x32_bf16 v[108:111], v[132:135], v[188:191], v[108:111]
	v_mfma_f32_16x16x32_bf16 v[104:107], v[150:153], v[188:191], v[104:107]
	v_mfma_f32_16x16x32_bf16 v[100:103], v[132:135], v[196:199], v[100:103]
	v_mfma_f32_16x16x32_bf16 v[96:99], v[150:153], v[196:199], v[96:99]
	s_setprio 0
	s_barrier
	s_add_i32 s18, 0, 0x14000
	s_add_i32 s16, s16, s37
	v_add_u32_e32 v158, s18, v168
	v_lshl_add_u64 v[216:217], s[62:63], 0, v[160:161]
	s_mov_b32 m0, s16
	ds_read_b128 v[200:203], v158
	ds_read_b128 v[204:207], v158 offset:1024
	ds_read_b128 v[208:211], v158 offset:2048
	ds_read_b128 v[212:215], v158 offset:3072
	global_load_lds_dwordx4 v[216:217], off
	v_lshl_add_u64 v[218:219], s[62:63], 0, v[136:137]
	s_add_i32 m0, s16, 0x2000
	s_nop 0
	global_load_lds_dwordx4 v[218:219], off
	s_barrier
	s_waitcnt lgkmcnt(0)
	s_setprio 1
	s_waitcnt lgkmcnt(0)
	v_mfma_f32_16x16x32_bf16 v[68:71], v[200:203], v[154:157], v[68:71]
	v_mfma_f32_16x16x32_bf16 v[64:67], v[208:211], v[154:157], v[64:67]
	v_mfma_f32_16x16x32_bf16 v[52:55], v[200:203], v[176:179], v[52:55]
	v_mfma_f32_16x16x32_bf16 v[48:51], v[208:211], v[176:179], v[48:51]
	v_mfma_f32_16x16x32_bf16 v[44:47], v[200:203], v[184:187], v[44:47]
	v_mfma_f32_16x16x32_bf16 v[40:43], v[208:211], v[184:187], v[40:43]
	v_mfma_f32_16x16x32_bf16 v[36:39], v[200:203], v[192:195], v[36:39]
	v_mfma_f32_16x16x32_bf16 v[32:35], v[208:211], v[192:195], v[32:35]
	v_mfma_f32_16x16x32_bf16 v[68:71], v[204:207], v[172:175], v[68:71]
	v_mfma_f32_16x16x32_bf16 v[64:67], v[212:215], v[172:175], v[64:67]
	v_mfma_f32_16x16x32_bf16 v[52:55], v[204:207], v[180:183], v[52:55]
	v_mfma_f32_16x16x32_bf16 v[48:51], v[212:215], v[180:183], v[48:51]
	v_mfma_f32_16x16x32_bf16 v[44:47], v[204:207], v[188:191], v[44:47]
	v_mfma_f32_16x16x32_bf16 v[40:43], v[212:215], v[188:191], v[40:43]
	v_mfma_f32_16x16x32_bf16 v[36:39], v[204:207], v[196:199], v[36:39]
	v_mfma_f32_16x16x32_bf16 v[32:35], v[212:215], v[196:199], v[32:35]
	s_setprio 0
	s_mov_b32 m0, s38
	v_lshl_add_u64 v[220:221], s[8:9], 0, v[140:141]
	s_barrier
	ds_read_b128 v[154:157], v170 offset:16384
	ds_read_b128 v[172:175], v170 offset:17408
	ds_read_b128 v[176:179], v170 offset:18432
	ds_read_b128 v[180:183], v170 offset:19456
	ds_read_b128 v[184:187], v170 offset:20480
	ds_read_b128 v[188:191], v170 offset:21504
	ds_read_b128 v[192:195], v170 offset:22528
	ds_read_b128 v[196:199], v170 offset:23552
	global_load_lds_dwordx4 v[220:221], off
	v_lshl_add_u64 v[222:223], s[8:9], 0, v[138:139]
	s_mov_b32 m0, s39
	s_nop 0
	global_load_lds_dwordx4 v[222:223], off
	s_barrier
	s_waitcnt lgkmcnt(0)
	s_setprio 1
	s_waitcnt lgkmcnt(0)
	v_mfma_f32_16x16x32_bf16 v[92:95], v[128:131], v[154:157], v[92:95]
	v_mfma_f32_16x16x32_bf16 v[88:91], v[146:149], v[154:157], v[88:91]
	v_mfma_f32_16x16x32_bf16 v[84:87], v[128:131], v[176:179], v[84:87]
	v_mfma_f32_16x16x32_bf16 v[80:83], v[146:149], v[176:179], v[80:83]
	v_mfma_f32_16x16x32_bf16 v[76:79], v[128:131], v[184:187], v[76:79]
	v_mfma_f32_16x16x32_bf16 v[72:75], v[146:149], v[184:187], v[72:75]
	v_mfma_f32_16x16x32_bf16 v[60:63], v[128:131], v[192:195], v[60:63]
	v_mfma_f32_16x16x32_bf16 v[56:59], v[146:149], v[192:195], v[56:59]
	v_mfma_f32_16x16x32_bf16 v[92:95], v[132:135], v[172:175], v[92:95]
	v_mfma_f32_16x16x32_bf16 v[88:91], v[150:153], v[172:175], v[88:91]
	v_mfma_f32_16x16x32_bf16 v[84:87], v[132:135], v[180:183], v[84:87]
	v_mfma_f32_16x16x32_bf16 v[80:83], v[150:153], v[180:183], v[80:83]
	v_mfma_f32_16x16x32_bf16 v[76:79], v[132:135], v[188:191], v[76:79]
	v_mfma_f32_16x16x32_bf16 v[72:75], v[150:153], v[188:191], v[72:75]
	v_mfma_f32_16x16x32_bf16 v[60:63], v[132:135], v[196:199], v[60:63]
	v_mfma_f32_16x16x32_bf16 v[56:59], v[150:153], v[196:199], v[56:59]
	s_setprio 0
	s_barrier
	s_add_u32 s16, s62, 0x40000
	s_addc_u32 s17, s63, 0
	s_add_i32 s18, s18, s37
	v_lshl_add_u64 v[128:129], s[16:17], 0, v[160:161]
	s_mov_b32 m0, s18
	s_nop 0
	global_load_lds_dwordx4 v[128:129], off
	v_lshl_add_u64 v[128:129], s[16:17], 0, v[136:137]
	s_add_i32 m0, s18, 0x2000
	s_nop 0
	global_load_lds_dwordx4 v[128:129], off
	s_waitcnt vmcnt(6)
	s_barrier
	s_setprio 1
	v_mfma_f32_16x16x32_bf16 v[28:31], v[200:203], v[154:157], v[28:31]
	v_mfma_f32_16x16x32_bf16 v[24:27], v[208:211], v[154:157], v[24:27]
	v_mfma_f32_16x16x32_bf16 v[20:23], v[200:203], v[176:179], v[20:23]
	v_mfma_f32_16x16x32_bf16 v[16:19], v[208:211], v[176:179], v[16:19]
	v_mfma_f32_16x16x32_bf16 v[12:15], v[200:203], v[184:187], v[12:15]
	v_mfma_f32_16x16x32_bf16 v[8:11], v[208:211], v[184:187], v[8:11]
	v_mfma_f32_16x16x32_bf16 v[4:7], v[200:203], v[192:195], v[4:7]
	v_mfma_f32_16x16x32_bf16 v[0:3], v[208:211], v[192:195], v[0:3]
	v_mfma_f32_16x16x32_bf16 v[28:31], v[204:207], v[172:175], v[28:31]
	v_mfma_f32_16x16x32_bf16 v[24:27], v[212:215], v[172:175], v[24:27]
	v_mfma_f32_16x16x32_bf16 v[20:23], v[204:207], v[180:183], v[20:23]
	v_mfma_f32_16x16x32_bf16 v[16:19], v[212:215], v[180:183], v[16:19]
	v_mfma_f32_16x16x32_bf16 v[12:15], v[204:207], v[188:191], v[12:15]
	v_mfma_f32_16x16x32_bf16 v[8:11], v[212:215], v[188:191], v[8:11]
	v_mfma_f32_16x16x32_bf16 v[4:7], v[204:207], v[196:199], v[4:7]
	v_mfma_f32_16x16x32_bf16 v[0:3], v[212:215], v[196:199], v[0:3]
	s_setprio 0
	s_add_i32 s16, 0, 0x18000
	v_add_u32_e32 v150, s16, v168
	s_barrier
	ds_read_b128 v[128:131], v150
	ds_read_b128 v[132:135], v150 offset:1024
	ds_read_b128 v[146:149], v150 offset:2048
	ds_read_b128 v[150:153], v150 offset:3072
	s_add_u32 s8, s8, 0x40000
	s_addc_u32 s9, s9, 0
	s_mov_b32 m0, s40
	v_lshl_add_u64 v[200:201], s[8:9], 0, v[140:141]
	ds_read_b128 v[154:157], v170 offset:32768
	ds_read_b128 v[172:175], v170 offset:33792
	ds_read_b128 v[176:179], v170 offset:34816
	ds_read_b128 v[180:183], v170 offset:35840
	ds_read_b128 v[184:187], v170 offset:36864
	ds_read_b128 v[188:191], v170 offset:37888
	ds_read_b128 v[192:195], v170 offset:38912
	ds_read_b128 v[196:199], v170 offset:39936
	global_load_lds_dwordx4 v[200:201], off
	v_lshl_add_u64 v[200:201], s[8:9], 0, v[138:139]
	s_mov_b32 m0, s41
	s_nop 0
	global_load_lds_dwordx4 v[200:201], off
	s_waitcnt lgkmcnt(8)
	s_barrier
	s_waitcnt lgkmcnt(0)
	s_setprio 1
	s_waitcnt lgkmcnt(0)
	v_mfma_f32_16x16x32_bf16 v[124:127], v[128:131], v[154:157], v[124:127]
	v_mfma_f32_16x16x32_bf16 v[120:123], v[146:149], v[154:157], v[120:123]
	v_mfma_f32_16x16x32_bf16 v[116:119], v[128:131], v[176:179], v[116:119]
	v_mfma_f32_16x16x32_bf16 v[112:115], v[146:149], v[176:179], v[112:115]
	v_mfma_f32_16x16x32_bf16 v[108:111], v[128:131], v[184:187], v[108:111]
	v_mfma_f32_16x16x32_bf16 v[104:107], v[146:149], v[184:187], v[104:107]
	v_mfma_f32_16x16x32_bf16 v[100:103], v[128:131], v[192:195], v[100:103]
	v_mfma_f32_16x16x32_bf16 v[96:99], v[146:149], v[192:195], v[96:99]
	v_mfma_f32_16x16x32_bf16 v[124:127], v[132:135], v[172:175], v[124:127]
	v_mfma_f32_16x16x32_bf16 v[120:123], v[150:153], v[172:175], v[120:123]
	v_mfma_f32_16x16x32_bf16 v[116:119], v[132:135], v[180:183], v[116:119]
	v_mfma_f32_16x16x32_bf16 v[112:115], v[150:153], v[180:183], v[112:115]
	v_mfma_f32_16x16x32_bf16 v[108:111], v[132:135], v[188:191], v[108:111]
	v_mfma_f32_16x16x32_bf16 v[104:107], v[150:153], v[188:191], v[104:107]
	v_mfma_f32_16x16x32_bf16 v[100:103], v[132:135], v[196:199], v[100:103]
	v_mfma_f32_16x16x32_bf16 v[96:99], v[150:153], v[196:199], v[96:99]
	s_setprio 0
	s_barrier
	s_add_i32 s17, 0, 0x1c000
	s_add_i32 s8, s16, s37
	v_add_u32_e32 v158, s17, v168
	v_lshl_add_u64 v[216:217], v[216:217], 0, s[74:75]
	s_mov_b32 m0, s8
	ds_read_b128 v[200:203], v158
	ds_read_b128 v[204:207], v158 offset:1024
	ds_read_b128 v[208:211], v158 offset:2048
	ds_read_b128 v[212:215], v158 offset:3072
	global_load_lds_dwordx4 v[216:217], off
	v_lshl_add_u64 v[216:217], v[218:219], 0, s[74:75]
	s_add_i32 m0, s8, 0x2000
	s_nop 0
	global_load_lds_dwordx4 v[216:217], off
	s_barrier
	s_waitcnt lgkmcnt(0)
	s_setprio 1
	s_waitcnt lgkmcnt(0)
	v_mfma_f32_16x16x32_bf16 v[68:71], v[200:203], v[154:157], v[68:71]
	v_mfma_f32_16x16x32_bf16 v[64:67], v[208:211], v[154:157], v[64:67]
	v_mfma_f32_16x16x32_bf16 v[52:55], v[200:203], v[176:179], v[52:55]
	v_mfma_f32_16x16x32_bf16 v[48:51], v[208:211], v[176:179], v[48:51]
	v_mfma_f32_16x16x32_bf16 v[44:47], v[200:203], v[184:187], v[44:47]
	v_mfma_f32_16x16x32_bf16 v[40:43], v[208:211], v[184:187], v[40:43]
	v_mfma_f32_16x16x32_bf16 v[36:39], v[200:203], v[192:195], v[36:39]
	v_mfma_f32_16x16x32_bf16 v[32:35], v[208:211], v[192:195], v[32:35]
	v_mfma_f32_16x16x32_bf16 v[68:71], v[204:207], v[172:175], v[68:71]
	v_mfma_f32_16x16x32_bf16 v[64:67], v[212:215], v[172:175], v[64:67]
	v_mfma_f32_16x16x32_bf16 v[52:55], v[204:207], v[180:183], v[52:55]
	v_mfma_f32_16x16x32_bf16 v[48:51], v[212:215], v[180:183], v[48:51]
	v_mfma_f32_16x16x32_bf16 v[44:47], v[204:207], v[188:191], v[44:47]
	v_mfma_f32_16x16x32_bf16 v[40:43], v[212:215], v[188:191], v[40:43]
	v_mfma_f32_16x16x32_bf16 v[36:39], v[204:207], v[196:199], v[36:39]
	v_mfma_f32_16x16x32_bf16 v[32:35], v[212:215], v[196:199], v[32:35]
	s_setprio 0
	s_mov_b32 m0, s42
	v_lshl_add_u64 v[216:217], v[220:221], 0, s[74:75]
	s_barrier
	ds_read_b128 v[154:157], v170 offset:49152
	ds_read_b128 v[172:175], v170 offset:50176
	ds_read_b128 v[176:179], v170 offset:51200
	ds_read_b128 v[180:183], v170 offset:52224
	ds_read_b128 v[184:187], v170 offset:53248
	ds_read_b128 v[188:191], v170 offset:54272
	ds_read_b128 v[192:195], v170 offset:55296
	ds_read_b128 v[196:199], v170 offset:56320
	global_load_lds_dwordx4 v[216:217], off
	v_lshl_add_u64 v[216:217], v[222:223], 0, s[74:75]
	s_mov_b32 m0, s43
	s_nop 0
	global_load_lds_dwordx4 v[216:217], off
	s_barrier
	s_waitcnt lgkmcnt(0)
	s_setprio 1
	s_waitcnt lgkmcnt(0)
	v_mfma_f32_16x16x32_bf16 v[92:95], v[128:131], v[154:157], v[92:95]
	v_mfma_f32_16x16x32_bf16 v[88:91], v[146:149], v[154:157], v[88:91]
	v_mfma_f32_16x16x32_bf16 v[84:87], v[128:131], v[176:179], v[84:87]
	v_mfma_f32_16x16x32_bf16 v[80:83], v[146:149], v[176:179], v[80:83]
	v_mfma_f32_16x16x32_bf16 v[76:79], v[128:131], v[184:187], v[76:79]
	v_mfma_f32_16x16x32_bf16 v[72:75], v[146:149], v[184:187], v[72:75]
	v_mfma_f32_16x16x32_bf16 v[60:63], v[128:131], v[192:195], v[60:63]
	v_mfma_f32_16x16x32_bf16 v[56:59], v[146:149], v[192:195], v[56:59]
	v_mfma_f32_16x16x32_bf16 v[92:95], v[132:135], v[172:175], v[92:95]
	v_mfma_f32_16x16x32_bf16 v[88:91], v[150:153], v[172:175], v[88:91]
	v_mfma_f32_16x16x32_bf16 v[84:87], v[132:135], v[180:183], v[84:87]
	v_mfma_f32_16x16x32_bf16 v[80:83], v[150:153], v[180:183], v[80:83]
	v_mfma_f32_16x16x32_bf16 v[76:79], v[132:135], v[188:191], v[76:79]
	v_mfma_f32_16x16x32_bf16 v[72:75], v[150:153], v[188:191], v[72:75]
	v_mfma_f32_16x16x32_bf16 v[60:63], v[132:135], v[196:199], v[60:63]
	v_mfma_f32_16x16x32_bf16 v[56:59], v[150:153], v[196:199], v[56:59]
	s_setprio 0
	s_barrier
	s_add_u32 s8, s62, 0x40080
	s_addc_u32 s9, s63, 0
	s_add_i32 s16, s17, s37
	v_lshl_add_u64 v[128:129], s[8:9], 0, v[160:161]
	s_mov_b32 m0, s16
	s_nop 0
	global_load_lds_dwordx4 v[128:129], off
	v_lshl_add_u64 v[128:129], s[8:9], 0, v[136:137]
	s_add_i32 m0, s16, 0x2000
	s_nop 0
	global_load_lds_dwordx4 v[128:129], off
	s_waitcnt vmcnt(6)
	s_barrier
	s_setprio 1
	v_mfma_f32_16x16x32_bf16 v[28:31], v[200:203], v[154:157], v[28:31]
	v_mfma_f32_16x16x32_bf16 v[24:27], v[208:211], v[154:157], v[24:27]
	v_mfma_f32_16x16x32_bf16 v[20:23], v[200:203], v[176:179], v[20:23]
	v_mfma_f32_16x16x32_bf16 v[16:19], v[208:211], v[176:179], v[16:19]
	v_mfma_f32_16x16x32_bf16 v[12:15], v[200:203], v[184:187], v[12:15]
	v_mfma_f32_16x16x32_bf16 v[8:11], v[208:211], v[184:187], v[8:11]
	v_mfma_f32_16x16x32_bf16 v[4:7], v[200:203], v[192:195], v[4:7]
	v_mfma_f32_16x16x32_bf16 v[0:3], v[208:211], v[192:195], v[0:3]
	v_mfma_f32_16x16x32_bf16 v[28:31], v[204:207], v[172:175], v[28:31]
	v_mfma_f32_16x16x32_bf16 v[24:27], v[212:215], v[172:175], v[24:27]
	v_mfma_f32_16x16x32_bf16 v[20:23], v[204:207], v[180:183], v[20:23]
	v_mfma_f32_16x16x32_bf16 v[16:19], v[212:215], v[180:183], v[16:19]
	v_mfma_f32_16x16x32_bf16 v[12:15], v[204:207], v[188:191], v[12:15]
	v_mfma_f32_16x16x32_bf16 v[8:11], v[212:215], v[188:191], v[8:11]
	v_mfma_f32_16x16x32_bf16 v[4:7], v[204:207], v[196:199], v[4:7]
	v_mfma_f32_16x16x32_bf16 v[0:3], v[212:215], v[196:199], v[0:3]
	s_setprio 0
	s_add_i32 s15, s15, 2
	s_add_u32 s60, s60, 0x100
	s_addc_u32 s61, s61, 0
	s_add_u32 s13, s13, 0x100
	s_addc_u32 s14, s14, 0
	s_cmp_gt_u32 s15, 13
	s_barrier
	s_cbranch_scc0 .LBB0_350
	v_lshl_add_u32 v146, s65, 8, v159
	v_readlane_b32 s8, v249, 24
	v_ashrrev_i32_e32 v147, 31, v146
	v_readlane_b32 s9, v249, 25
	v_readlane_b32 s12, v249, 26
	v_lshl_or_b32 v156, s66, 8, v169
	v_lshl_add_u64 v[128:129], v[146:147], 3, s[8:9]
	global_load_dwordx2 v[130:131], v[128:129], off
	s_ashr_i32 s8, s65, 5
	s_ashr_i32 s9, s8, 31
	s_lshl_b64 s[8:9], s[8:9], 14
	v_readlane_b32 s13, v249, 27
	s_add_u32 s8, s12, s8
	v_ashrrev_i32_e32 v157, 31, v156
	s_addc_u32 s9, s13, s9
	v_lshl_add_u64 v[180:181], v[156:157], 2, s[8:9]
	v_readlane_b32 s8, v253, 29
	v_readlane_b32 s9, v253, 30
	s_mov_b32 s1, 0x100000
	s_mov_b32 s66, s0
	s_mov_b32 s65, s4
	s_mov_b64 s[20:21], s[6:7]
	v_readlane_b32 s62, v255, 4
	v_readlane_b32 s63, v255, 5
	s_waitcnt vmcnt(0)
	v_ffbh_u32_e32 v132, v131
	v_min_u32_e32 v132, 32, v132
	v_lshlrev_b64 v[130:131], v132, v[130:131]
	v_min_u32_e32 v130, 1, v130
	v_or_b32_e32 v130, v131, v130
	v_cvt_f32_u32_e32 v130, v130
	v_sub_u32_e32 v131, 32, v132
	v_ldexp_f32 v130, v130, v131
	v_mul_f32_e32 v130, 0x37800000, v130
	v_fmamk_f32 v158, v130, 0x3a800000, v240
	global_load_dwordx2 v[130:131], v[128:129], off offset:128
	v_cmp_gt_f32_e32 vcc, s53, v158
	v_mul_f32_e32 v164, 0x4b800000, v158
	s_waitcnt vmcnt(0)
	v_ffbh_u32_e32 v132, v131
	v_min_u32_e32 v132, 32, v132
	v_lshlrev_b64 v[130:131], v132, v[130:131]
	v_min_u32_e32 v130, 1, v130
	v_or_b32_e32 v130, v131, v130
	v_cvt_f32_u32_e32 v130, v130
	v_sub_u32_e32 v131, 32, v132
	v_cndmask_b32_e32 v158, v158, v164, vcc
	v_rsq_f32_e32 v158, v158
	v_ldexp_f32 v130, v130, v131
	v_mul_f32_e32 v130, 0x37800000, v130
	v_fmamk_f32 v171, v130, 0x3a800000, v240
	global_load_dwordx2 v[130:131], v[128:129], off offset:256
	v_mul_f32_e32 v164, 0x45800000, v158
	v_cndmask_b32_e32 v184, v158, v164, vcc
	v_cmp_gt_f32_e32 vcc, s53, v171
	v_mul_f32_e32 v158, 0x4b800000, v171
	s_waitcnt vmcnt(0)
	v_ffbh_u32_e32 v132, v131
	v_min_u32_e32 v132, 32, v132
	v_lshlrev_b64 v[130:131], v132, v[130:131]
	v_min_u32_e32 v130, 1, v130
	v_or_b32_e32 v130, v131, v130
	v_cvt_f32_u32_e32 v130, v130
	v_sub_u32_e32 v131, 32, v132
	v_cndmask_b32_e32 v158, v171, v158, vcc
	v_rsq_f32_e32 v158, v158
	v_ldexp_f32 v130, v130, v131
	v_mul_f32_e32 v130, 0x37800000, v130
	v_fmamk_f32 v172, v130, 0x3a800000, v240
	global_load_dwordx2 v[130:131], v[128:129], off offset:384
	v_mul_f32_e32 v164, 0x45800000, v158
	v_cndmask_b32_e32 v182, v158, v164, vcc
	v_cmp_gt_f32_e32 vcc, s53, v172
	v_mul_f32_e32 v158, 0x4b800000, v172
	s_waitcnt vmcnt(0)
	v_ffbh_u32_e32 v132, v131
	v_min_u32_e32 v132, 32, v132
	v_lshlrev_b64 v[130:131], v132, v[130:131]
	v_min_u32_e32 v130, 1, v130
	v_or_b32_e32 v130, v131, v130
	v_cvt_f32_u32_e32 v130, v130
	v_sub_u32_e32 v131, 32, v132
	v_cndmask_b32_e32 v158, v172, v158, vcc
	v_rsq_f32_e32 v158, v158
	v_ldexp_f32 v130, v130, v131
	v_mul_f32_e32 v130, 0x37800000, v130
	v_fmamk_f32 v173, v130, 0x3a800000, v240
	global_load_dwordx2 v[130:131], v[128:129], off offset:1024
	v_mul_f32_e32 v164, 0x45800000, v158
	s_waitcnt vmcnt(0)
	v_ffbh_u32_e32 v132, v131
	v_min_u32_e32 v132, 32, v132
	v_lshlrev_b64 v[130:131], v132, v[130:131]
	v_min_u32_e32 v130, 1, v130
	v_or_b32_e32 v130, v131, v130
	v_cvt_f32_u32_e32 v130, v130
	v_sub_u32_e32 v131, 32, v132
	v_ldexp_f32 v130, v130, v131
	v_mul_f32_e32 v130, 0x37800000, v130
	v_fmamk_f32 v174, v130, 0x3a800000, v240
	global_load_dwordx2 v[130:131], v[128:129], off offset:1152
	s_waitcnt vmcnt(0)
	v_ffbh_u32_e32 v132, v131
	v_min_u32_e32 v132, 32, v132
	v_lshlrev_b64 v[130:131], v132, v[130:131]
	v_min_u32_e32 v130, 1, v130
	v_or_b32_e32 v130, v131, v130
	v_cvt_f32_u32_e32 v130, v130
	v_sub_u32_e32 v131, 32, v132
	v_ldexp_f32 v130, v130, v131
	v_mul_f32_e32 v130, 0x37800000, v130
	v_fmamk_f32 v175, v130, 0x3a800000, v240
	global_load_dwordx2 v[130:131], v[128:129], off offset:1280
	s_waitcnt vmcnt(0)
	v_ffbh_u32_e32 v132, v131
	global_load_dwordx2 v[128:129], v[128:129], off offset:1408
	v_min_u32_e32 v132, 32, v132
	v_lshlrev_b64 v[130:131], v132, v[130:131]
	v_min_u32_e32 v130, 1, v130
	v_or_b32_e32 v130, v131, v130
	v_cvt_f32_u32_e32 v130, v130
	v_sub_u32_e32 v131, 32, v132
	v_ldexp_f32 v130, v130, v131
	v_mul_f32_e32 v130, 0x37800000, v130
	v_fmamk_f32 v177, v130, 0x3a800000, v240
	s_waitcnt vmcnt(0)
	v_ffbh_u32_e32 v130, v129
	v_min_u32_e32 v130, 32, v130
	v_lshlrev_b64 v[128:129], v130, v[128:129]
	v_min_u32_e32 v128, 1, v128
	v_or_b32_e32 v128, v129, v128
	v_cvt_f32_u32_e32 v128, v128
	v_sub_u32_e32 v129, 32, v130
	v_ldexp_f32 v128, v128, v129
	v_mul_f32_e32 v128, 0x37800000, v128
	v_fmamk_f32 v179, v128, 0x3a800000, v240
	global_load_dwordx4 v[128:131], v[180:181], off offset:16
	global_load_dwordx4 v[132:135], v[180:181], off
	s_waitcnt vmcnt(0)
	v_pk_add_f32 v[148:149], v[130:131], 0 op_sel_hi:[1,0]
	v_pk_add_f32 v[152:153], v[134:135], 0 op_sel_hi:[1,0]
	v_pk_add_f32 v[154:155], v[132:133], 0 op_sel_hi:[1,0]
	v_pk_add_f32 v[150:151], v[128:129], 0 op_sel_hi:[1,0]
	global_load_dwordx4 v[128:131], v[180:181], off offset:528
	global_load_dwordx4 v[132:135], v[180:181], off offset:512
	v_cndmask_b32_e32 v180, v158, v164, vcc
	v_cmp_gt_f32_e32 vcc, s53, v173
	v_mul_f32_e32 v158, 0x4b800000, v173
	v_pk_fma_f32 v[122:123], v[122:123], v[184:185], v[148:149] op_sel_hi:[1,0,1]
	v_cndmask_b32_e32 v158, v173, v158, vcc
	v_rsq_f32_e32 v158, v158
	v_pk_fma_f32 v[126:127], v[126:127], v[184:185], v[152:153] op_sel_hi:[1,0,1]
	v_pk_fma_f32 v[124:125], v[124:125], v[184:185], v[154:155] op_sel_hi:[1,0,1]
	v_pk_fma_f32 v[120:121], v[120:121], v[184:185], v[150:151] op_sel_hi:[1,0,1]
	v_mul_f32_e32 v164, 0x45800000, v158
	v_cndmask_b32_e32 v178, v158, v164, vcc
	v_cmp_gt_f32_e32 vcc, s53, v174
	v_mul_f32_e32 v158, 0x4b800000, v174
	v_max_f32_e32 v122, 0, v122
	v_cndmask_b32_e32 v158, v174, v158, vcc
	v_rsq_f32_e32 v158, v158
	v_max_f32_e32 v124, 0, v124
	v_max_f32_e32 v120, 0, v120
	v_max_f32_e32 v121, 0, v121
	v_mul_f32_e32 v164, 0x45800000, v158
	v_cndmask_b32_e32 v176, v158, v164, vcc
	v_cmp_gt_f32_e32 vcc, s53, v175
	v_mul_f32_e32 v158, 0x4b800000, v175
	v_mul_f32_e32 v124, v124, v124
	v_cndmask_b32_e32 v158, v175, v158, vcc
	v_rsq_f32_e32 v158, v158
	v_mul_f32_e32 v120, v120, v120
	v_max_f32_e32 v125, 0, v125
	v_mul_f32_e32 v121, v121, v121
	v_mul_f32_e32 v164, 0x45800000, v158
	v_cndmask_b32_e32 v174, v158, v164, vcc
	v_cmp_gt_f32_e32 vcc, s53, v177
	v_mul_f32_e32 v158, 0x4b800000, v177
	v_max_f32_e32 v126, 0, v126
	v_cndmask_b32_e32 v158, v177, v158, vcc
	v_rsq_f32_e32 v158, v158
	v_mul_f32_e32 v125, v125, v125
	v_mul_f32_e32 v126, v126, v126
	v_pk_fma_f32 v[114:115], v[114:115], v[182:183], v[148:149] op_sel_hi:[1,0,1]
	v_mul_f32_e32 v164, 0x45800000, v158
	v_cndmask_b32_e32 v172, v158, v164, vcc
	v_cmp_gt_f32_e32 vcc, s53, v179
	v_mul_f32_e32 v158, 0x4b800000, v179
	v_pk_fma_f32 v[118:119], v[118:119], v[182:183], v[152:153] op_sel_hi:[1,0,1]
	v_cndmask_b32_e32 v158, v179, v158, vcc
	v_rsq_f32_e32 v158, v158
	v_pk_fma_f32 v[116:117], v[116:117], v[182:183], v[154:155] op_sel_hi:[1,0,1]
	v_pk_fma_f32 v[112:113], v[112:113], v[182:183], v[150:151] op_sel_hi:[1,0,1]
	v_max_f32_e32 v114, 0, v114
	v_mul_f32_e32 v164, 0x45800000, v158
	v_cndmask_b32_e32 v158, v158, v164, vcc
	v_mul_f32_e32 v164, v122, v122
	v_max_f32_e32 v122, 0, v127
	v_mul_f32_e32 v127, v122, v122
	v_max_f32_e32 v122, 0, v123
	v_mul_f32_e32 v165, v122, v122
	v_cvt_pk_bf16_f32 v122, v124, v125
	v_cvt_pk_bf16_f32 v123, v126, v127
	v_cvt_pk_bf16_f32 v124, v120, v121
	v_lshlrev_b64 v[120:121], 13, v[146:147]
	v_lshl_add_u64 v[120:121], s[8:9], 0, v[120:121]
	v_lshlrev_b64 v[126:127], 1, v[156:157]
	v_lshl_add_u64 v[120:121], v[120:121], 0, v[126:127]
	v_cvt_pk_bf16_f32 v125, v164, v165
	global_store_dwordx4 v[120:121], v[122:125], off
	v_max_f32_e32 v116, 0, v116
	v_max_f32_e32 v112, 0, v112
	v_mul_f32_e32 v122, v114, v114
	v_max_f32_e32 v114, 0, v119
	v_mul_f32_e32 v116, v116, v116
	v_mul_f32_e32 v112, v112, v112
	v_max_f32_e32 v117, 0, v117
	v_max_f32_e32 v113, 0, v113
	v_max_f32_e32 v118, 0, v118
	v_mul_f32_e32 v119, v114, v114
	v_max_f32_e32 v114, 0, v115
	v_mul_f32_e32 v117, v117, v117
	v_mul_f32_e32 v113, v113, v113
	v_mul_f32_e32 v118, v118, v118
	v_mul_f32_e32 v123, v114, v114
	v_cvt_pk_bf16_f32 v114, v116, v117
	v_cvt_pk_bf16_f32 v115, v118, v119
	v_cvt_pk_bf16_f32 v116, v112, v113
	v_or_b32_e32 v112, 16, v146
	v_ashrrev_i32_e32 v113, 31, v112
	v_lshlrev_b64 v[112:113], 13, v[112:113]
	v_lshl_add_u64 v[112:113], s[8:9], 0, v[112:113]
	v_pk_fma_f32 v[106:107], v[106:107], v[180:181], v[148:149] op_sel_hi:[1,0,1]
	v_lshl_add_u64 v[112:113], v[112:113], 0, v[126:127]
	v_pk_fma_f32 v[110:111], v[110:111], v[180:181], v[152:153] op_sel_hi:[1,0,1]
	v_pk_fma_f32 v[108:109], v[108:109], v[180:181], v[154:155] op_sel_hi:[1,0,1]
	v_pk_fma_f32 v[104:105], v[104:105], v[180:181], v[150:151] op_sel_hi:[1,0,1]
	v_max_f32_e32 v106, 0, v106
	v_cvt_pk_bf16_f32 v117, v122, v123
	global_store_dwordx4 v[112:113], v[114:117], off
	v_max_f32_e32 v108, 0, v108
	v_max_f32_e32 v104, 0, v104
	v_mul_f32_e32 v114, v106, v106
	v_max_f32_e32 v106, 0, v111
	v_mul_f32_e32 v108, v108, v108
	v_mul_f32_e32 v104, v104, v104
	v_max_f32_e32 v109, 0, v109
	v_max_f32_e32 v105, 0, v105
	v_max_f32_e32 v110, 0, v110
	v_mul_f32_e32 v111, v106, v106
	v_max_f32_e32 v106, 0, v107
	v_mul_f32_e32 v109, v109, v109
	v_mul_f32_e32 v105, v105, v105
	v_mul_f32_e32 v110, v110, v110
	v_mul_f32_e32 v115, v106, v106
	v_cvt_pk_bf16_f32 v106, v108, v109
	v_cvt_pk_bf16_f32 v107, v110, v111
	v_cvt_pk_bf16_f32 v108, v104, v105
	v_or_b32_e32 v104, 32, v146
	v_ashrrev_i32_e32 v105, 31, v104
	v_lshlrev_b64 v[104:105], 13, v[104:105]
	v_lshl_add_u64 v[104:105], s[8:9], 0, v[104:105]
	v_pk_fma_f32 v[98:99], v[98:99], v[178:179], v[148:149] op_sel_hi:[1,0,1]
	v_lshl_add_u64 v[104:105], v[104:105], 0, v[126:127]
	v_pk_fma_f32 v[102:103], v[102:103], v[178:179], v[152:153] op_sel_hi:[1,0,1]
	v_pk_fma_f32 v[100:101], v[100:101], v[178:179], v[154:155] op_sel_hi:[1,0,1]
	v_pk_fma_f32 v[96:97], v[96:97], v[178:179], v[150:151] op_sel_hi:[1,0,1]
	v_max_f32_e32 v98, 0, v98
	v_cvt_pk_bf16_f32 v109, v114, v115
	global_store_dwordx4 v[104:105], v[106:109], off
	v_max_f32_e32 v100, 0, v100
	v_max_f32_e32 v96, 0, v96
	v_mul_f32_e32 v106, v98, v98
	v_max_f32_e32 v98, 0, v103
	v_mul_f32_e32 v100, v100, v100
	v_mul_f32_e32 v96, v96, v96
	v_max_f32_e32 v101, 0, v101
	v_max_f32_e32 v97, 0, v97
	v_max_f32_e32 v102, 0, v102
	v_mul_f32_e32 v103, v98, v98
	v_max_f32_e32 v98, 0, v99
	v_mul_f32_e32 v101, v101, v101
	v_mul_f32_e32 v97, v97, v97
	v_mul_f32_e32 v102, v102, v102
	v_mul_f32_e32 v107, v98, v98
	v_cvt_pk_bf16_f32 v98, v100, v101
	v_cvt_pk_bf16_f32 v99, v102, v103
	v_cvt_pk_bf16_f32 v100, v96, v97
	v_or_b32_e32 v96, 48, v146
	v_ashrrev_i32_e32 v97, 31, v96
	v_lshlrev_b64 v[96:97], 13, v[96:97]
	v_lshl_add_u64 v[96:97], s[8:9], 0, v[96:97]
	v_pk_fma_f32 v[90:91], v[90:91], v[176:177], v[148:149] op_sel_hi:[1,0,1]
	v_lshl_add_u64 v[96:97], v[96:97], 0, v[126:127]
	v_pk_fma_f32 v[94:95], v[94:95], v[176:177], v[152:153] op_sel_hi:[1,0,1]
	v_max_f32_e32 v90, 0, v90
	v_cvt_pk_bf16_f32 v101, v106, v107
	global_store_dwordx4 v[96:97], v[98:101], off
	v_pk_fma_f32 v[92:93], v[92:93], v[176:177], v[154:155] op_sel_hi:[1,0,1]
	v_max_f32_e32 v94, 0, v94
	v_mul_f32_e32 v98, v90, v90
	v_max_f32_e32 v90, 0, v95
	v_max_f32_e32 v92, 0, v92
	v_max_f32_e32 v93, 0, v93
	v_mul_f32_e32 v94, v94, v94
	v_mul_f32_e32 v95, v90, v90
	v_max_f32_e32 v90, 0, v91
	v_pk_fma_f32 v[88:89], v[88:89], v[176:177], v[150:151] op_sel_hi:[1,0,1]
	v_mul_f32_e32 v92, v92, v92
	v_mul_f32_e32 v93, v93, v93
	v_mul_f32_e32 v99, v90, v90
	v_cvt_pk_bf16_f32 v90, v92, v93
	v_cvt_pk_bf16_f32 v91, v94, v95
	v_add_co_u32_e32 v94, vcc, s1, v120
	v_pk_fma_f32 v[82:83], v[82:83], v[174:175], v[148:149] op_sel_hi:[1,0,1]
	v_max_f32_e32 v88, 0, v88
	v_max_f32_e32 v89, 0, v89
	v_addc_co_u32_e32 v95, vcc, 0, v121, vcc
	v_pk_fma_f32 v[86:87], v[86:87], v[174:175], v[152:153] op_sel_hi:[1,0,1]
	v_max_f32_e32 v82, 0, v82
	v_mul_f32_e32 v88, v88, v88
	v_mul_f32_e32 v89, v89, v89
	v_cvt_pk_bf16_f32 v92, v88, v89
	v_cvt_pk_bf16_f32 v93, v98, v99
	global_store_dwordx4 v[94:95], v[90:93], off
	v_pk_fma_f32 v[84:85], v[84:85], v[174:175], v[154:155] op_sel_hi:[1,0,1]
	v_max_f32_e32 v86, 0, v86
	v_mul_f32_e32 v90, v82, v82
	v_max_f32_e32 v82, 0, v87
	v_max_f32_e32 v84, 0, v84
	v_max_f32_e32 v85, 0, v85
	v_mul_f32_e32 v86, v86, v86
	v_mul_f32_e32 v87, v82, v82
	v_max_f32_e32 v82, 0, v83
	s_mov_b32 s1, 0x120000
	v_pk_fma_f32 v[80:81], v[80:81], v[174:175], v[150:151] op_sel_hi:[1,0,1]
	v_mul_f32_e32 v84, v84, v84
	v_mul_f32_e32 v85, v85, v85
	v_mul_f32_e32 v91, v82, v82
	v_cvt_pk_bf16_f32 v82, v84, v85
	v_cvt_pk_bf16_f32 v83, v86, v87
	v_add_co_u32_e32 v86, vcc, s1, v120
	v_pk_fma_f32 v[74:75], v[74:75], v[172:173], v[148:149] op_sel_hi:[1,0,1]
	v_max_f32_e32 v80, 0, v80
	v_max_f32_e32 v81, 0, v81
	v_addc_co_u32_e32 v87, vcc, 0, v121, vcc
	v_pk_fma_f32 v[78:79], v[78:79], v[172:173], v[152:153] op_sel_hi:[1,0,1]
	v_max_f32_e32 v74, 0, v74
	v_mul_f32_e32 v80, v80, v80
	v_mul_f32_e32 v81, v81, v81
	v_cvt_pk_bf16_f32 v84, v80, v81
	v_cvt_pk_bf16_f32 v85, v90, v91
	global_store_dwordx4 v[86:87], v[82:85], off
	v_pk_fma_f32 v[76:77], v[76:77], v[172:173], v[154:155] op_sel_hi:[1,0,1]
	v_max_f32_e32 v78, 0, v78
	v_mul_f32_e32 v82, v74, v74
	v_max_f32_e32 v74, 0, v79
	v_max_f32_e32 v76, 0, v76
	v_max_f32_e32 v77, 0, v77
	v_mul_f32_e32 v78, v78, v78
	v_mul_f32_e32 v79, v74, v74
	v_max_f32_e32 v74, 0, v75
	s_mov_b32 s1, 0x140000
	v_pk_fma_f32 v[72:73], v[72:73], v[172:173], v[150:151] op_sel_hi:[1,0,1]
	v_mul_f32_e32 v76, v76, v76
	v_mul_f32_e32 v77, v77, v77
	v_mul_f32_e32 v83, v74, v74
	v_cvt_pk_bf16_f32 v74, v76, v77
	v_cvt_pk_bf16_f32 v75, v78, v79
	v_add_co_u32_e32 v78, vcc, s1, v120
	v_pk_fma_f32 v[58:59], v[58:59], v[158:159], v[148:149] op_sel_hi:[1,0,1]
	v_max_f32_e32 v72, 0, v72
	v_max_f32_e32 v73, 0, v73
	v_addc_co_u32_e32 v79, vcc, 0, v121, vcc
	v_pk_fma_f32 v[62:63], v[62:63], v[158:159], v[152:153] op_sel_hi:[1,0,1]
	v_max_f32_e32 v58, 0, v58
	v_mul_f32_e32 v72, v72, v72
	v_mul_f32_e32 v73, v73, v73
	v_cvt_pk_bf16_f32 v76, v72, v73
	v_cvt_pk_bf16_f32 v77, v82, v83
	global_store_dwordx4 v[78:79], v[74:77], off
	v_pk_fma_f32 v[60:61], v[60:61], v[158:159], v[154:155] op_sel_hi:[1,0,1]
	v_max_f32_e32 v62, 0, v62
	v_mul_f32_e32 v74, v58, v58
	v_max_f32_e32 v58, 0, v63
	v_max_f32_e32 v60, 0, v60
	v_max_f32_e32 v61, 0, v61
	v_mul_f32_e32 v62, v62, v62
	v_mul_f32_e32 v63, v58, v58
	v_max_f32_e32 v58, 0, v59
	s_mov_b32 s1, 0x160000
	v_pk_fma_f32 v[56:57], v[56:57], v[158:159], v[150:151] op_sel_hi:[1,0,1]
	v_mul_f32_e32 v60, v60, v60
	v_mul_f32_e32 v61, v61, v61
	v_mul_f32_e32 v75, v58, v58
	v_cvt_pk_bf16_f32 v58, v60, v61
	v_cvt_pk_bf16_f32 v59, v62, v63
	v_add_co_u32_e32 v62, vcc, s1, v120
	s_waitcnt vmcnt(7)
	v_pk_add_f32 v[134:135], v[134:135], 0 op_sel_hi:[1,0]
	v_max_f32_e32 v56, 0, v56
	v_max_f32_e32 v57, 0, v57
	v_addc_co_u32_e32 v63, vcc, 0, v121, vcc
	v_pk_add_f32 v[130:131], v[130:131], 0 op_sel_hi:[1,0]
	v_mul_f32_e32 v56, v56, v56
	v_mul_f32_e32 v57, v57, v57
	v_cvt_pk_bf16_f32 v60, v56, v57
	v_cvt_pk_bf16_f32 v61, v74, v75
	global_store_dwordx4 v[62:63], v[58:61], off
	v_pk_fma_f32 v[62:63], v[66:67], v[184:185], v[130:131] op_sel_hi:[1,0,1]
	v_pk_add_f32 v[132:133], v[132:133], 0 op_sel_hi:[1,0]
	v_pk_fma_f32 v[58:59], v[70:71], v[184:185], v[134:135] op_sel_hi:[1,0,1]
	v_pk_add_f32 v[128:129], v[128:129], 0 op_sel_hi:[1,0]
	v_max_f32_e32 v58, 0, v58
	v_mul_f32_e32 v66, v58, v58
	v_max_f32_e32 v58, 0, v62
	v_pk_fma_f32 v[60:61], v[68:69], v[184:185], v[132:133] op_sel_hi:[1,0,1]
	v_mul_f32_e32 v62, v58, v58
	v_max_f32_e32 v58, 0, v59
	v_pk_fma_f32 v[64:65], v[64:65], v[184:185], v[128:129] op_sel_hi:[1,0,1]
	v_max_f32_e32 v60, 0, v60
	v_max_f32_e32 v61, 0, v61
	v_mul_f32_e32 v59, v58, v58
	v_max_f32_e32 v58, 0, v63
	v_pk_fma_f32 v[48:49], v[48:49], v[182:183], v[128:129] op_sel_hi:[1,0,1]
	v_mul_f32_e32 v60, v60, v60
	v_max_f32_e32 v64, 0, v64
	v_mul_f32_e32 v61, v61, v61
	v_max_f32_e32 v65, 0, v65
	v_mul_f32_e32 v63, v58, v58
	v_cvt_pk_bf16_f32 v58, v60, v61
	v_pk_fma_f32 v[52:53], v[52:53], v[182:183], v[132:133] op_sel_hi:[1,0,1]
	v_pk_fma_f32 v[50:51], v[50:51], v[182:183], v[130:131] op_sel_hi:[1,0,1]
	v_max_f32_e32 v48, 0, v48
	v_mul_f32_e32 v64, v64, v64
	v_mul_f32_e32 v65, v65, v65
	v_cvt_pk_bf16_f32 v59, v66, v59
	v_cvt_pk_bf16_f32 v60, v64, v65
	v_cvt_pk_bf16_f32 v61, v62, v63
	global_store_dwordx4 v[120:121], v[58:61], off offset:256
	v_pk_fma_f32 v[54:55], v[54:55], v[182:183], v[134:135] op_sel_hi:[1,0,1]
	v_max_f32_e32 v49, 0, v49
	v_mul_f32_e32 v58, v48, v48
	v_max_f32_e32 v48, 0, v53
	v_max_f32_e32 v50, 0, v50
	v_max_f32_e32 v52, 0, v52
	v_mul_f32_e32 v48, v48, v48
	v_mul_f32_e32 v53, v49, v49
	v_max_f32_e32 v49, 0, v54
	v_mul_f32_e32 v54, v50, v50
	v_max_f32_e32 v50, 0, v55
	v_max_f32_e32 v51, 0, v51
	v_pk_fma_f32 v[40:41], v[40:41], v[180:181], v[128:129] op_sel_hi:[1,0,1]
	v_mul_f32_e32 v52, v52, v52
	v_mul_f32_e32 v49, v49, v49
	v_mul_f32_e32 v50, v50, v50
	v_mul_f32_e32 v51, v51, v51
	v_cvt_pk_bf16_f32 v48, v52, v48
	v_pk_fma_f32 v[44:45], v[44:45], v[180:181], v[132:133] op_sel_hi:[1,0,1]
	v_pk_fma_f32 v[42:43], v[42:43], v[180:181], v[130:131] op_sel_hi:[1,0,1]
	v_max_f32_e32 v40, 0, v40
	v_cvt_pk_bf16_f32 v49, v49, v50
	v_cvt_pk_bf16_f32 v50, v58, v53
	v_cvt_pk_bf16_f32 v51, v54, v51
	global_store_dwordx4 v[112:113], v[48:51], off offset:256
	v_pk_fma_f32 v[46:47], v[46:47], v[180:181], v[134:135] op_sel_hi:[1,0,1]
	v_max_f32_e32 v41, 0, v41
	v_mul_f32_e32 v48, v40, v40
	v_max_f32_e32 v40, 0, v45
	v_max_f32_e32 v42, 0, v42
	v_max_f32_e32 v44, 0, v44
	v_mul_f32_e32 v40, v40, v40
	v_mul_f32_e32 v45, v41, v41
	v_max_f32_e32 v41, 0, v46
	v_mul_f32_e32 v46, v42, v42
	v_max_f32_e32 v42, 0, v47
	v_max_f32_e32 v43, 0, v43
	v_pk_fma_f32 v[32:33], v[32:33], v[178:179], v[128:129] op_sel_hi:[1,0,1]
	v_mul_f32_e32 v44, v44, v44
	v_mul_f32_e32 v41, v41, v41
	v_mul_f32_e32 v42, v42, v42
	v_mul_f32_e32 v43, v43, v43
	v_cvt_pk_bf16_f32 v40, v44, v40
	v_pk_fma_f32 v[36:37], v[36:37], v[178:179], v[132:133] op_sel_hi:[1,0,1]
	v_pk_fma_f32 v[34:35], v[34:35], v[178:179], v[130:131] op_sel_hi:[1,0,1]
	v_max_f32_e32 v32, 0, v32
	v_cvt_pk_bf16_f32 v41, v41, v42
	v_cvt_pk_bf16_f32 v42, v48, v45
	v_cvt_pk_bf16_f32 v43, v46, v43
	global_store_dwordx4 v[104:105], v[40:43], off offset:256
	v_pk_fma_f32 v[38:39], v[38:39], v[178:179], v[134:135] op_sel_hi:[1,0,1]
	v_max_f32_e32 v33, 0, v33
	v_mul_f32_e32 v40, v32, v32
	v_max_f32_e32 v32, 0, v37
	v_max_f32_e32 v34, 0, v34
	v_max_f32_e32 v36, 0, v36
	v_mul_f32_e32 v32, v32, v32
	v_mul_f32_e32 v37, v33, v33
	v_max_f32_e32 v33, 0, v38
	v_mul_f32_e32 v38, v34, v34
	v_max_f32_e32 v34, 0, v39
	v_max_f32_e32 v35, 0, v35
	v_pk_fma_f32 v[24:25], v[24:25], v[176:177], v[128:129] op_sel_hi:[1,0,1]
	v_mul_f32_e32 v36, v36, v36
	v_mul_f32_e32 v33, v33, v33
	v_mul_f32_e32 v34, v34, v34
	v_mul_f32_e32 v35, v35, v35
	v_cvt_pk_bf16_f32 v32, v36, v32
	v_pk_fma_f32 v[28:29], v[28:29], v[176:177], v[132:133] op_sel_hi:[1,0,1]
	v_pk_fma_f32 v[26:27], v[26:27], v[176:177], v[130:131] op_sel_hi:[1,0,1]
	v_max_f32_e32 v24, 0, v24
	v_cvt_pk_bf16_f32 v33, v33, v34
	v_cvt_pk_bf16_f32 v34, v40, v37
	v_cvt_pk_bf16_f32 v35, v38, v35
	global_store_dwordx4 v[96:97], v[32:35], off offset:256
	v_pk_fma_f32 v[30:31], v[30:31], v[176:177], v[134:135] op_sel_hi:[1,0,1]
	v_max_f32_e32 v25, 0, v25
	v_mul_f32_e32 v32, v24, v24
	v_max_f32_e32 v24, 0, v29
	v_max_f32_e32 v26, 0, v26
	s_mov_b64 s[8:9], 0x100000
	v_max_f32_e32 v28, 0, v28
	v_mul_f32_e32 v24, v24, v24
	v_mul_f32_e32 v29, v25, v25
	v_max_f32_e32 v25, 0, v30
	v_mul_f32_e32 v30, v26, v26
	v_max_f32_e32 v26, 0, v31
	v_max_f32_e32 v27, 0, v27
	v_pk_fma_f32 v[16:17], v[16:17], v[174:175], v[128:129] op_sel_hi:[1,0,1]
	v_lshl_add_u64 v[88:89], v[120:121], 0, s[8:9]
	v_mul_f32_e32 v28, v28, v28
	v_mul_f32_e32 v25, v25, v25
	v_mul_f32_e32 v26, v26, v26
	v_mul_f32_e32 v27, v27, v27
	v_cvt_pk_bf16_f32 v24, v28, v24
	v_pk_fma_f32 v[20:21], v[20:21], v[174:175], v[132:133] op_sel_hi:[1,0,1]
	v_pk_fma_f32 v[18:19], v[18:19], v[174:175], v[130:131] op_sel_hi:[1,0,1]
	v_max_f32_e32 v16, 0, v16
	v_cvt_pk_bf16_f32 v25, v25, v26
	v_cvt_pk_bf16_f32 v26, v32, v29
	v_cvt_pk_bf16_f32 v27, v30, v27
	global_store_dwordx4 v[88:89], v[24:27], off offset:256
	v_pk_fma_f32 v[22:23], v[22:23], v[174:175], v[134:135] op_sel_hi:[1,0,1]
	v_max_f32_e32 v17, 0, v17
	v_mul_f32_e32 v24, v16, v16
	v_max_f32_e32 v16, 0, v21
	v_max_f32_e32 v18, 0, v18
	s_mov_b64 s[8:9], 0x120000
	v_max_f32_e32 v20, 0, v20
	v_mul_f32_e32 v16, v16, v16
	v_mul_f32_e32 v21, v17, v17
	v_max_f32_e32 v17, 0, v22
	v_mul_f32_e32 v22, v18, v18
	v_max_f32_e32 v18, 0, v23
	v_max_f32_e32 v19, 0, v19
	v_pk_fma_f32 v[8:9], v[8:9], v[172:173], v[128:129] op_sel_hi:[1,0,1]
	v_lshl_add_u64 v[80:81], v[120:121], 0, s[8:9]
	v_mul_f32_e32 v20, v20, v20
	v_mul_f32_e32 v17, v17, v17
	v_mul_f32_e32 v18, v18, v18
	v_mul_f32_e32 v19, v19, v19
	v_cvt_pk_bf16_f32 v16, v20, v16
	v_pk_fma_f32 v[12:13], v[12:13], v[172:173], v[132:133] op_sel_hi:[1,0,1]
	v_pk_fma_f32 v[10:11], v[10:11], v[172:173], v[130:131] op_sel_hi:[1,0,1]
	v_max_f32_e32 v8, 0, v8
	v_cvt_pk_bf16_f32 v17, v17, v18
	v_cvt_pk_bf16_f32 v18, v24, v21
	v_cvt_pk_bf16_f32 v19, v22, v19
	global_store_dwordx4 v[80:81], v[16:19], off offset:256
	v_pk_fma_f32 v[14:15], v[14:15], v[172:173], v[134:135] op_sel_hi:[1,0,1]
	v_max_f32_e32 v9, 0, v9
	v_mul_f32_e32 v16, v8, v8
	v_max_f32_e32 v8, 0, v13
	v_max_f32_e32 v10, 0, v10
	s_mov_b64 s[8:9], 0x140000
	v_max_f32_e32 v12, 0, v12
	v_mul_f32_e32 v8, v8, v8
	v_mul_f32_e32 v13, v9, v9
	v_max_f32_e32 v9, 0, v14
	v_mul_f32_e32 v14, v10, v10
	v_max_f32_e32 v10, 0, v15
	v_max_f32_e32 v11, 0, v11
	v_pk_fma_f32 v[2:3], v[2:3], v[158:159], v[130:131] op_sel_hi:[1,0,1]
	v_pk_fma_f32 v[0:1], v[0:1], v[158:159], v[128:129] op_sel_hi:[1,0,1]
	v_lshl_add_u64 v[72:73], v[120:121], 0, s[8:9]
	v_mul_f32_e32 v12, v12, v12
	v_mul_f32_e32 v9, v9, v9
	v_mul_f32_e32 v10, v10, v10
	v_mul_f32_e32 v11, v11, v11
	v_cvt_pk_bf16_f32 v8, v12, v8
	v_pk_fma_f32 v[6:7], v[6:7], v[158:159], v[134:135] op_sel_hi:[1,0,1]
	v_pk_fma_f32 v[4:5], v[4:5], v[158:159], v[132:133] op_sel_hi:[1,0,1]
	v_max_f32_e32 v0, 0, v0
	v_max_f32_e32 v1, 0, v1
	v_max_f32_e32 v2, 0, v2
	s_mov_b64 s[8:9], 0x160000
	v_cvt_pk_bf16_f32 v9, v9, v10
	v_cvt_pk_bf16_f32 v10, v16, v13
	v_cvt_pk_bf16_f32 v11, v14, v11
	global_store_dwordx4 v[72:73], v[8:11], off offset:256
	v_max_f32_e32 v3, 0, v3
	v_lshl_add_u64 v[56:57], v[120:121], 0, s[8:9]
	v_mul_f32_e32 v8, v0, v0
	v_max_f32_e32 v0, 0, v5
	v_mul_f32_e32 v5, v1, v1
	v_max_f32_e32 v1, 0, v6
	v_mul_f32_e32 v6, v2, v2
	v_max_f32_e32 v2, 0, v7
	v_max_f32_e32 v4, 0, v4
	v_mul_f32_e32 v0, v0, v0
	v_mul_f32_e32 v1, v1, v1
	v_mul_f32_e32 v2, v2, v2
	v_mul_f32_e32 v3, v3, v3
	s_and_b64 vcc, exec, s[2:3]
	s_mov_b64 s[8:9], s[58:59]
	v_mul_f32_e32 v4, v4, v4
	v_cvt_pk_bf16_f32 v0, v4, v0
	v_cvt_pk_bf16_f32 v1, v1, v2
	v_cvt_pk_bf16_f32 v2, v8, v5
	v_cvt_pk_bf16_f32 v3, v6, v3
	global_store_dwordx4 v[56:57], v[0:3], off offset:256
	s_cbranch_vccz .LBB0_343
	s_waitcnt vmcnt(0)
	s_mov_b32 s90, s62
	s_cmpk_gt_u32 s36, 0xff
	s_cbranch_scc1 .LBB0_354
	s_barrier

.LBB0_382:
	v_mul_f32_e32 v64, v225, v225
	v_mul_f32_e32 v65, v221, v221
	v_fmac_f32_e32 v64, v224, v224
	v_fmac_f32_e32 v65, v220, v220
	v_add_f32_e32 v64, v64, v65
	v_mul_f32_e32 v65, v223, v223
	v_fmac_f32_e32 v65, v222, v222
	v_or_b32_e32 v190, 0x80, v184
	v_readlane_b32 s6, v250, 56
	v_add_f32_e32 v64, v65, v64
	v_mul_f32_e32 v65, v219, v219
	v_ashrrev_i32_e32 v191, 31, v190
	v_readlane_b32 s7, v250, 57
	v_fmac_f32_e32 v65, v218, v218
	v_add_f32_e32 v164, v65, v64
	v_lshl_add_u64 v[84:85], v[190:191], 2, s[6:7]
	global_load_dwordx4 v[64:67], v[200:201], off offset:528
	global_load_dwordx4 v[68:71], v[200:201], off offset:512
	global_load_dwordx4 v[80:83], v[84:85], off offset:16
	s_nop 0
	global_load_dwordx4 v[84:87], v[84:85], off
	s_nop 0
	global_load_dwordx4 v[218:221], v[186:187], off offset:528
	global_load_dwordx4 v[222:225], v[186:187], off offset:512
	v_readlane_b32 s6, v249, 24
	v_readlane_b32 s7, v249, 25
	s_waitcnt vmcnt(0)
	v_pk_fma_f32 v[90:91], v[58:59], v[66:67], v[90:91]
	v_pk_fma_f32 v[62:63], v[62:63], v[70:71], v[94:95]
	v_pk_add_f32 v[186:187], v[224:225], 1.0 op_sel_hi:[1,0]
	v_pk_add_f32 v[192:193], v[222:223], 1.0 op_sel_hi:[1,0]
	v_pk_mul_f32 v[186:187], v[86:87], v[186:187]
	v_pk_mul_f32 v[192:193], v[84:85], v[192:193]
	v_pk_add_f32 v[84:85], v[220:221], 1.0 op_sel_hi:[1,0]
	v_pk_add_f32 v[86:87], v[218:219], 1.0 op_sel_hi:[1,0]
	v_pk_mul_f32 v[196:197], v[82:83], v[84:85]
	v_pk_mul_f32 v[200:201], v[80:81], v[86:87]
	global_load_dwordx4 v[80:83], v[188:189], off offset:528
	global_load_dwordx4 v[84:87], v[188:189], off offset:512
	v_pk_fma_f32 v[60:61], v[60:61], v[68:69], v[92:93]
	v_pk_fma_f32 v[92:93], v[56:57], v[64:65], v[88:89]
	v_cvt_pk_bf16_f32 v56, v60, v61
	v_cvt_pk_bf16_f32 v57, v62, v63
	v_lshl_add_u64 v[188:189], v[194:195], 0, v[190:191]
	v_cvt_pk_bf16_f32 v58, v92, v93
	v_cvt_pk_bf16_f32 v59, v90, v91
	global_store_dwordx4 v[158:159], v[56:59], off offset:256
	v_pk_fma_f32 v[78:79], v[54:55], v[70:71], v[78:79]
	v_pk_fma_f32 v[76:77], v[52:53], v[68:69], v[76:77]
	v_mul_f32_e32 v56, v61, v61
	v_mul_f32_e32 v57, v63, v63
	v_fmac_f32_e32 v56, v60, v60
	v_fmac_f32_e32 v57, v62, v62
	v_add_f32_e32 v56, v56, v57
	v_mul_f32_e32 v57, v93, v93
	v_fmac_f32_e32 v57, v92, v92
	v_add_f32_e32 v56, v57, v56
	v_mul_f32_e32 v57, v91, v91
	v_fmac_f32_e32 v57, v90, v90
	v_add_f32_e32 v56, v57, v56
	v_add_f32_e32 v88, v164, v56
	v_pk_mul_f32 v[58:59], v[62:63], v[186:187]
	v_pk_mul_f32 v[56:57], v[60:61], v[192:193]
	v_pk_mul_f32 v[60:61], v[90:91], v[196:197]
	v_pk_mul_f32 v[62:63], v[92:93], v[200:201]
	v_cvt_pk_bf16_f32 v56, v56, v57
	v_cvt_pk_bf16_f32 v57, v58, v59
	v_pk_fma_f32 v[74:75], v[50:51], v[66:67], v[74:75]
	v_cvt_pk_bf16_f32 v58, v62, v63
	v_cvt_pk_bf16_f32 v59, v60, v61
	v_lshl_add_u64 v[60:61], v[188:189], 1, s[28:29]
	global_store_dwordx4 v[60:61], v[56:59], off
	global_load_dwordx4 v[56:59], v[212:213], off offset:528
	s_nop 0
	global_load_dwordx4 v[60:63], v[212:213], off offset:512
	v_pk_fma_f32 v[72:73], v[48:49], v[64:65], v[72:73]
	v_cvt_pk_bf16_f32 v48, v76, v77
	v_cvt_pk_bf16_f32 v49, v78, v79
	v_lshl_add_u64 v[90:91], v[154:155], 0, v[190:191]
	v_cvt_pk_bf16_f32 v50, v72, v73
	v_cvt_pk_bf16_f32 v51, v74, v75
	global_store_dwordx4 v[156:157], v[48:51], off offset:256
	v_pk_mul_f32 v[52:53], v[74:75], v[196:197]
	v_pk_mul_f32 v[54:55], v[72:73], v[200:201]
	v_pk_mul_f32 v[50:51], v[78:79], v[186:187]
	v_pk_mul_f32 v[48:49], v[76:77], v[192:193]
	s_waitcnt vmcnt(1)
	v_pk_fma_f32 v[82:83], v[42:43], v[66:67], v[82:83]
	v_cvt_pk_bf16_f32 v48, v48, v49
	v_cvt_pk_bf16_f32 v49, v50, v51
	v_cvt_pk_bf16_f32 v50, v54, v55
	v_cvt_pk_bf16_f32 v51, v52, v53
	v_lshl_add_u64 v[52:53], v[90:91], 1, s[28:29]
	global_store_dwordx4 v[52:53], v[48:51], off
	global_load_dwordx4 v[48:51], v[152:153], off offset:528
	s_nop 0
	global_load_dwordx4 v[52:55], v[152:153], off offset:512
	v_pk_fma_f32 v[86:87], v[46:47], v[70:71], v[86:87]
	v_pk_fma_f32 v[84:85], v[44:45], v[68:69], v[84:85]
	v_pk_fma_f32 v[80:81], v[40:41], v[64:65], v[80:81]
	v_cvt_pk_bf16_f32 v40, v84, v85
	v_cvt_pk_bf16_f32 v41, v86, v87
	v_lshl_add_u64 v[90:91], v[202:203], 0, v[190:191]
	v_cvt_pk_bf16_f32 v42, v80, v81
	v_cvt_pk_bf16_f32 v43, v82, v83
	global_store_dwordx4 v[204:205], v[40:43], off offset:256
	v_pk_mul_f32 v[44:45], v[196:197], v[82:83]
	v_pk_mul_f32 v[46:47], v[200:201], v[80:81]
	v_pk_mul_f32 v[42:43], v[186:187], v[86:87]
	v_pk_mul_f32 v[40:41], v[192:193], v[84:85]
	v_pk_fma_f32 v[58:59], v[34:35], v[66:67], v[58:59]
	v_cvt_pk_bf16_f32 v40, v40, v41
	v_cvt_pk_bf16_f32 v41, v42, v43
	v_cvt_pk_bf16_f32 v42, v46, v47
	v_cvt_pk_bf16_f32 v43, v44, v45
	v_lshl_add_u64 v[44:45], v[90:91], 1, s[28:29]
	global_store_dwordx4 v[44:45], v[40:43], off
	v_lshl_add_u64 v[44:45], v[184:185], 2, v[210:211]
	global_load_dwordx4 v[40:43], v[44:45], off offset:528
	s_nop 0
	global_load_dwordx4 v[44:47], v[44:45], off offset:512
	v_pk_fma_f32 v[62:63], v[38:39], v[70:71], v[62:63]
	v_pk_fma_f32 v[60:61], v[36:37], v[68:69], v[60:61]
	v_pk_fma_f32 v[56:57], v[32:33], v[64:65], v[56:57]
	v_cvt_pk_bf16_f32 v32, v60, v61
	v_cvt_pk_bf16_f32 v33, v62, v63
	v_lshl_add_u64 v[90:91], v[206:207], 0, v[190:191]
	v_cvt_pk_bf16_f32 v34, v56, v57
	v_cvt_pk_bf16_f32 v35, v58, v59
	global_store_dwordx4 v[208:209], v[32:35], off offset:256
	v_pk_mul_f32 v[36:37], v[196:197], v[58:59]
	v_pk_mul_f32 v[38:39], v[200:201], v[56:57]
	v_pk_mul_f32 v[34:35], v[186:187], v[62:63]
	v_pk_mul_f32 v[32:33], v[192:193], v[60:61]
	s_waitcnt vmcnt(1)
	v_pk_fma_f32 v[54:55], v[30:31], v[70:71], v[54:55]
	v_cvt_pk_bf16_f32 v32, v32, v33
	v_cvt_pk_bf16_f32 v33, v34, v35
	v_cvt_pk_bf16_f32 v34, v38, v39
	v_cvt_pk_bf16_f32 v35, v36, v37
	v_lshl_add_u64 v[36:37], v[90:91], 1, s[28:29]
	global_store_dwordx4 v[36:37], v[32:35], off
	global_load_dwordx4 v[32:35], v[226:227], off offset:528
	s_nop 0
	global_load_dwordx4 v[36:39], v[226:227], off offset:512
	v_pk_fma_f32 v[52:53], v[28:29], v[68:69], v[52:53]
	v_pk_fma_f32 v[28:29], v[26:27], v[66:67], v[50:51]
	v_pk_fma_f32 v[30:31], v[24:25], v[64:65], v[48:49]
	v_cvt_pk_bf16_f32 v24, v52, v53
	v_cvt_pk_bf16_f32 v25, v54, v55
	v_lshl_add_u64 v[90:91], v[214:215], 0, v[190:191]
	v_cvt_pk_bf16_f32 v26, v30, v31
	v_cvt_pk_bf16_f32 v27, v28, v29
	global_store_dwordx4 v[216:217], v[24:27], off offset:256
	v_pk_mul_f32 v[48:49], v[196:197], v[28:29]
	v_pk_mul_f32 v[50:51], v[200:201], v[30:31]
	v_pk_mul_f32 v[26:27], v[186:187], v[54:55]
	v_pk_mul_f32 v[24:25], v[192:193], v[52:53]
	v_pk_fma_f32 v[18:19], v[18:19], v[66:67], v[42:43]
	v_cvt_pk_bf16_f32 v24, v24, v25
	v_cvt_pk_bf16_f32 v25, v26, v27
	v_cvt_pk_bf16_f32 v26, v50, v51
	v_cvt_pk_bf16_f32 v27, v48, v49
	v_lshl_add_u64 v[48:49], v[90:91], 1, s[28:29]
	global_store_dwordx4 v[48:49], v[24:27], off
	global_load_dwordx4 v[24:27], v[198:199], off offset:528
	s_nop 0
	global_load_dwordx4 v[48:51], v[198:199], off offset:512
	v_pk_fma_f32 v[22:23], v[22:23], v[70:71], v[46:47]
	v_pk_fma_f32 v[20:21], v[20:21], v[68:69], v[44:45]
	v_pk_fma_f32 v[16:17], v[16:17], v[64:65], v[40:41]
	v_cvt_pk_bf16_f32 v40, v20, v21
	v_cvt_pk_bf16_f32 v41, v22, v23
	v_lshl_add_u64 v[90:91], v[228:229], 0, v[190:191]
	v_cvt_pk_bf16_f32 v42, v16, v17
	v_cvt_pk_bf16_f32 v43, v18, v19
	global_store_dwordx4 v[230:231], v[40:43], off offset:256
	v_pk_mul_f32 v[44:45], v[196:197], v[18:19]
	v_pk_mul_f32 v[46:47], v[200:201], v[16:17]
	v_pk_mul_f32 v[42:43], v[186:187], v[22:23]
	v_pk_mul_f32 v[40:41], v[192:193], v[20:21]
	s_waitcnt vmcnt(1)
	v_pk_fma_f32 v[10:11], v[10:11], v[66:67], v[34:35]
	v_cvt_pk_bf16_f32 v40, v40, v41
	v_cvt_pk_bf16_f32 v41, v42, v43
	v_cvt_pk_bf16_f32 v42, v46, v47
	v_cvt_pk_bf16_f32 v43, v44, v45
	v_lshl_add_u64 v[44:45], v[90:91], 1, s[28:29]
	global_store_dwordx4 v[44:45], v[40:43], off
	v_pk_fma_f32 v[14:15], v[14:15], v[70:71], v[38:39]
	v_pk_fma_f32 v[12:13], v[12:13], v[68:69], v[36:37]
	v_pk_fma_f32 v[8:9], v[8:9], v[64:65], v[32:33]
	v_cvt_pk_bf16_f32 v32, v12, v13
	v_cvt_pk_bf16_f32 v33, v14, v15
	v_lshl_add_u64 v[40:41], v[232:233], 0, v[190:191]
	v_cvt_pk_bf16_f32 v34, v8, v9
	v_cvt_pk_bf16_f32 v35, v10, v11
	global_store_dwordx4 v[234:235], v[32:35], off offset:256
	v_pk_mul_f32 v[36:37], v[196:197], v[10:11]
	v_pk_mul_f32 v[38:39], v[200:201], v[8:9]
	v_pk_mul_f32 v[34:35], v[186:187], v[14:15]
	v_pk_mul_f32 v[32:33], v[192:193], v[12:13]
	v_pk_fma_f32 v[0:1], v[0:1], v[64:65], v[24:25]
	v_cvt_pk_bf16_f32 v32, v32, v33
	v_cvt_pk_bf16_f32 v33, v34, v35
	v_cvt_pk_bf16_f32 v34, v38, v39
	v_cvt_pk_bf16_f32 v35, v36, v37
	v_lshl_add_u64 v[36:37], v[40:41], 1, s[28:29]
	global_store_dwordx4 v[36:37], v[32:35], off
	v_pk_fma_f32 v[6:7], v[6:7], v[70:71], v[50:51]
	v_pk_fma_f32 v[4:5], v[4:5], v[68:69], v[48:49]
	v_lshl_add_u64 v[32:33], v[236:237], 0, v[190:191]
	v_cvt_pk_bf16_f32 v24, v4, v5
	v_cvt_pk_bf16_f32 v25, v6, v7
	v_pk_fma_f32 v[2:3], v[2:3], v[66:67], v[26:27]
	v_cvt_pk_bf16_f32 v26, v0, v1
	v_lshl_add_u64 v[32:33], v[32:33], 1, s[28:29]
	v_cvt_pk_bf16_f32 v27, v2, v3
	global_store_dwordx4 v[246:247], v[24:27], off offset:256
	v_pk_mul_f32 v[34:35], v[196:197], v[2:3]
	v_pk_mul_f32 v[36:37], v[200:201], v[0:1]
	v_pk_mul_f32 v[24:25], v[192:193], v[4:5]
	v_pk_mul_f32 v[26:27], v[186:187], v[6:7]
	v_cvt_pk_bf16_f32 v24, v24, v25
	s_nop 0
	v_cvt_pk_bf16_f32 v25, v26, v27
	v_cvt_pk_bf16_f32 v26, v36, v37
	v_cvt_pk_bf16_f32 v27, v34, v35
	global_store_dwordx4 v[32:33], v[24:27], off
	s_nop 1
	v_mov_b32_e32 v24, v163
	s_nop 0
	v_lshlrev_b32_e32 v24, 2, v24
	v_bitop3_b32 v24, v24, 64, v248 bitop3:0x6c
	ds_bpermute_b32 v24, v24, v88
	s_waitcnt lgkmcnt(0)
	v_add_f32_e32 v26, v88, v24
	v_mov_b32_e32 v24, v163
	s_nop 0
	v_lshlrev_b32_e32 v24, 2, v24
	v_bitop3_b32 v24, v24, s46, v248 bitop3:0x6c
	ds_bpermute_b32 v27, v24, v26
	v_lshl_add_u64 v[24:25], v[182:183], 3, s[6:7]
	s_mov_b64 s[6:7], exec
	s_and_b64 s[8:9], s[6:7], s[2:3]
	v_mov_b32_e32 v240, 0x358637bd
	s_mov_b64 exec, s[8:9]
	s_cbranch_execz .LBB0_384
	s_waitcnt lgkmcnt(0)
	v_add_f32_e32 v26, v26, v27
	v_mul_f32_e32 v26, 0x47800000, v26
	v_rndne_f32_e32 v26, v26
	s_mov_b32 s1, 0x2f800000
	v_mul_f32_e64 v27, |v26|, s1
	v_floor_f32_e32 v27, v27
	s_mov_b32 s1, 0xcf800000
	v_fma_f32 v32, v27, s1, |v26|
	v_cvt_u32_f32_e32 v32, v32
	v_cvt_u32_f32_e32 v27, v27
	v_ashrrev_i32_e32 v33, 31, v26
	v_xor_b32_e32 v26, v32, v33
	v_xor_b32_e32 v27, v27, v33
	v_sub_co_u32_e32 v26, vcc, v26, v33
	s_nop 1
	v_subb_co_u32_e32 v27, vcc, v27, v33, vcc
	global_atomic_add_x2 v[24:25], v[26:27], off
